# v21 with per-segment priority toggles removed from the 10 looped GEMM mainloops and one static priority raise for the trailing wave half instead
# baseline (speedup 1.0000x reference)
; #define PG8_STAGE(bufoff, gbase, voff) do { _Pragma("unroll") for (int _i = 0; _i < 2; ++_i) \
;         __builtin_amdgcn_global_load_lds((const unsigned*)((const char*)(gbase) + (voff)[_i]), (LAS unsigned*)(lds + (bufoff) + ldsw + _i * 8192), 16, 0, 0); } while (0)
; #define PG8_LDA(dst, b, h) do { _Pragma("unroll") for (int m = 0; m < 4; ++m) _Pragma("unroll") for (int k = 0; k < 2; ++k) dst[m][k] = *(const LAS bf16x8*)(lds + PG8_SA(b, h) + aoff + m * 2048 + k * 1024); } while (0)
; #define PG8_LDB(dst, b, h) do { _Pragma("unroll") for (int n = 0; n < 2; ++n) _Pragma("unroll") for (int k = 0; k < 2; ++k) dst[n][k] = *(const LAS bf16x8*)(lds + PG8_SB(b, h) + boff + n * 2048 + k * 1024); } while (0)
; #define PG8_SCHED __builtin_amdgcn_sched_barrier(0)
; template <class Epi, class Sched>
; __device__ __forceinline__ void gemm_phase(LAS unsigned char* lds, const GemmP g, const Sched& S, const Epi& E, int tid) {
;     ...
;         for (int t = 0; t < nt; t += 2) {
;             const bool last = (t == nt - 2);
;             const char* a1 = cA + (size_t)(t + 1) * kstep;
;             const char* a2 = last ? nA : cA + (size_t)(t + 2) * kstep; const char* b2 = last ? nB : cB + (size_t)(t + 2) * kstep;
;             const char* a3 = a2 + kstep; const char* b3 = b2 + kstep;
;             PG8_LDB(B0, 0, 0); PG8_LDB(B1, 0, 1); PG8_SCHED; PG8_LDA(At, 0, 0); PG8_STAGE(PG8_SA(1, 1), a1 + hstepA, voffA);
;     ...
; #pragma unroll
;         for (int a = 0; a < 2; ++a)
; #pragma unroll
;             for (int b = 0; b < 2; ++b)
; #pragma unroll
;                 for (int m = 0; m < 4; ++m)
; #pragma unroll
;                     for (int n = 0; n < 2; ++n) acc[a][b][m][n] = (f32x4){0.f, 0.f, 0.f, 0.f};
;         cur = nxt; cA = nA; cB = nB; ++ui;
.LBB0_165:
	s_add_u32 s71, s44, 0x100
	s_addc_u32 s72, s45, 0
	s_add_u32 s4, s4, 0x40080
	v_mov_b32_e32 v0, 0
	s_addc_u32 s5, s5, 0
	s_mov_b32 s73, -2
	v_mov_b32_e32 v1, v0
	v_mov_b32_e32 v2, v0
	v_mov_b32_e32 v3, v0
	v_mov_b32_e32 v4, v0
	v_mov_b32_e32 v5, v0
	v_mov_b32_e32 v6, v0
	v_mov_b32_e32 v7, v0
	v_mov_b32_e32 v16, v0
	v_mov_b32_e32 v17, v0
	v_mov_b32_e32 v18, v0
	v_mov_b32_e32 v19, v0
	v_mov_b32_e32 v20, v0
	v_mov_b32_e32 v21, v0
	v_mov_b32_e32 v22, v0
	v_mov_b32_e32 v23, v0
	v_mov_b32_e32 v32, v0
	v_mov_b32_e32 v33, v0
	v_mov_b32_e32 v34, v0
	v_mov_b32_e32 v35, v0
	v_mov_b32_e32 v36, v0
	v_mov_b32_e32 v37, v0
	v_mov_b32_e32 v38, v0
	v_mov_b32_e32 v39, v0
	v_mov_b32_e32 v48, v0
	v_mov_b32_e32 v49, v0
	v_mov_b32_e32 v50, v0
	v_mov_b32_e32 v51, v0
	v_mov_b32_e32 v52, v0
	v_mov_b32_e32 v53, v0
	v_mov_b32_e32 v54, v0
	v_mov_b32_e32 v55, v0
	v_mov_b32_e32 v8, v0
	v_mov_b32_e32 v9, v0
	v_mov_b32_e32 v10, v0
	v_mov_b32_e32 v11, v0
	v_mov_b32_e32 v12, v0
	v_mov_b32_e32 v13, v0
	v_mov_b32_e32 v14, v0
	v_mov_b32_e32 v15, v0
	v_mov_b32_e32 v24, v0
	v_mov_b32_e32 v25, v0
	v_mov_b32_e32 v26, v0
	v_mov_b32_e32 v27, v0
	v_mov_b32_e32 v28, v0
	v_mov_b32_e32 v29, v0
	v_mov_b32_e32 v30, v0
	v_mov_b32_e32 v31, v0
	v_mov_b32_e32 v40, v0
	v_mov_b32_e32 v41, v0
	v_mov_b32_e32 v42, v0
	v_mov_b32_e32 v43, v0
	v_mov_b32_e32 v44, v0
	v_mov_b32_e32 v45, v0
	v_mov_b32_e32 v46, v0
	v_mov_b32_e32 v47, v0
	v_mov_b32_e32 v56, v0
	v_mov_b32_e32 v57, v0
	v_mov_b32_e32 v58, v0
	v_mov_b32_e32 v59, v0
	v_mov_b32_e32 v60, v0
	v_mov_b32_e32 v61, v0
	v_mov_b32_e32 v62, v0
	v_mov_b32_e32 v63, v0
	v_mov_b32_e32 v64, v0
	v_mov_b32_e32 v65, v0
	v_mov_b32_e32 v66, v0
	v_mov_b32_e32 v67, v0
	v_mov_b32_e32 v68, v0
	v_mov_b32_e32 v69, v0
	v_mov_b32_e32 v70, v0
	v_mov_b32_e32 v71, v0
	v_mov_b32_e32 v80, v0
	v_mov_b32_e32 v81, v0
	v_mov_b32_e32 v82, v0
	v_mov_b32_e32 v83, v0
	v_mov_b32_e32 v84, v0
	v_mov_b32_e32 v85, v0
	v_mov_b32_e32 v86, v0
	v_mov_b32_e32 v87, v0
	v_mov_b32_e32 v96, v0
	v_mov_b32_e32 v97, v0
	v_mov_b32_e32 v98, v0
	v_mov_b32_e32 v99, v0
	v_mov_b32_e32 v100, v0
	v_mov_b32_e32 v101, v0
	v_mov_b32_e32 v102, v0
	v_mov_b32_e32 v103, v0
	v_mov_b32_e32 v112, v0
	v_mov_b32_e32 v113, v0
	v_mov_b32_e32 v114, v0
	v_mov_b32_e32 v115, v0
	v_mov_b32_e32 v116, v0
	v_mov_b32_e32 v117, v0
	v_mov_b32_e32 v118, v0
	v_mov_b32_e32 v119, v0
	v_mov_b32_e32 v72, v0
	v_mov_b32_e32 v73, v0
	v_mov_b32_e32 v74, v0
	v_mov_b32_e32 v75, v0
	v_mov_b32_e32 v76, v0
	v_mov_b32_e32 v77, v0
	v_mov_b32_e32 v78, v0
	v_mov_b32_e32 v79, v0
	v_mov_b32_e32 v88, v0
	v_mov_b32_e32 v89, v0
	v_mov_b32_e32 v90, v0
	v_mov_b32_e32 v91, v0
	v_mov_b32_e32 v92, v0
	v_mov_b32_e32 v93, v0
	v_mov_b32_e32 v94, v0
	v_mov_b32_e32 v95, v0
	v_mov_b32_e32 v104, v0
	v_mov_b32_e32 v105, v0
	v_mov_b32_e32 v106, v0
	v_mov_b32_e32 v107, v0
	v_mov_b32_e32 v108, v0
	v_mov_b32_e32 v109, v0
	v_mov_b32_e32 v110, v0
	v_mov_b32_e32 v111, v0
	v_mov_b32_e32 v120, v0
	v_mov_b32_e32 v121, v0
	v_mov_b32_e32 v122, v0
	v_mov_b32_e32 v123, v0
	v_mov_b32_e32 v124, v0
	v_mov_b32_e32 v125, v0
	v_mov_b32_e32 v126, v0
	v_mov_b32_e32 v127, v0
	s_cmp_lg_u64 s[16:17], 0
	s_cbranch_scc1 .Lsp_166
	s_setprio 1
.Lsp_166:
.LBB0_166:
	ds_read_b128 v[144:147], v157
	ds_read_b128 v[148:151], v228
	ds_read_b128 v[152:155], v157 offset:2048
	ds_read_b128 v[162:165], v228 offset:2048
	ds_read_b128 v[166:169], v158
	ds_read_b128 v[170:173], v229
	ds_read_b128 v[174:177], v158 offset:2048
	ds_read_b128 v[178:181], v229 offset:2048
	s_add_u32 s44, s4, 0xfffc0080
	s_addc_u32 s45, s5, -1
	s_cmp_eq_u32 s73, 12
	s_cselect_b32 s47, s37, s45
	s_cselect_b32 s46, s36, s44
	s_cselect_b32 s45, s39, s72
	s_cselect_b32 s44, s38, s71
	v_lshl_add_u64 v[214:215], s[4:5], 0, v[138:139]
	s_add_i32 m0, s53, 0xc000
	ds_read_b128 v[182:185], v159
	ds_read_b128 v[186:189], v226
	ds_read_b128 v[190:193], v159 offset:2048
	ds_read_b128 v[194:197], v226 offset:2048
	ds_read_b128 v[198:201], v159 offset:4096
	ds_read_b128 v[202:205], v226 offset:4096
	ds_read_b128 v[206:209], v159 offset:6144
	ds_read_b128 v[210:213], v226 offset:6144
	global_load_lds_dwordx4 v[214:215], off
	v_lshl_add_u64 v[214:215], s[4:5], 0, v[136:137]
	s_add_i32 m0, s53, 0xe000
	s_nop 0
	global_load_lds_dwordx4 v[214:215], off
	s_cmp_eq_u32 s73, -2
	s_cbranch_scc1 .Lfirstit_1
	s_waitcnt vmcnt(8)
; #define PG8_STAGE(bufoff, gbase, voff) do { _Pragma("unroll") for (int _i = 0; _i < 2; ++_i) \
;         __builtin_amdgcn_global_load_lds((const unsigned*)((const char*)(gbase) + (voff)[_i]), (LAS unsigned*)(lds + (bufoff) + ldsw + _i * 8192), 16, 0, 0); } while (0)
; #define PG8_LDA(dst, b, h) do { _Pragma("unroll") for (int m = 0; m < 4; ++m) _Pragma("unroll") for (int k = 0; k < 2; ++k) dst[m][k] = *(const LAS bf16x8*)(lds + PG8_SA(b, h) + aoff + m * 2048 + k * 1024); } while (0)
; #define PG8_LDB(dst, b, h) do { _Pragma("unroll") for (int n = 0; n < 2; ++n) _Pragma("unroll") for (int k = 0; k < 2; ++k) dst[n][k] = *(const LAS bf16x8*)(lds + PG8_SB(b, h) + boff + n * 2048 + k * 1024); } while (0)
; #define PG8_MMA(ai, bj, At, Bt) do { __builtin_amdgcn_s_setprio(1); _Pragma("unroll") for (int m = 0; m < 4; ++m) _Pragma("unroll") for (int n = 0; n < 2; ++n) _Pragma("unroll") for (int k = 0; k < 2; ++k) \
;         acc[ai][bj][m][n] = __builtin_amdgcn_mfma_f32_16x16x32_bf16(Bt[n][k], At[m][k], acc[ai][bj][m][n], 0, 0, 0); __builtin_amdgcn_s_setprio(0); } while (0)
; #define PG8_WAIT_V(n) asm volatile("s_waitcnt vmcnt(" #n ")" ::: "memory")
; #define PG8_WAIT_L(n) asm volatile("s_waitcnt lgkmcnt(" #n ")" ::: "memory")
; #define PG8_BAR __builtin_amdgcn_s_barrier()
; #define PG8_SCHED __builtin_amdgcn_sched_barrier(0)
; template <class Epi, class Sched>
; __device__ __forceinline__ void gemm_phase(LAS unsigned char* lds, const GemmP g, const Sched& S, const Epi& E, int tid) {
;     ...
;             PG8_LDB(B0, 0, 0); PG8_LDB(B1, 0, 1); PG8_SCHED; PG8_LDA(At, 0, 0); PG8_STAGE(PG8_SA(1, 1), a1 + hstepA, voffA);
;             PG8_WAIT_V(8); PG8_WAIT_L(0); PG8_BAR; PG8_MMA(0, 0, At, B0); PG8_MMA(0, 1, At, B1); PG8_BAR; PG8_SCHED;
;             PG8_LDA(At, 0, 1); PG8_STAGE(PG8_SB(0, 0), b2, voffB); PG8_STAGE(PG8_SB(0, 1), b2 + hstepB, voffB); PG8_STAGE(PG8_SA(0, 0), a2, voffA);
;             PG8_WAIT_V(8); PG8_WAIT_L(0); PG8_BAR; PG8_MMA(1, 0, At, B0); PG8_MMA(1, 1, At, B1); PG8_BAR; PG8_SCHED;
;             PG8_LDB(B0, 1, 0); PG8_LDB(B1, 1, 1); PG8_SCHED; PG8_LDA(At, 1, 0); PG8_STAGE(PG8_SA(0, 1), a2 + hstepA, voffA);
.Lfirstit_1:
	s_waitcnt lgkmcnt(0)
	s_barrier
	s_waitcnt lgkmcnt(0)
	v_mfma_f32_16x16x32_bf16 v[124:127], v[144:147], v[182:185], v[124:127]
	v_mfma_f32_16x16x32_bf16 v[120:123], v[152:155], v[182:185], v[120:123]
	v_mfma_f32_16x16x32_bf16 v[108:111], v[144:147], v[190:193], v[108:111]
	v_mfma_f32_16x16x32_bf16 v[104:107], v[152:155], v[190:193], v[104:107]
	v_mfma_f32_16x16x32_bf16 v[92:95], v[144:147], v[198:201], v[92:95]
	v_mfma_f32_16x16x32_bf16 v[88:91], v[152:155], v[198:201], v[88:91]
	v_mfma_f32_16x16x32_bf16 v[76:79], v[144:147], v[206:209], v[76:79]
	v_mfma_f32_16x16x32_bf16 v[72:75], v[152:155], v[206:209], v[72:75]
	v_mfma_f32_16x16x32_bf16 v[124:127], v[148:151], v[186:189], v[124:127]
	v_mfma_f32_16x16x32_bf16 v[120:123], v[162:165], v[186:189], v[120:123]
	v_mfma_f32_16x16x32_bf16 v[108:111], v[148:151], v[194:197], v[108:111]
	v_mfma_f32_16x16x32_bf16 v[104:107], v[162:165], v[194:197], v[104:107]
	v_mfma_f32_16x16x32_bf16 v[92:95], v[148:151], v[202:205], v[92:95]
	v_mfma_f32_16x16x32_bf16 v[88:91], v[162:165], v[202:205], v[88:91]
	v_mfma_f32_16x16x32_bf16 v[76:79], v[148:151], v[210:213], v[76:79]
	v_mfma_f32_16x16x32_bf16 v[72:75], v[162:165], v[210:213], v[72:75]
	v_mfma_f32_16x16x32_bf16 v[116:119], v[166:169], v[182:185], v[116:119]
	v_mfma_f32_16x16x32_bf16 v[112:115], v[174:177], v[182:185], v[112:115]
	v_mfma_f32_16x16x32_bf16 v[100:103], v[166:169], v[190:193], v[100:103]
	v_mfma_f32_16x16x32_bf16 v[96:99], v[174:177], v[190:193], v[96:99]
	v_mfma_f32_16x16x32_bf16 v[84:87], v[166:169], v[198:201], v[84:87]
	v_mfma_f32_16x16x32_bf16 v[80:83], v[174:177], v[198:201], v[80:83]
	v_mfma_f32_16x16x32_bf16 v[68:71], v[166:169], v[206:209], v[68:71]
	v_mfma_f32_16x16x32_bf16 v[64:67], v[174:177], v[206:209], v[64:67]
	v_mfma_f32_16x16x32_bf16 v[116:119], v[170:173], v[186:189], v[116:119]
	v_mfma_f32_16x16x32_bf16 v[112:115], v[178:181], v[186:189], v[112:115]
	v_mfma_f32_16x16x32_bf16 v[100:103], v[170:173], v[194:197], v[100:103]
	v_mfma_f32_16x16x32_bf16 v[96:99], v[178:181], v[194:197], v[96:99]
	v_mfma_f32_16x16x32_bf16 v[84:87], v[170:173], v[202:205], v[84:87]
	v_mfma_f32_16x16x32_bf16 v[80:83], v[178:181], v[202:205], v[80:83]
	v_mfma_f32_16x16x32_bf16 v[68:71], v[170:173], v[210:213], v[68:71]
	v_mfma_f32_16x16x32_bf16 v[64:67], v[178:181], v[210:213], v[64:67]
	s_barrier
	s_add_i32 s74, s67, s52
	v_lshl_add_u64 v[214:215], s[44:45], 0, v[130:131]
	s_mov_b32 m0, s74
	ds_read_b128 v[182:185], v159 offset:16384
	ds_read_b128 v[186:189], v226 offset:16384
	ds_read_b128 v[190:193], v159 offset:18432
	ds_read_b128 v[194:197], v226 offset:18432
	ds_read_b128 v[198:201], v159 offset:20480
	ds_read_b128 v[202:205], v226 offset:20480
	ds_read_b128 v[206:209], v159 offset:22528
	ds_read_b128 v[210:213], v226 offset:22528
	global_load_lds_dwordx4 v[214:215], off
	s_add_i32 m0, s74, 0x2000
	s_add_u32 s74, s44, 0x40000
	v_lshl_add_u64 v[216:217], s[44:45], 0, v[134:135]
	s_addc_u32 s75, s45, 0
	s_add_i32 s76, s68, s52
	global_load_lds_dwordx4 v[216:217], off
	v_lshl_add_u64 v[218:219], s[74:75], 0, v[130:131]
	s_mov_b32 m0, s76
	v_lshl_add_u64 v[220:221], s[46:47], 0, v[132:133]
	global_load_lds_dwordx4 v[218:219], off
	v_lshl_add_u64 v[218:219], s[74:75], 0, v[134:135]
	s_add_i32 m0, s76, 0x2000
	s_nop 0
	global_load_lds_dwordx4 v[218:219], off
	v_lshl_add_u64 v[218:219], s[46:47], 0, v[128:129]
	s_mov_b32 m0, s53
	s_nop 0
	global_load_lds_dwordx4 v[218:219], off
	s_mov_b32 m0, s54
	s_nop 0
	global_load_lds_dwordx4 v[220:221], off
	s_waitcnt vmcnt(8)
	s_waitcnt lgkmcnt(0)
	s_barrier
	s_waitcnt lgkmcnt(0)
	v_mfma_f32_16x16x32_bf16 v[60:63], v[144:147], v[182:185], v[60:63]
	v_mfma_f32_16x16x32_bf16 v[56:59], v[152:155], v[182:185], v[56:59]
	v_mfma_f32_16x16x32_bf16 v[44:47], v[144:147], v[190:193], v[44:47]
	v_mfma_f32_16x16x32_bf16 v[40:43], v[152:155], v[190:193], v[40:43]
	v_mfma_f32_16x16x32_bf16 v[28:31], v[144:147], v[198:201], v[28:31]
	v_mfma_f32_16x16x32_bf16 v[24:27], v[152:155], v[198:201], v[24:27]
	v_mfma_f32_16x16x32_bf16 v[12:15], v[144:147], v[206:209], v[12:15]
	v_mfma_f32_16x16x32_bf16 v[8:11], v[152:155], v[206:209], v[8:11]
	v_mfma_f32_16x16x32_bf16 v[60:63], v[148:151], v[186:189], v[60:63]
	v_mfma_f32_16x16x32_bf16 v[56:59], v[162:165], v[186:189], v[56:59]
	v_mfma_f32_16x16x32_bf16 v[44:47], v[148:151], v[194:197], v[44:47]
	v_mfma_f32_16x16x32_bf16 v[40:43], v[162:165], v[194:197], v[40:43]
	v_mfma_f32_16x16x32_bf16 v[28:31], v[148:151], v[202:205], v[28:31]
	v_mfma_f32_16x16x32_bf16 v[24:27], v[162:165], v[202:205], v[24:27]
	v_mfma_f32_16x16x32_bf16 v[12:15], v[148:151], v[210:213], v[12:15]
	v_mfma_f32_16x16x32_bf16 v[8:11], v[162:165], v[210:213], v[8:11]
	v_mfma_f32_16x16x32_bf16 v[52:55], v[166:169], v[182:185], v[52:55]
	v_mfma_f32_16x16x32_bf16 v[48:51], v[174:177], v[182:185], v[48:51]
	v_mfma_f32_16x16x32_bf16 v[36:39], v[166:169], v[190:193], v[36:39]
	v_mfma_f32_16x16x32_bf16 v[32:35], v[174:177], v[190:193], v[32:35]
	v_mfma_f32_16x16x32_bf16 v[20:23], v[166:169], v[198:201], v[20:23]
	v_mfma_f32_16x16x32_bf16 v[16:19], v[174:177], v[198:201], v[16:19]
	v_mfma_f32_16x16x32_bf16 v[4:7], v[166:169], v[206:209], v[4:7]
	v_mfma_f32_16x16x32_bf16 v[0:3], v[174:177], v[206:209], v[0:3]
	v_mfma_f32_16x16x32_bf16 v[52:55], v[170:173], v[186:189], v[52:55]
	v_mfma_f32_16x16x32_bf16 v[48:51], v[178:181], v[186:189], v[48:51]
	v_mfma_f32_16x16x32_bf16 v[36:39], v[170:173], v[194:197], v[36:39]
	v_mfma_f32_16x16x32_bf16 v[32:35], v[178:181], v[194:197], v[32:35]
	v_mfma_f32_16x16x32_bf16 v[20:23], v[170:173], v[202:205], v[20:23]
	v_mfma_f32_16x16x32_bf16 v[16:19], v[178:181], v[202:205], v[16:19]
	v_mfma_f32_16x16x32_bf16 v[4:7], v[170:173], v[210:213], v[4:7]
	v_mfma_f32_16x16x32_bf16 v[0:3], v[178:181], v[210:213], v[0:3]
	s_barrier
; #define PG8_STAGE(bufoff, gbase, voff) do { _Pragma("unroll") for (int _i = 0; _i < 2; ++_i) \
;         __builtin_amdgcn_global_load_lds((const unsigned*)((const char*)(gbase) + (voff)[_i]), (LAS unsigned*)(lds + (bufoff) + ldsw + _i * 8192), 16, 0, 0); } while (0)
; #define PG8_LDA(dst, b, h) do { _Pragma("unroll") for (int m = 0; m < 4; ++m) _Pragma("unroll") for (int k = 0; k < 2; ++k) dst[m][k] = *(const LAS bf16x8*)(lds + PG8_SA(b, h) + aoff + m * 2048 + k * 1024); } while (0)
; #define PG8_LDB(dst, b, h) do { _Pragma("unroll") for (int n = 0; n < 2; ++n) _Pragma("unroll") for (int k = 0; k < 2; ++k) dst[n][k] = *(const LAS bf16x8*)(lds + PG8_SB(b, h) + boff + n * 2048 + k * 1024); } while (0)
; #define PG8_MMA(ai, bj, At, Bt) do { __builtin_amdgcn_s_setprio(1); _Pragma("unroll") for (int m = 0; m < 4; ++m) _Pragma("unroll") for (int n = 0; n < 2; ++n) _Pragma("unroll") for (int k = 0; k < 2; ++k) \
;         acc[ai][bj][m][n] = __builtin_amdgcn_mfma_f32_16x16x32_bf16(Bt[n][k], At[m][k], acc[ai][bj][m][n], 0, 0, 0); __builtin_amdgcn_s_setprio(0); } while (0)
; #define PG8_WAIT_V(n) asm volatile("s_waitcnt vmcnt(" #n ")" ::: "memory")
; #define PG8_WAIT_L(n) asm volatile("s_waitcnt lgkmcnt(" #n ")" ::: "memory")
; #define PG8_BAR __builtin_amdgcn_s_barrier()
; #define PG8_SCHED __builtin_amdgcn_sched_barrier(0)
; template <class Epi, class Sched>
; __device__ __forceinline__ void gemm_phase(LAS unsigned char* lds, const GemmP g, const Sched& S, const Epi& E, int tid) {
;     ...
;             PG8_LDB(B0, 1, 0); PG8_LDB(B1, 1, 1); PG8_SCHED; PG8_LDA(At, 1, 0); PG8_STAGE(PG8_SA(0, 1), a2 + hstepA, voffA);
;             PG8_WAIT_V(8); PG8_WAIT_L(0); PG8_BAR; PG8_MMA(0, 0, At, B0); PG8_MMA(0, 1, At, B1); PG8_BAR; PG8_SCHED;
	s_add_i32 s74, 0, 0x18000
	s_add_i32 s75, 0, 0x1c000
	v_add_u32_e32 v162, s74, v156
	v_add_u32_e32 v178, s75, v156
	v_add_u32_e32 v230, s74, v227
	v_add_u32_e32 v231, s75, v227
	ds_read_b128 v[144:147], v162
	ds_read_b128 v[148:151], v230
	ds_read_b128 v[152:155], v162 offset:2048
	ds_read_b128 v[162:165], v230 offset:2048
	ds_read_b128 v[166:169], v178
	ds_read_b128 v[170:173], v231
	ds_read_b128 v[174:177], v178 offset:2048
	ds_read_b128 v[178:181], v231 offset:2048
	s_add_u32 s46, s46, 0x40000
	s_addc_u32 s47, s47, 0
	s_mov_b32 m0, s55
	v_lshl_add_u64 v[222:223], s[46:47], 0, v[128:129]
	ds_read_b128 v[182:185], v159 offset:32768
	ds_read_b128 v[186:189], v226 offset:32768
	ds_read_b128 v[190:193], v159 offset:34816
	ds_read_b128 v[194:197], v226 offset:34816
	ds_read_b128 v[198:201], v159 offset:36864
	ds_read_b128 v[202:205], v226 offset:36864
	ds_read_b128 v[206:209], v159 offset:38912
	ds_read_b128 v[210:213], v226 offset:38912
	global_load_lds_dwordx4 v[222:223], off
	v_lshl_add_u64 v[222:223], s[46:47], 0, v[132:133]
	s_mov_b32 m0, s56
	s_nop 0
	global_load_lds_dwordx4 v[222:223], off
	s_waitcnt vmcnt(8)
	s_waitcnt lgkmcnt(0)
	s_barrier
	s_waitcnt lgkmcnt(0)
	v_mfma_f32_16x16x32_bf16 v[124:127], v[144:147], v[182:185], v[124:127]
	v_mfma_f32_16x16x32_bf16 v[120:123], v[152:155], v[182:185], v[120:123]
	v_mfma_f32_16x16x32_bf16 v[108:111], v[144:147], v[190:193], v[108:111]
	v_mfma_f32_16x16x32_bf16 v[104:107], v[152:155], v[190:193], v[104:107]
	v_mfma_f32_16x16x32_bf16 v[92:95], v[144:147], v[198:201], v[92:95]
	v_mfma_f32_16x16x32_bf16 v[88:91], v[152:155], v[198:201], v[88:91]
	v_mfma_f32_16x16x32_bf16 v[76:79], v[144:147], v[206:209], v[76:79]
	v_mfma_f32_16x16x32_bf16 v[72:75], v[152:155], v[206:209], v[72:75]
	v_mfma_f32_16x16x32_bf16 v[124:127], v[148:151], v[186:189], v[124:127]
	v_mfma_f32_16x16x32_bf16 v[120:123], v[162:165], v[186:189], v[120:123]
	v_mfma_f32_16x16x32_bf16 v[108:111], v[148:151], v[194:197], v[108:111]
	v_mfma_f32_16x16x32_bf16 v[104:107], v[162:165], v[194:197], v[104:107]
	v_mfma_f32_16x16x32_bf16 v[92:95], v[148:151], v[202:205], v[92:95]
	v_mfma_f32_16x16x32_bf16 v[88:91], v[162:165], v[202:205], v[88:91]
	v_mfma_f32_16x16x32_bf16 v[76:79], v[148:151], v[210:213], v[76:79]
	v_mfma_f32_16x16x32_bf16 v[72:75], v[162:165], v[210:213], v[72:75]
	v_mfma_f32_16x16x32_bf16 v[116:119], v[166:169], v[182:185], v[116:119]
	v_mfma_f32_16x16x32_bf16 v[112:115], v[174:177], v[182:185], v[112:115]
	v_mfma_f32_16x16x32_bf16 v[100:103], v[166:169], v[190:193], v[100:103]
	v_mfma_f32_16x16x32_bf16 v[96:99], v[174:177], v[190:193], v[96:99]
	v_mfma_f32_16x16x32_bf16 v[84:87], v[166:169], v[198:201], v[84:87]
	v_mfma_f32_16x16x32_bf16 v[80:83], v[174:177], v[198:201], v[80:83]
	v_mfma_f32_16x16x32_bf16 v[68:71], v[166:169], v[206:209], v[68:71]
	v_mfma_f32_16x16x32_bf16 v[64:67], v[174:177], v[206:209], v[64:67]
	v_mfma_f32_16x16x32_bf16 v[116:119], v[170:173], v[186:189], v[116:119]
	v_mfma_f32_16x16x32_bf16 v[112:115], v[178:181], v[186:189], v[112:115]
	v_mfma_f32_16x16x32_bf16 v[100:103], v[170:173], v[194:197], v[100:103]
	v_mfma_f32_16x16x32_bf16 v[96:99], v[178:181], v[194:197], v[96:99]
	v_mfma_f32_16x16x32_bf16 v[84:87], v[170:173], v[202:205], v[84:87]
	v_mfma_f32_16x16x32_bf16 v[80:83], v[178:181], v[202:205], v[80:83]
	v_mfma_f32_16x16x32_bf16 v[68:71], v[170:173], v[210:213], v[68:71]
	v_mfma_f32_16x16x32_bf16 v[64:67], v[178:181], v[210:213], v[64:67]
	s_barrier
; #define PG8_STAGE(bufoff, gbase, voff) do { _Pragma("unroll") for (int _i = 0; _i < 2; ++_i) \
;         __builtin_amdgcn_global_load_lds((const unsigned*)((const char*)(gbase) + (voff)[_i]), (LAS unsigned*)(lds + (bufoff) + ldsw + _i * 8192), 16, 0, 0); } while (0)
; #define PG8_LDA(dst, b, h) do { _Pragma("unroll") for (int m = 0; m < 4; ++m) _Pragma("unroll") for (int k = 0; k < 2; ++k) dst[m][k] = *(const LAS bf16x8*)(lds + PG8_SA(b, h) + aoff + m * 2048 + k * 1024); } while (0)
; #define PG8_MMA(ai, bj, At, Bt) do { __builtin_amdgcn_s_setprio(1); _Pragma("unroll") for (int m = 0; m < 4; ++m) _Pragma("unroll") for (int n = 0; n < 2; ++n) _Pragma("unroll") for (int k = 0; k < 2; ++k) \
;         acc[ai][bj][m][n] = __builtin_amdgcn_mfma_f32_16x16x32_bf16(Bt[n][k], At[m][k], acc[ai][bj][m][n], 0, 0, 0); __builtin_amdgcn_s_setprio(0); } while (0)
; #define PG8_WAIT_V(n) asm volatile("s_waitcnt vmcnt(" #n ")" ::: "memory")
; #define PG8_WAIT_L(n) asm volatile("s_waitcnt lgkmcnt(" #n ")" ::: "memory")
; #define PG8_BAR __builtin_amdgcn_s_barrier()
; #define PG8_SCHED __builtin_amdgcn_sched_barrier(0)
; template <class Epi, class Sched>
; __device__ __forceinline__ void gemm_phase(LAS unsigned char* lds, const GemmP g, const Sched& S, const Epi& E, int tid) {
;     ...
;             PG8_LDA(At, 1, 1); PG8_STAGE(PG8_SB(1, 0), b3, voffB); PG8_STAGE(PG8_SB(1, 1), b3 + hstepB, voffB); PG8_STAGE(PG8_SA(1, 0), a3, voffA);
;             PG8_WAIT_V(8); PG8_WAIT_L(0); PG8_BAR; PG8_MMA(1, 0, At, B0); PG8_MMA(1, 1, At, B1); PG8_BAR; PG8_SCHED;
;         }
	s_add_i32 s46, s74, s52
	v_lshl_add_u64 v[214:215], v[214:215], 0, s[14:15]
	s_mov_b32 m0, s46
	ds_read_b128 v[182:185], v159 offset:49152
	ds_read_b128 v[186:189], v226 offset:49152
	ds_read_b128 v[190:193], v159 offset:51200
	ds_read_b128 v[194:197], v226 offset:51200
	ds_read_b128 v[198:201], v159 offset:53248
	ds_read_b128 v[202:205], v226 offset:53248
	ds_read_b128 v[206:209], v159 offset:55296
	ds_read_b128 v[210:213], v226 offset:55296
	global_load_lds_dwordx4 v[214:215], off
	s_add_i32 m0, s46, 0x2000
	s_add_u32 s44, s44, 0x40080
	v_lshl_add_u64 v[214:215], v[216:217], 0, s[14:15]
	s_addc_u32 s45, s45, 0
	s_add_i32 s46, s75, s52
	global_load_lds_dwordx4 v[214:215], off
	v_lshl_add_u64 v[214:215], s[44:45], 0, v[130:131]
	s_mov_b32 m0, s46
	s_nop 0
	global_load_lds_dwordx4 v[214:215], off
	v_lshl_add_u64 v[214:215], s[44:45], 0, v[134:135]
	s_add_i32 m0, s46, 0x2000
	s_nop 0
	global_load_lds_dwordx4 v[214:215], off
	v_lshl_add_u64 v[214:215], v[218:219], 0, s[14:15]
	s_mov_b32 m0, s62
	s_nop 0
	global_load_lds_dwordx4 v[214:215], off
	v_lshl_add_u64 v[214:215], v[220:221], 0, s[14:15]
	s_mov_b32 m0, s63
	s_nop 0
	global_load_lds_dwordx4 v[214:215], off
	s_waitcnt vmcnt(8)
	s_waitcnt lgkmcnt(0)
	s_barrier
	s_waitcnt lgkmcnt(0)
	v_mfma_f32_16x16x32_bf16 v[60:63], v[144:147], v[182:185], v[60:63]
	v_mfma_f32_16x16x32_bf16 v[56:59], v[152:155], v[182:185], v[56:59]
	v_mfma_f32_16x16x32_bf16 v[44:47], v[144:147], v[190:193], v[44:47]
	v_mfma_f32_16x16x32_bf16 v[40:43], v[152:155], v[190:193], v[40:43]
	v_mfma_f32_16x16x32_bf16 v[28:31], v[144:147], v[198:201], v[28:31]
	v_mfma_f32_16x16x32_bf16 v[24:27], v[152:155], v[198:201], v[24:27]
	v_mfma_f32_16x16x32_bf16 v[12:15], v[144:147], v[206:209], v[12:15]
	v_mfma_f32_16x16x32_bf16 v[8:11], v[152:155], v[206:209], v[8:11]
	v_mfma_f32_16x16x32_bf16 v[60:63], v[148:151], v[186:189], v[60:63]
	v_mfma_f32_16x16x32_bf16 v[56:59], v[162:165], v[186:189], v[56:59]
	v_mfma_f32_16x16x32_bf16 v[44:47], v[148:151], v[194:197], v[44:47]
	v_mfma_f32_16x16x32_bf16 v[40:43], v[162:165], v[194:197], v[40:43]
	v_mfma_f32_16x16x32_bf16 v[28:31], v[148:151], v[202:205], v[28:31]
	v_mfma_f32_16x16x32_bf16 v[24:27], v[162:165], v[202:205], v[24:27]
	v_mfma_f32_16x16x32_bf16 v[12:15], v[148:151], v[210:213], v[12:15]
	v_mfma_f32_16x16x32_bf16 v[8:11], v[162:165], v[210:213], v[8:11]
	v_mfma_f32_16x16x32_bf16 v[52:55], v[166:169], v[182:185], v[52:55]
	v_mfma_f32_16x16x32_bf16 v[48:51], v[174:177], v[182:185], v[48:51]
	v_mfma_f32_16x16x32_bf16 v[36:39], v[166:169], v[190:193], v[36:39]
	v_mfma_f32_16x16x32_bf16 v[32:35], v[174:177], v[190:193], v[32:35]
	v_mfma_f32_16x16x32_bf16 v[20:23], v[166:169], v[198:201], v[20:23]
	v_mfma_f32_16x16x32_bf16 v[16:19], v[174:177], v[198:201], v[16:19]
	v_mfma_f32_16x16x32_bf16 v[4:7], v[166:169], v[206:209], v[4:7]
	v_mfma_f32_16x16x32_bf16 v[0:3], v[174:177], v[206:209], v[0:3]
	v_mfma_f32_16x16x32_bf16 v[52:55], v[170:173], v[186:189], v[52:55]
	v_mfma_f32_16x16x32_bf16 v[48:51], v[178:181], v[186:189], v[48:51]
	v_mfma_f32_16x16x32_bf16 v[36:39], v[170:173], v[194:197], v[36:39]
	v_mfma_f32_16x16x32_bf16 v[32:35], v[178:181], v[194:197], v[32:35]
	v_mfma_f32_16x16x32_bf16 v[20:23], v[170:173], v[202:205], v[20:23]
	v_mfma_f32_16x16x32_bf16 v[16:19], v[178:181], v[202:205], v[16:19]
	v_mfma_f32_16x16x32_bf16 v[4:7], v[170:173], v[210:213], v[4:7]
	v_mfma_f32_16x16x32_bf16 v[0:3], v[178:181], v[210:213], v[0:3]
	s_barrier
	s_add_i32 s73, s73, 2
	s_add_u32 s71, s71, 0x100
	s_addc_u32 s72, s72, 0
	s_add_u32 s4, s4, 0x100
	s_addc_u32 s5, s5, 0
	s_cmp_gt_u32 s73, 13
	s_cbranch_scc0 .LBB0_166
	s_setprio 0
	s_and_b64 vcc, exec, s[16:17]
	s_cbranch_vccz .LBB0_169
	s_barrier

; #define PG8_STAGE(bufoff, gbase, voff) do { _Pragma("unroll") for (int _i = 0; _i < 2; ++_i) \
;         __builtin_amdgcn_global_load_lds((const unsigned*)((const char*)(gbase) + (voff)[_i]), (LAS unsigned*)(lds + (bufoff) + ldsw + _i * 8192), 16, 0, 0); } while (0)
; #define PG8_LDA(dst, b, h) do { _Pragma("unroll") for (int m = 0; m < 4; ++m) _Pragma("unroll") for (int k = 0; k < 2; ++k) dst[m][k] = *(const LAS bf16x8*)(lds + PG8_SA(b, h) + aoff + m * 2048 + k * 1024); } while (0)
; #define PG8_LDB(dst, b, h) do { _Pragma("unroll") for (int n = 0; n < 2; ++n) _Pragma("unroll") for (int k = 0; k < 2; ++k) dst[n][k] = *(const LAS bf16x8*)(lds + PG8_SB(b, h) + boff + n * 2048 + k * 1024); } while (0)
; #define PG8_MMA(ai, bj, At, Bt) do { __builtin_amdgcn_s_setprio(1); _Pragma("unroll") for (int m = 0; m < 4; ++m) _Pragma("unroll") for (int n = 0; n < 2; ++n) _Pragma("unroll") for (int k = 0; k < 2; ++k) \
;         acc[ai][bj][m][n] = __builtin_amdgcn_mfma_f32_16x16x32_bf16(Bt[n][k], At[m][k], acc[ai][bj][m][n], 0, 0, 0); __builtin_amdgcn_s_setprio(0); } while (0)
; #define PG8_WAIT_V(n) asm volatile("s_waitcnt vmcnt(" #n ")" ::: "memory")
; #define PG8_WAIT_L(n) asm volatile("s_waitcnt lgkmcnt(" #n ")" ::: "memory")
; #define PG8_BAR __builtin_amdgcn_s_barrier()
; template <class Epi, class Sched>
; __device__ __forceinline__ void gemm_phase(LAS unsigned char* lds, const GemmP g, const Sched& S, const Epi& E, int tid) {
;     ...
;         for (int t = 0; t < nt; t += 2) {
;             const bool last = (t == nt - 2);
;             const char* a1 = cA + (size_t)(t + 1) * kstep;
;             const char* a2 = last ? nA : cA + (size_t)(t + 2) * kstep; const char* b2 = last ? nB : cB + (size_t)(t + 2) * kstep;
;             const char* a3 = a2 + kstep; const char* b3 = b2 + kstep;
;             PG8_LDB(B0, 0, 0); PG8_LDB(B1, 0, 1); PG8_SCHED; PG8_LDA(At, 0, 0); PG8_STAGE(PG8_SA(1, 1), a1 + hstepA, voffA);
;             PG8_WAIT_V(8); PG8_WAIT_L(0); PG8_BAR; PG8_MMA(0, 0, At, B0); PG8_MMA(0, 1, At, B1); PG8_BAR; PG8_SCHED;
;     ...
; #pragma unroll
;         for (int a = 0; a < 2; ++a)
; #pragma unroll
;             for (int b = 0; b < 2; ++b)
; #pragma unroll
;                 for (int m = 0; m < 4; ++m)
; #pragma unroll
;                     for (int n = 0; n < 2; ++n) acc[a][b][m][n] = (f32x4){0.f, 0.f, 0.f, 0.f};
;         cur = nxt; cA = nA; cB = nB; ++ui;
.LBB0_222:
	s_add_u32 s69, s40, 0x100
	s_addc_u32 s70, s41, 0
	s_add_u32 s38, s38, 0x40080
	v_mov_b32_e32 v0, 0
	s_addc_u32 s39, s39, 0
	s_mov_b32 s71, -2
	v_mov_b32_e32 v1, v0
	v_mov_b32_e32 v2, v0
	v_mov_b32_e32 v3, v0
	v_mov_b32_e32 v4, v0
	v_mov_b32_e32 v5, v0
	v_mov_b32_e32 v6, v0
	v_mov_b32_e32 v7, v0
	v_mov_b32_e32 v8, v0
	v_mov_b32_e32 v9, v0
	v_mov_b32_e32 v10, v0
	v_mov_b32_e32 v11, v0
	v_mov_b32_e32 v12, v0
	v_mov_b32_e32 v13, v0
	v_mov_b32_e32 v14, v0
	v_mov_b32_e32 v15, v0
	v_mov_b32_e32 v24, v0
	v_mov_b32_e32 v25, v0
	v_mov_b32_e32 v26, v0
	v_mov_b32_e32 v27, v0
	v_mov_b32_e32 v28, v0
	v_mov_b32_e32 v29, v0
	v_mov_b32_e32 v30, v0
	v_mov_b32_e32 v31, v0
	v_mov_b32_e32 v40, v0
	v_mov_b32_e32 v41, v0
	v_mov_b32_e32 v42, v0
	v_mov_b32_e32 v43, v0
	v_mov_b32_e32 v44, v0
	v_mov_b32_e32 v45, v0
	v_mov_b32_e32 v46, v0
	v_mov_b32_e32 v47, v0
	v_mov_b32_e32 v16, v0
	v_mov_b32_e32 v17, v0
	v_mov_b32_e32 v18, v0
	v_mov_b32_e32 v19, v0
	v_mov_b32_e32 v20, v0
	v_mov_b32_e32 v21, v0
	v_mov_b32_e32 v22, v0
	v_mov_b32_e32 v23, v0
	v_mov_b32_e32 v32, v0
	v_mov_b32_e32 v33, v0
	v_mov_b32_e32 v34, v0
	v_mov_b32_e32 v35, v0
	v_mov_b32_e32 v36, v0
	v_mov_b32_e32 v37, v0
	v_mov_b32_e32 v38, v0
	v_mov_b32_e32 v39, v0
	v_mov_b32_e32 v48, v0
	v_mov_b32_e32 v49, v0
	v_mov_b32_e32 v50, v0
	v_mov_b32_e32 v51, v0
	v_mov_b32_e32 v52, v0
	v_mov_b32_e32 v53, v0
	v_mov_b32_e32 v54, v0
	v_mov_b32_e32 v55, v0
	v_mov_b32_e32 v56, v0
	v_mov_b32_e32 v57, v0
	v_mov_b32_e32 v58, v0
	v_mov_b32_e32 v59, v0
	v_mov_b32_e32 v60, v0
	v_mov_b32_e32 v61, v0
	v_mov_b32_e32 v62, v0
	v_mov_b32_e32 v63, v0
	v_mov_b32_e32 v64, v0
	v_mov_b32_e32 v65, v0
	v_mov_b32_e32 v66, v0
	v_mov_b32_e32 v67, v0
	v_mov_b32_e32 v68, v0
	v_mov_b32_e32 v69, v0
	v_mov_b32_e32 v70, v0
	v_mov_b32_e32 v71, v0
	v_mov_b32_e32 v72, v0
	v_mov_b32_e32 v73, v0
	v_mov_b32_e32 v74, v0
	v_mov_b32_e32 v75, v0
	v_mov_b32_e32 v76, v0
	v_mov_b32_e32 v77, v0
	v_mov_b32_e32 v78, v0
	v_mov_b32_e32 v79, v0
	v_mov_b32_e32 v88, v0
	v_mov_b32_e32 v89, v0
	v_mov_b32_e32 v90, v0
	v_mov_b32_e32 v91, v0
	v_mov_b32_e32 v92, v0
	v_mov_b32_e32 v93, v0
	v_mov_b32_e32 v94, v0
	v_mov_b32_e32 v95, v0
	v_mov_b32_e32 v104, v0
	v_mov_b32_e32 v105, v0
	v_mov_b32_e32 v106, v0
	v_mov_b32_e32 v107, v0
	v_mov_b32_e32 v108, v0
	v_mov_b32_e32 v109, v0
	v_mov_b32_e32 v110, v0
	v_mov_b32_e32 v111, v0
	v_mov_b32_e32 v80, v0
	v_mov_b32_e32 v81, v0
	v_mov_b32_e32 v82, v0
	v_mov_b32_e32 v83, v0
	v_mov_b32_e32 v84, v0
	v_mov_b32_e32 v85, v0
	v_mov_b32_e32 v86, v0
	v_mov_b32_e32 v87, v0
	v_mov_b32_e32 v96, v0
	v_mov_b32_e32 v97, v0
	v_mov_b32_e32 v98, v0
	v_mov_b32_e32 v99, v0
	v_mov_b32_e32 v100, v0
	v_mov_b32_e32 v101, v0
	v_mov_b32_e32 v102, v0
	v_mov_b32_e32 v103, v0
	v_mov_b32_e32 v112, v0
	v_mov_b32_e32 v113, v0
	v_mov_b32_e32 v114, v0
	v_mov_b32_e32 v115, v0
	v_mov_b32_e32 v116, v0
	v_mov_b32_e32 v117, v0
	v_mov_b32_e32 v118, v0
	v_mov_b32_e32 v119, v0
	v_mov_b32_e32 v120, v0
	v_mov_b32_e32 v121, v0
	v_mov_b32_e32 v122, v0
	v_mov_b32_e32 v123, v0
	v_mov_b32_e32 v124, v0
	v_mov_b32_e32 v125, v0
	v_mov_b32_e32 v126, v0
	v_mov_b32_e32 v127, v0
	s_cmp_lg_u64 s[14:15], 0
	s_cbranch_scc1 .Lsp_223
	s_setprio 1
.Lsp_223:
.LBB0_223:
	ds_read_b128 v[146:149], v142
	ds_read_b128 v[150:153], v142 offset:1024
	ds_read_b128 v[154:157], v142 offset:2048
	ds_read_b128 v[158:161], v142 offset:3072
	ds_read_b128 v[162:165], v143
	ds_read_b128 v[166:169], v143 offset:1024
	ds_read_b128 v[170:173], v143 offset:2048
	ds_read_b128 v[174:177], v143 offset:3072
	s_add_u32 s40, s38, 0xfffc0080
	s_addc_u32 s41, s39, -1
	s_cmp_eq_u32 s71, 12
	s_cselect_b32 s45, s35, s41
	s_cselect_b32 s44, s34, s40
	s_cselect_b32 s41, s37, s70
	s_cselect_b32 s40, s36, s69
	v_lshl_add_u64 v[210:211], s[38:39], 0, v[138:139]
	s_add_i32 m0, s54, 0xc000
	ds_read_b128 v[178:181], v144
	ds_read_b128 v[182:185], v144 offset:1024
	ds_read_b128 v[186:189], v144 offset:2048
	ds_read_b128 v[190:193], v144 offset:3072
	ds_read_b128 v[194:197], v144 offset:4096
	ds_read_b128 v[198:201], v144 offset:5120
	ds_read_b128 v[202:205], v144 offset:6144
	ds_read_b128 v[206:209], v144 offset:7168
	global_load_lds_dwordx4 v[210:211], off
	v_lshl_add_u64 v[210:211], s[38:39], 0, v[136:137]
	s_add_i32 m0, s54, 0xe000
	s_nop 0
	global_load_lds_dwordx4 v[210:211], off
	s_waitcnt vmcnt(8)
	s_waitcnt lgkmcnt(0)
	s_barrier
	s_waitcnt lgkmcnt(0)
	v_mfma_f32_16x16x32_bf16 v[124:127], v[146:149], v[178:181], v[124:127]
	v_mfma_f32_16x16x32_bf16 v[120:123], v[154:157], v[178:181], v[120:123]
	v_mfma_f32_16x16x32_bf16 v[116:119], v[146:149], v[186:189], v[116:119]
	v_mfma_f32_16x16x32_bf16 v[112:115], v[154:157], v[186:189], v[112:115]
	v_mfma_f32_16x16x32_bf16 v[100:103], v[146:149], v[194:197], v[100:103]
	v_mfma_f32_16x16x32_bf16 v[96:99], v[154:157], v[194:197], v[96:99]
	v_mfma_f32_16x16x32_bf16 v[84:87], v[146:149], v[202:205], v[84:87]
	v_mfma_f32_16x16x32_bf16 v[80:83], v[154:157], v[202:205], v[80:83]
	v_mfma_f32_16x16x32_bf16 v[124:127], v[150:153], v[182:185], v[124:127]
	v_mfma_f32_16x16x32_bf16 v[120:123], v[158:161], v[182:185], v[120:123]
	v_mfma_f32_16x16x32_bf16 v[116:119], v[150:153], v[190:193], v[116:119]
	v_mfma_f32_16x16x32_bf16 v[112:115], v[158:161], v[190:193], v[112:115]
	v_mfma_f32_16x16x32_bf16 v[100:103], v[150:153], v[198:201], v[100:103]
	v_mfma_f32_16x16x32_bf16 v[96:99], v[158:161], v[198:201], v[96:99]
	v_mfma_f32_16x16x32_bf16 v[84:87], v[150:153], v[206:209], v[84:87]
	v_mfma_f32_16x16x32_bf16 v[80:83], v[158:161], v[206:209], v[80:83]
	v_mfma_f32_16x16x32_bf16 v[108:111], v[162:165], v[178:181], v[108:111]
	v_mfma_f32_16x16x32_bf16 v[104:107], v[170:173], v[178:181], v[104:107]
	v_mfma_f32_16x16x32_bf16 v[92:95], v[162:165], v[186:189], v[92:95]
	v_mfma_f32_16x16x32_bf16 v[88:91], v[170:173], v[186:189], v[88:91]
	v_mfma_f32_16x16x32_bf16 v[76:79], v[162:165], v[194:197], v[76:79]
	v_mfma_f32_16x16x32_bf16 v[72:75], v[170:173], v[194:197], v[72:75]
	v_mfma_f32_16x16x32_bf16 v[68:71], v[162:165], v[202:205], v[68:71]
	v_mfma_f32_16x16x32_bf16 v[64:67], v[170:173], v[202:205], v[64:67]
	v_mfma_f32_16x16x32_bf16 v[108:111], v[166:169], v[182:185], v[108:111]
	v_mfma_f32_16x16x32_bf16 v[104:107], v[174:177], v[182:185], v[104:107]
	v_mfma_f32_16x16x32_bf16 v[92:95], v[166:169], v[190:193], v[92:95]
	v_mfma_f32_16x16x32_bf16 v[88:91], v[174:177], v[190:193], v[88:91]
	v_mfma_f32_16x16x32_bf16 v[76:79], v[166:169], v[198:201], v[76:79]
	v_mfma_f32_16x16x32_bf16 v[72:75], v[174:177], v[198:201], v[72:75]
	v_mfma_f32_16x16x32_bf16 v[68:71], v[166:169], v[206:209], v[68:71]
	v_mfma_f32_16x16x32_bf16 v[64:67], v[174:177], v[206:209], v[64:67]
	s_barrier
; #define PG8_STAGE(bufoff, gbase, voff) do { _Pragma("unroll") for (int _i = 0; _i < 2; ++_i) \
;         __builtin_amdgcn_global_load_lds((const unsigned*)((const char*)(gbase) + (voff)[_i]), (LAS unsigned*)(lds + (bufoff) + ldsw + _i * 8192), 16, 0, 0); } while (0)
; #define PG8_LDA(dst, b, h) do { _Pragma("unroll") for (int m = 0; m < 4; ++m) _Pragma("unroll") for (int k = 0; k < 2; ++k) dst[m][k] = *(const LAS bf16x8*)(lds + PG8_SA(b, h) + aoff + m * 2048 + k * 1024); } while (0)
; #define PG8_LDB(dst, b, h) do { _Pragma("unroll") for (int n = 0; n < 2; ++n) _Pragma("unroll") for (int k = 0; k < 2; ++k) dst[n][k] = *(const LAS bf16x8*)(lds + PG8_SB(b, h) + boff + n * 2048 + k * 1024); } while (0)
; #define PG8_MMA(ai, bj, At, Bt) do { __builtin_amdgcn_s_setprio(1); _Pragma("unroll") for (int m = 0; m < 4; ++m) _Pragma("unroll") for (int n = 0; n < 2; ++n) _Pragma("unroll") for (int k = 0; k < 2; ++k) \
;         acc[ai][bj][m][n] = __builtin_amdgcn_mfma_f32_16x16x32_bf16(Bt[n][k], At[m][k], acc[ai][bj][m][n], 0, 0, 0); __builtin_amdgcn_s_setprio(0); } while (0)
; #define PG8_WAIT_V(n) asm volatile("s_waitcnt vmcnt(" #n ")" ::: "memory")
; #define PG8_WAIT_L(n) asm volatile("s_waitcnt lgkmcnt(" #n ")" ::: "memory")
; #define PG8_BAR __builtin_amdgcn_s_barrier()
; #define PG8_SCHED __builtin_amdgcn_sched_barrier(0)
; template <class Epi, class Sched>
; __device__ __forceinline__ void gemm_phase(LAS unsigned char* lds, const GemmP g, const Sched& S, const Epi& E, int tid) {
;     ...
;             PG8_LDA(At, 0, 1); PG8_STAGE(PG8_SB(0, 0), b2, voffB); PG8_STAGE(PG8_SB(0, 1), b2 + hstepB, voffB); PG8_STAGE(PG8_SA(0, 0), a2, voffA);
;             PG8_WAIT_V(8); PG8_WAIT_L(0); PG8_BAR; PG8_MMA(1, 0, At, B0); PG8_MMA(1, 1, At, B1); PG8_BAR; PG8_SCHED;
;             PG8_LDB(B0, 1, 0); PG8_LDB(B1, 1, 1); PG8_SCHED; PG8_LDA(At, 1, 0); PG8_STAGE(PG8_SA(0, 1), a2 + hstepA, voffA);
;             PG8_WAIT_V(8); PG8_WAIT_L(0); PG8_BAR; PG8_MMA(0, 0, At, B0); PG8_MMA(0, 1, At, B1); PG8_BAR; PG8_SCHED;
	s_add_i32 s72, s63, s53
	v_lshl_add_u64 v[210:211], s[40:41], 0, v[132:133]
	s_mov_b32 m0, s72
	ds_read_b128 v[178:181], v144 offset:16384
	ds_read_b128 v[182:185], v144 offset:17408
	ds_read_b128 v[186:189], v144 offset:18432
	ds_read_b128 v[190:193], v144 offset:19456
	ds_read_b128 v[194:197], v144 offset:20480
	ds_read_b128 v[198:201], v144 offset:21504
	ds_read_b128 v[202:205], v144 offset:22528
	ds_read_b128 v[206:209], v144 offset:23552
	global_load_lds_dwordx4 v[210:211], off
	s_add_i32 m0, s72, 0x2000
	s_add_u32 s72, s40, 0x40000
	v_lshl_add_u64 v[212:213], s[40:41], 0, v[128:129]
	s_addc_u32 s73, s41, 0
	s_add_i32 s74, s64, s53
	global_load_lds_dwordx4 v[212:213], off
	v_lshl_add_u64 v[214:215], s[72:73], 0, v[132:133]
	s_mov_b32 m0, s74
	v_lshl_add_u64 v[216:217], s[44:45], 0, v[130:131]
	global_load_lds_dwordx4 v[214:215], off
	v_lshl_add_u64 v[214:215], s[72:73], 0, v[128:129]
	s_add_i32 m0, s74, 0x2000
	s_nop 0
	global_load_lds_dwordx4 v[214:215], off
	v_lshl_add_u64 v[214:215], s[44:45], 0, v[134:135]
	s_mov_b32 m0, s54
	s_nop 0
	global_load_lds_dwordx4 v[214:215], off
	s_mov_b32 m0, s55
	s_nop 0
	global_load_lds_dwordx4 v[216:217], off
	s_waitcnt vmcnt(8)
	s_waitcnt lgkmcnt(0)
	s_barrier
	s_waitcnt lgkmcnt(0)
	v_mfma_f32_16x16x32_bf16 v[60:63], v[146:149], v[178:181], v[60:63]
	v_mfma_f32_16x16x32_bf16 v[56:59], v[154:157], v[178:181], v[56:59]
	v_mfma_f32_16x16x32_bf16 v[52:55], v[146:149], v[186:189], v[52:55]
	v_mfma_f32_16x16x32_bf16 v[48:51], v[154:157], v[186:189], v[48:51]
	v_mfma_f32_16x16x32_bf16 v[36:39], v[146:149], v[194:197], v[36:39]
	v_mfma_f32_16x16x32_bf16 v[32:35], v[154:157], v[194:197], v[32:35]
	v_mfma_f32_16x16x32_bf16 v[20:23], v[146:149], v[202:205], v[20:23]
	v_mfma_f32_16x16x32_bf16 v[16:19], v[154:157], v[202:205], v[16:19]
	v_mfma_f32_16x16x32_bf16 v[60:63], v[150:153], v[182:185], v[60:63]
	v_mfma_f32_16x16x32_bf16 v[56:59], v[158:161], v[182:185], v[56:59]
	v_mfma_f32_16x16x32_bf16 v[52:55], v[150:153], v[190:193], v[52:55]
	v_mfma_f32_16x16x32_bf16 v[48:51], v[158:161], v[190:193], v[48:51]
	v_mfma_f32_16x16x32_bf16 v[36:39], v[150:153], v[198:201], v[36:39]
	v_mfma_f32_16x16x32_bf16 v[32:35], v[158:161], v[198:201], v[32:35]
	v_mfma_f32_16x16x32_bf16 v[20:23], v[150:153], v[206:209], v[20:23]
	v_mfma_f32_16x16x32_bf16 v[16:19], v[158:161], v[206:209], v[16:19]
	v_mfma_f32_16x16x32_bf16 v[44:47], v[162:165], v[178:181], v[44:47]
	v_mfma_f32_16x16x32_bf16 v[40:43], v[170:173], v[178:181], v[40:43]
	v_mfma_f32_16x16x32_bf16 v[28:31], v[162:165], v[186:189], v[28:31]
	v_mfma_f32_16x16x32_bf16 v[24:27], v[170:173], v[186:189], v[24:27]
	v_mfma_f32_16x16x32_bf16 v[12:15], v[162:165], v[194:197], v[12:15]
	v_mfma_f32_16x16x32_bf16 v[8:11], v[170:173], v[194:197], v[8:11]
	v_mfma_f32_16x16x32_bf16 v[4:7], v[162:165], v[202:205], v[4:7]
	v_mfma_f32_16x16x32_bf16 v[0:3], v[170:173], v[202:205], v[0:3]
	v_mfma_f32_16x16x32_bf16 v[44:47], v[166:169], v[182:185], v[44:47]
	v_mfma_f32_16x16x32_bf16 v[40:43], v[174:177], v[182:185], v[40:43]
	v_mfma_f32_16x16x32_bf16 v[28:31], v[166:169], v[190:193], v[28:31]
	v_mfma_f32_16x16x32_bf16 v[24:27], v[174:177], v[190:193], v[24:27]
	v_mfma_f32_16x16x32_bf16 v[12:15], v[166:169], v[198:201], v[12:15]
	v_mfma_f32_16x16x32_bf16 v[8:11], v[174:177], v[198:201], v[8:11]
	v_mfma_f32_16x16x32_bf16 v[4:7], v[166:169], v[206:209], v[4:7]
	v_mfma_f32_16x16x32_bf16 v[0:3], v[174:177], v[206:209], v[0:3]
	s_barrier
	s_add_i32 s72, 0, 0x18000
	v_add_u32_e32 v145, s72, v141
	s_add_i32 s73, 0, 0x1c000
	ds_read_b128 v[146:149], v145
	ds_read_b128 v[150:153], v145 offset:1024
	ds_read_b128 v[154:157], v145 offset:2048
	ds_read_b128 v[158:161], v145 offset:3072
	v_add_u32_e32 v145, s73, v141
	ds_read_b128 v[162:165], v145
	ds_read_b128 v[166:169], v145 offset:1024
	ds_read_b128 v[170:173], v145 offset:2048
	ds_read_b128 v[174:177], v145 offset:3072
	s_add_u32 s44, s44, 0x40000
	s_addc_u32 s45, s45, 0
	s_mov_b32 m0, s56
	v_lshl_add_u64 v[218:219], s[44:45], 0, v[134:135]
	ds_read_b128 v[178:181], v144 offset:32768
	ds_read_b128 v[182:185], v144 offset:33792
	ds_read_b128 v[186:189], v144 offset:34816
	ds_read_b128 v[190:193], v144 offset:35840
	ds_read_b128 v[194:197], v144 offset:36864
	ds_read_b128 v[198:201], v144 offset:37888
	ds_read_b128 v[202:205], v144 offset:38912
	ds_read_b128 v[206:209], v144 offset:39936
	global_load_lds_dwordx4 v[218:219], off
	v_lshl_add_u64 v[218:219], s[44:45], 0, v[130:131]
	s_mov_b32 m0, s57
	s_nop 0
	global_load_lds_dwordx4 v[218:219], off
	s_waitcnt vmcnt(8)
	s_waitcnt lgkmcnt(0)
	s_barrier
; #define PG8_STAGE(bufoff, gbase, voff) do { _Pragma("unroll") for (int _i = 0; _i < 2; ++_i) \
;         __builtin_amdgcn_global_load_lds((const unsigned*)((const char*)(gbase) + (voff)[_i]), (LAS unsigned*)(lds + (bufoff) + ldsw + _i * 8192), 16, 0, 0); } while (0)
; #define PG8_LDA(dst, b, h) do { _Pragma("unroll") for (int m = 0; m < 4; ++m) _Pragma("unroll") for (int k = 0; k < 2; ++k) dst[m][k] = *(const LAS bf16x8*)(lds + PG8_SA(b, h) + aoff + m * 2048 + k * 1024); } while (0)
; #define PG8_MMA(ai, bj, At, Bt) do { __builtin_amdgcn_s_setprio(1); _Pragma("unroll") for (int m = 0; m < 4; ++m) _Pragma("unroll") for (int n = 0; n < 2; ++n) _Pragma("unroll") for (int k = 0; k < 2; ++k) \
;         acc[ai][bj][m][n] = __builtin_amdgcn_mfma_f32_16x16x32_bf16(Bt[n][k], At[m][k], acc[ai][bj][m][n], 0, 0, 0); __builtin_amdgcn_s_setprio(0); } while (0)
; #define PG8_WAIT_V(n) asm volatile("s_waitcnt vmcnt(" #n ")" ::: "memory")
; #define PG8_WAIT_L(n) asm volatile("s_waitcnt lgkmcnt(" #n ")" ::: "memory")
; #define PG8_BAR __builtin_amdgcn_s_barrier()
; #define PG8_SCHED __builtin_amdgcn_sched_barrier(0)
; template <class Epi, class Sched>
; __device__ __forceinline__ void gemm_phase(LAS unsigned char* lds, const GemmP g, const Sched& S, const Epi& E, int tid) {
;     ...
;             PG8_WAIT_V(8); PG8_WAIT_L(0); PG8_BAR; PG8_MMA(0, 0, At, B0); PG8_MMA(0, 1, At, B1); PG8_BAR; PG8_SCHED;
;             PG8_LDA(At, 1, 1); PG8_STAGE(PG8_SB(1, 0), b3, voffB); PG8_STAGE(PG8_SB(1, 1), b3 + hstepB, voffB); PG8_STAGE(PG8_SA(1, 0), a3, voffA);
;             PG8_WAIT_V(8); PG8_WAIT_L(0); PG8_BAR; PG8_MMA(1, 0, At, B0); PG8_MMA(1, 1, At, B1); PG8_BAR; PG8_SCHED;
;         }
	s_waitcnt lgkmcnt(0)
	v_mfma_f32_16x16x32_bf16 v[124:127], v[146:149], v[178:181], v[124:127]
	v_mfma_f32_16x16x32_bf16 v[120:123], v[154:157], v[178:181], v[120:123]
	v_mfma_f32_16x16x32_bf16 v[116:119], v[146:149], v[186:189], v[116:119]
	v_mfma_f32_16x16x32_bf16 v[112:115], v[154:157], v[186:189], v[112:115]
	v_mfma_f32_16x16x32_bf16 v[100:103], v[146:149], v[194:197], v[100:103]
	v_mfma_f32_16x16x32_bf16 v[96:99], v[154:157], v[194:197], v[96:99]
	v_mfma_f32_16x16x32_bf16 v[84:87], v[146:149], v[202:205], v[84:87]
	v_mfma_f32_16x16x32_bf16 v[80:83], v[154:157], v[202:205], v[80:83]
	v_mfma_f32_16x16x32_bf16 v[124:127], v[150:153], v[182:185], v[124:127]
	v_mfma_f32_16x16x32_bf16 v[120:123], v[158:161], v[182:185], v[120:123]
	v_mfma_f32_16x16x32_bf16 v[116:119], v[150:153], v[190:193], v[116:119]
	v_mfma_f32_16x16x32_bf16 v[112:115], v[158:161], v[190:193], v[112:115]
	v_mfma_f32_16x16x32_bf16 v[100:103], v[150:153], v[198:201], v[100:103]
	v_mfma_f32_16x16x32_bf16 v[96:99], v[158:161], v[198:201], v[96:99]
	v_mfma_f32_16x16x32_bf16 v[84:87], v[150:153], v[206:209], v[84:87]
	v_mfma_f32_16x16x32_bf16 v[80:83], v[158:161], v[206:209], v[80:83]
	v_mfma_f32_16x16x32_bf16 v[108:111], v[162:165], v[178:181], v[108:111]
	v_mfma_f32_16x16x32_bf16 v[104:107], v[170:173], v[178:181], v[104:107]
	v_mfma_f32_16x16x32_bf16 v[92:95], v[162:165], v[186:189], v[92:95]
	v_mfma_f32_16x16x32_bf16 v[88:91], v[170:173], v[186:189], v[88:91]
	v_mfma_f32_16x16x32_bf16 v[76:79], v[162:165], v[194:197], v[76:79]
	v_mfma_f32_16x16x32_bf16 v[72:75], v[170:173], v[194:197], v[72:75]
	v_mfma_f32_16x16x32_bf16 v[68:71], v[162:165], v[202:205], v[68:71]
	v_mfma_f32_16x16x32_bf16 v[64:67], v[170:173], v[202:205], v[64:67]
	v_mfma_f32_16x16x32_bf16 v[108:111], v[166:169], v[182:185], v[108:111]
	v_mfma_f32_16x16x32_bf16 v[104:107], v[174:177], v[182:185], v[104:107]
	v_mfma_f32_16x16x32_bf16 v[92:95], v[166:169], v[190:193], v[92:95]
	v_mfma_f32_16x16x32_bf16 v[88:91], v[174:177], v[190:193], v[88:91]
	v_mfma_f32_16x16x32_bf16 v[76:79], v[166:169], v[198:201], v[76:79]
	v_mfma_f32_16x16x32_bf16 v[72:75], v[174:177], v[198:201], v[72:75]
	v_mfma_f32_16x16x32_bf16 v[68:71], v[166:169], v[206:209], v[68:71]
	v_mfma_f32_16x16x32_bf16 v[64:67], v[174:177], v[206:209], v[64:67]
	s_barrier
	s_add_i32 s44, s72, s53
	v_lshl_add_u64 v[210:211], v[210:211], 0, s[12:13]
	s_mov_b32 m0, s44
	ds_read_b128 v[178:181], v144 offset:49152
	ds_read_b128 v[182:185], v144 offset:50176
	ds_read_b128 v[186:189], v144 offset:51200
	ds_read_b128 v[190:193], v144 offset:52224
	ds_read_b128 v[194:197], v144 offset:53248
	ds_read_b128 v[198:201], v144 offset:54272
	ds_read_b128 v[202:205], v144 offset:55296
	ds_read_b128 v[206:209], v144 offset:56320
	global_load_lds_dwordx4 v[210:211], off
	s_add_i32 m0, s44, 0x2000
	s_add_u32 s40, s40, 0x40080
	v_lshl_add_u64 v[210:211], v[212:213], 0, s[12:13]
	s_addc_u32 s41, s41, 0
	s_add_i32 s44, s73, s53
	global_load_lds_dwordx4 v[210:211], off
	v_lshl_add_u64 v[210:211], s[40:41], 0, v[132:133]
	s_mov_b32 m0, s44
	s_nop 0
	global_load_lds_dwordx4 v[210:211], off
	v_lshl_add_u64 v[210:211], s[40:41], 0, v[128:129]
	s_add_i32 m0, s44, 0x2000
	s_nop 0
	global_load_lds_dwordx4 v[210:211], off
	v_lshl_add_u64 v[210:211], v[214:215], 0, s[12:13]
	s_mov_b32 m0, s61
	s_nop 0
	global_load_lds_dwordx4 v[210:211], off
	v_lshl_add_u64 v[210:211], v[216:217], 0, s[12:13]
	s_mov_b32 m0, s62
	s_nop 0
	global_load_lds_dwordx4 v[210:211], off
	s_waitcnt vmcnt(8)
	s_waitcnt lgkmcnt(0)
	s_barrier
	s_waitcnt lgkmcnt(0)
	v_mfma_f32_16x16x32_bf16 v[60:63], v[146:149], v[178:181], v[60:63]
	v_mfma_f32_16x16x32_bf16 v[56:59], v[154:157], v[178:181], v[56:59]
	v_mfma_f32_16x16x32_bf16 v[52:55], v[146:149], v[186:189], v[52:55]
	v_mfma_f32_16x16x32_bf16 v[48:51], v[154:157], v[186:189], v[48:51]
	v_mfma_f32_16x16x32_bf16 v[36:39], v[146:149], v[194:197], v[36:39]
	v_mfma_f32_16x16x32_bf16 v[32:35], v[154:157], v[194:197], v[32:35]
	v_mfma_f32_16x16x32_bf16 v[20:23], v[146:149], v[202:205], v[20:23]
	v_mfma_f32_16x16x32_bf16 v[16:19], v[154:157], v[202:205], v[16:19]
	v_mfma_f32_16x16x32_bf16 v[60:63], v[150:153], v[182:185], v[60:63]
	v_mfma_f32_16x16x32_bf16 v[56:59], v[158:161], v[182:185], v[56:59]
	v_mfma_f32_16x16x32_bf16 v[52:55], v[150:153], v[190:193], v[52:55]
	v_mfma_f32_16x16x32_bf16 v[48:51], v[158:161], v[190:193], v[48:51]
	v_mfma_f32_16x16x32_bf16 v[36:39], v[150:153], v[198:201], v[36:39]
	v_mfma_f32_16x16x32_bf16 v[32:35], v[158:161], v[198:201], v[32:35]
	v_mfma_f32_16x16x32_bf16 v[20:23], v[150:153], v[206:209], v[20:23]
	v_mfma_f32_16x16x32_bf16 v[16:19], v[158:161], v[206:209], v[16:19]
	v_mfma_f32_16x16x32_bf16 v[44:47], v[162:165], v[178:181], v[44:47]
	v_mfma_f32_16x16x32_bf16 v[40:43], v[170:173], v[178:181], v[40:43]
	v_mfma_f32_16x16x32_bf16 v[28:31], v[162:165], v[186:189], v[28:31]
	v_mfma_f32_16x16x32_bf16 v[24:27], v[170:173], v[186:189], v[24:27]
	v_mfma_f32_16x16x32_bf16 v[12:15], v[162:165], v[194:197], v[12:15]
	v_mfma_f32_16x16x32_bf16 v[8:11], v[170:173], v[194:197], v[8:11]
	v_mfma_f32_16x16x32_bf16 v[4:7], v[162:165], v[202:205], v[4:7]
	v_mfma_f32_16x16x32_bf16 v[0:3], v[170:173], v[202:205], v[0:3]
	v_mfma_f32_16x16x32_bf16 v[44:47], v[166:169], v[182:185], v[44:47]
	v_mfma_f32_16x16x32_bf16 v[40:43], v[174:177], v[182:185], v[40:43]
	v_mfma_f32_16x16x32_bf16 v[28:31], v[166:169], v[190:193], v[28:31]
	v_mfma_f32_16x16x32_bf16 v[24:27], v[174:177], v[190:193], v[24:27]
	v_mfma_f32_16x16x32_bf16 v[12:15], v[166:169], v[198:201], v[12:15]
	v_mfma_f32_16x16x32_bf16 v[8:11], v[174:177], v[198:201], v[8:11]
	v_mfma_f32_16x16x32_bf16 v[4:7], v[166:169], v[206:209], v[4:7]
	v_mfma_f32_16x16x32_bf16 v[0:3], v[174:177], v[206:209], v[0:3]
	s_barrier
	s_add_i32 s71, s71, 2
	s_add_u32 s69, s69, 0x100
	s_addc_u32 s70, s70, 0
	s_add_u32 s38, s38, 0x100
	s_addc_u32 s39, s39, 0
	s_cmp_gt_u32 s71, 13
	s_cbranch_scc0 .LBB0_223
	s_setprio 0
	s_and_b64 vcc, exec, s[14:15]
	s_cbranch_vccz .LBB0_226
	s_barrier

; #define PG8_STAGE(bufoff, gbase, voff) do { _Pragma("unroll") for (int _i = 0; _i < 2; ++_i) \
;         __builtin_amdgcn_global_load_lds((const unsigned*)((const char*)(gbase) + (voff)[_i]), (LAS unsigned*)(lds + (bufoff) + ldsw + _i * 8192), 16, 0, 0); } while (0)
; #define PG8_LDA(dst, b, h) do { _Pragma("unroll") for (int m = 0; m < 4; ++m) _Pragma("unroll") for (int k = 0; k < 2; ++k) dst[m][k] = *(const LAS bf16x8*)(lds + PG8_SA(b, h) + aoff + m * 2048 + k * 1024); } while (0)
; #define PG8_LDB(dst, b, h) do { _Pragma("unroll") for (int n = 0; n < 2; ++n) _Pragma("unroll") for (int k = 0; k < 2; ++k) dst[n][k] = *(const LAS bf16x8*)(lds + PG8_SB(b, h) + boff + n * 2048 + k * 1024); } while (0)
; #define PG8_MMA(ai, bj, At, Bt) do { __builtin_amdgcn_s_setprio(1); _Pragma("unroll") for (int m = 0; m < 4; ++m) _Pragma("unroll") for (int n = 0; n < 2; ++n) _Pragma("unroll") for (int k = 0; k < 2; ++k) \
;         acc[ai][bj][m][n] = __builtin_amdgcn_mfma_f32_16x16x32_bf16(Bt[n][k], At[m][k], acc[ai][bj][m][n], 0, 0, 0); __builtin_amdgcn_s_setprio(0); } while (0)
; #define PG8_WAIT_V(n) asm volatile("s_waitcnt vmcnt(" #n ")" ::: "memory")
; #define PG8_WAIT_L(n) asm volatile("s_waitcnt lgkmcnt(" #n ")" ::: "memory")
; #define PG8_BAR __builtin_amdgcn_s_barrier()
; template <class Epi, class Sched>
; __device__ __forceinline__ void gemm_phase(LAS unsigned char* lds, const GemmP g, const Sched& S, const Epi& E, int tid) {
;     ...
;         for (int t = 0; t < nt; t += 2) {
;             const bool last = (t == nt - 2);
;             const char* a1 = cA + (size_t)(t + 1) * kstep;
;             const char* a2 = last ? nA : cA + (size_t)(t + 2) * kstep; const char* b2 = last ? nB : cB + (size_t)(t + 2) * kstep;
;             const char* a3 = a2 + kstep; const char* b3 = b2 + kstep;
;             PG8_LDB(B0, 0, 0); PG8_LDB(B1, 0, 1); PG8_SCHED; PG8_LDA(At, 0, 0); PG8_STAGE(PG8_SA(1, 1), a1 + hstepA, voffA);
;             PG8_WAIT_V(8); PG8_WAIT_L(0); PG8_BAR; PG8_MMA(0, 0, At, B0); PG8_MMA(0, 1, At, B1); PG8_BAR; PG8_SCHED;
;     ...
; #pragma unroll
;         for (int a = 0; a < 2; ++a)
; #pragma unroll
;             for (int b = 0; b < 2; ++b)
; #pragma unroll
;                 for (int m = 0; m < 4; ++m)
; #pragma unroll
;                     for (int n = 0; n < 2; ++n) acc[a][b][m][n] = (f32x4){0.f, 0.f, 0.f, 0.f};
;         cur = nxt; cA = nA; cB = nB; ++ui;
.LBB0_242:
	s_add_u32 s62, s38, 0x100
	s_addc_u32 s63, s39, 0
	s_add_u32 s36, s36, 0x40080
	v_mov_b32_e32 v0, 0
	s_addc_u32 s37, s37, 0
	s_mov_b32 s64, -2
	v_mov_b32_e32 v1, v0
	v_mov_b32_e32 v2, v0
	v_mov_b32_e32 v3, v0
	v_mov_b32_e32 v4, v0
	v_mov_b32_e32 v5, v0
	v_mov_b32_e32 v6, v0
	v_mov_b32_e32 v7, v0
	v_mov_b32_e32 v8, v0
	v_mov_b32_e32 v9, v0
	v_mov_b32_e32 v10, v0
	v_mov_b32_e32 v11, v0
	v_mov_b32_e32 v12, v0
	v_mov_b32_e32 v13, v0
	v_mov_b32_e32 v14, v0
	v_mov_b32_e32 v15, v0
	v_mov_b32_e32 v24, v0
	v_mov_b32_e32 v25, v0
	v_mov_b32_e32 v26, v0
	v_mov_b32_e32 v27, v0
	v_mov_b32_e32 v28, v0
	v_mov_b32_e32 v29, v0
	v_mov_b32_e32 v30, v0
	v_mov_b32_e32 v31, v0
	v_mov_b32_e32 v40, v0
	v_mov_b32_e32 v41, v0
	v_mov_b32_e32 v42, v0
	v_mov_b32_e32 v43, v0
	v_mov_b32_e32 v44, v0
	v_mov_b32_e32 v45, v0
	v_mov_b32_e32 v46, v0
	v_mov_b32_e32 v47, v0
	v_mov_b32_e32 v16, v0
	v_mov_b32_e32 v17, v0
	v_mov_b32_e32 v18, v0
	v_mov_b32_e32 v19, v0
	v_mov_b32_e32 v20, v0
	v_mov_b32_e32 v21, v0
	v_mov_b32_e32 v22, v0
	v_mov_b32_e32 v23, v0
	v_mov_b32_e32 v32, v0
	v_mov_b32_e32 v33, v0
	v_mov_b32_e32 v34, v0
	v_mov_b32_e32 v35, v0
	v_mov_b32_e32 v36, v0
	v_mov_b32_e32 v37, v0
	v_mov_b32_e32 v38, v0
	v_mov_b32_e32 v39, v0
	v_mov_b32_e32 v48, v0
	v_mov_b32_e32 v49, v0
	v_mov_b32_e32 v50, v0
	v_mov_b32_e32 v51, v0
	v_mov_b32_e32 v52, v0
	v_mov_b32_e32 v53, v0
	v_mov_b32_e32 v54, v0
	v_mov_b32_e32 v55, v0
	v_mov_b32_e32 v56, v0
	v_mov_b32_e32 v57, v0
	v_mov_b32_e32 v58, v0
	v_mov_b32_e32 v59, v0
	v_mov_b32_e32 v60, v0
	v_mov_b32_e32 v61, v0
	v_mov_b32_e32 v62, v0
	v_mov_b32_e32 v63, v0
	v_mov_b32_e32 v64, v0
	v_mov_b32_e32 v65, v0
	v_mov_b32_e32 v66, v0
	v_mov_b32_e32 v67, v0
	v_mov_b32_e32 v68, v0
	v_mov_b32_e32 v69, v0
	v_mov_b32_e32 v70, v0
	v_mov_b32_e32 v71, v0
	v_mov_b32_e32 v72, v0
	v_mov_b32_e32 v73, v0
	v_mov_b32_e32 v74, v0
	v_mov_b32_e32 v75, v0
	v_mov_b32_e32 v76, v0
	v_mov_b32_e32 v77, v0
	v_mov_b32_e32 v78, v0
	v_mov_b32_e32 v79, v0
	v_mov_b32_e32 v88, v0
	v_mov_b32_e32 v89, v0
	v_mov_b32_e32 v90, v0
	v_mov_b32_e32 v91, v0
	v_mov_b32_e32 v92, v0
	v_mov_b32_e32 v93, v0
	v_mov_b32_e32 v94, v0
	v_mov_b32_e32 v95, v0
	v_mov_b32_e32 v104, v0
	v_mov_b32_e32 v105, v0
	v_mov_b32_e32 v106, v0
	v_mov_b32_e32 v107, v0
	v_mov_b32_e32 v108, v0
	v_mov_b32_e32 v109, v0
	v_mov_b32_e32 v110, v0
	v_mov_b32_e32 v111, v0
	v_mov_b32_e32 v80, v0
	v_mov_b32_e32 v81, v0
	v_mov_b32_e32 v82, v0
	v_mov_b32_e32 v83, v0
	v_mov_b32_e32 v84, v0
	v_mov_b32_e32 v85, v0
	v_mov_b32_e32 v86, v0
	v_mov_b32_e32 v87, v0
	v_mov_b32_e32 v96, v0
	v_mov_b32_e32 v97, v0
	v_mov_b32_e32 v98, v0
	v_mov_b32_e32 v99, v0
	v_mov_b32_e32 v100, v0
	v_mov_b32_e32 v101, v0
	v_mov_b32_e32 v102, v0
	v_mov_b32_e32 v103, v0
	v_mov_b32_e32 v112, v0
	v_mov_b32_e32 v113, v0
	v_mov_b32_e32 v114, v0
	v_mov_b32_e32 v115, v0
	v_mov_b32_e32 v116, v0
	v_mov_b32_e32 v117, v0
	v_mov_b32_e32 v118, v0
	v_mov_b32_e32 v119, v0
	v_mov_b32_e32 v120, v0
	v_mov_b32_e32 v121, v0
	v_mov_b32_e32 v122, v0
	v_mov_b32_e32 v123, v0
	v_mov_b32_e32 v124, v0
	v_mov_b32_e32 v125, v0
	v_mov_b32_e32 v126, v0
	v_mov_b32_e32 v127, v0
	s_cmp_lg_u64 s[12:13], 0
	s_cbranch_scc1 .Lsp_243
	s_setprio 1
.Lsp_243:
.LBB0_243:
	ds_read_b128 v[144:147], v141
	ds_read_b128 v[148:151], v141 offset:1024
	ds_read_b128 v[152:155], v141 offset:2048
	ds_read_b128 v[156:159], v141 offset:3072
	ds_read_b128 v[160:163], v142
	ds_read_b128 v[164:167], v142 offset:1024
	ds_read_b128 v[168:171], v142 offset:2048
	ds_read_b128 v[172:175], v142 offset:3072
	s_add_u32 s38, s36, 0xfffc0080
	s_addc_u32 s39, s37, -1
	s_cmp_eq_u32 s64, 12
	s_cselect_b32 s41, s31, s39
	s_cselect_b32 s40, s30, s38
	s_cselect_b32 s39, s35, s63
	s_cselect_b32 s38, s34, s62
	v_lshl_add_u64 v[208:209], s[36:37], 0, v[138:139]
	s_add_i32 m0, s49, 0xc000
	ds_read_b128 v[176:179], v143
	ds_read_b128 v[180:183], v143 offset:1024
	ds_read_b128 v[184:187], v143 offset:2048
	ds_read_b128 v[188:191], v143 offset:3072
	ds_read_b128 v[192:195], v143 offset:4096
	ds_read_b128 v[196:199], v143 offset:5120
	ds_read_b128 v[200:203], v143 offset:6144
	ds_read_b128 v[204:207], v143 offset:7168
	global_load_lds_dwordx4 v[208:209], off
	v_lshl_add_u64 v[208:209], s[36:37], 0, v[136:137]
	s_add_i32 m0, s49, 0xe000
	s_nop 0
	global_load_lds_dwordx4 v[208:209], off
	s_waitcnt vmcnt(8)
	s_waitcnt lgkmcnt(0)
	s_barrier
	s_waitcnt lgkmcnt(0)
	v_mfma_f32_16x16x32_bf16 v[124:127], v[144:147], v[176:179], v[124:127]
	v_mfma_f32_16x16x32_bf16 v[120:123], v[152:155], v[176:179], v[120:123]
	v_mfma_f32_16x16x32_bf16 v[116:119], v[144:147], v[184:187], v[116:119]
	v_mfma_f32_16x16x32_bf16 v[112:115], v[152:155], v[184:187], v[112:115]
	v_mfma_f32_16x16x32_bf16 v[100:103], v[144:147], v[192:195], v[100:103]
	v_mfma_f32_16x16x32_bf16 v[96:99], v[152:155], v[192:195], v[96:99]
	v_mfma_f32_16x16x32_bf16 v[84:87], v[144:147], v[200:203], v[84:87]
	v_mfma_f32_16x16x32_bf16 v[80:83], v[152:155], v[200:203], v[80:83]
	v_mfma_f32_16x16x32_bf16 v[124:127], v[148:151], v[180:183], v[124:127]
	v_mfma_f32_16x16x32_bf16 v[120:123], v[156:159], v[180:183], v[120:123]
	v_mfma_f32_16x16x32_bf16 v[116:119], v[148:151], v[188:191], v[116:119]
	v_mfma_f32_16x16x32_bf16 v[112:115], v[156:159], v[188:191], v[112:115]
	v_mfma_f32_16x16x32_bf16 v[100:103], v[148:151], v[196:199], v[100:103]
	v_mfma_f32_16x16x32_bf16 v[96:99], v[156:159], v[196:199], v[96:99]
	v_mfma_f32_16x16x32_bf16 v[84:87], v[148:151], v[204:207], v[84:87]
	v_mfma_f32_16x16x32_bf16 v[80:83], v[156:159], v[204:207], v[80:83]
	v_mfma_f32_16x16x32_bf16 v[108:111], v[160:163], v[176:179], v[108:111]
	v_mfma_f32_16x16x32_bf16 v[104:107], v[168:171], v[176:179], v[104:107]
	v_mfma_f32_16x16x32_bf16 v[92:95], v[160:163], v[184:187], v[92:95]
	v_mfma_f32_16x16x32_bf16 v[88:91], v[168:171], v[184:187], v[88:91]
	v_mfma_f32_16x16x32_bf16 v[76:79], v[160:163], v[192:195], v[76:79]
	v_mfma_f32_16x16x32_bf16 v[72:75], v[168:171], v[192:195], v[72:75]
	v_mfma_f32_16x16x32_bf16 v[68:71], v[160:163], v[200:203], v[68:71]
	v_mfma_f32_16x16x32_bf16 v[64:67], v[168:171], v[200:203], v[64:67]
	v_mfma_f32_16x16x32_bf16 v[108:111], v[164:167], v[180:183], v[108:111]
	v_mfma_f32_16x16x32_bf16 v[104:107], v[172:175], v[180:183], v[104:107]
	v_mfma_f32_16x16x32_bf16 v[92:95], v[164:167], v[188:191], v[92:95]
	v_mfma_f32_16x16x32_bf16 v[88:91], v[172:175], v[188:191], v[88:91]
	v_mfma_f32_16x16x32_bf16 v[76:79], v[164:167], v[196:199], v[76:79]
	v_mfma_f32_16x16x32_bf16 v[72:75], v[172:175], v[196:199], v[72:75]
	v_mfma_f32_16x16x32_bf16 v[68:71], v[164:167], v[204:207], v[68:71]
	v_mfma_f32_16x16x32_bf16 v[64:67], v[172:175], v[204:207], v[64:67]
	s_barrier
; #define PG8_STAGE(bufoff, gbase, voff) do { _Pragma("unroll") for (int _i = 0; _i < 2; ++_i) \
;         __builtin_amdgcn_global_load_lds((const unsigned*)((const char*)(gbase) + (voff)[_i]), (LAS unsigned*)(lds + (bufoff) + ldsw + _i * 8192), 16, 0, 0); } while (0)
; #define PG8_LDA(dst, b, h) do { _Pragma("unroll") for (int m = 0; m < 4; ++m) _Pragma("unroll") for (int k = 0; k < 2; ++k) dst[m][k] = *(const LAS bf16x8*)(lds + PG8_SA(b, h) + aoff + m * 2048 + k * 1024); } while (0)
; #define PG8_LDB(dst, b, h) do { _Pragma("unroll") for (int n = 0; n < 2; ++n) _Pragma("unroll") for (int k = 0; k < 2; ++k) dst[n][k] = *(const LAS bf16x8*)(lds + PG8_SB(b, h) + boff + n * 2048 + k * 1024); } while (0)
; #define PG8_MMA(ai, bj, At, Bt) do { __builtin_amdgcn_s_setprio(1); _Pragma("unroll") for (int m = 0; m < 4; ++m) _Pragma("unroll") for (int n = 0; n < 2; ++n) _Pragma("unroll") for (int k = 0; k < 2; ++k) \
;         acc[ai][bj][m][n] = __builtin_amdgcn_mfma_f32_16x16x32_bf16(Bt[n][k], At[m][k], acc[ai][bj][m][n], 0, 0, 0); __builtin_amdgcn_s_setprio(0); } while (0)
; #define PG8_WAIT_V(n) asm volatile("s_waitcnt vmcnt(" #n ")" ::: "memory")
; #define PG8_WAIT_L(n) asm volatile("s_waitcnt lgkmcnt(" #n ")" ::: "memory")
; #define PG8_BAR __builtin_amdgcn_s_barrier()
; #define PG8_SCHED __builtin_amdgcn_sched_barrier(0)
; template <class Epi, class Sched>
; __device__ __forceinline__ void gemm_phase(LAS unsigned char* lds, const GemmP g, const Sched& S, const Epi& E, int tid) {
;     ...
;             PG8_LDA(At, 0, 1); PG8_STAGE(PG8_SB(0, 0), b2, voffB); PG8_STAGE(PG8_SB(0, 1), b2 + hstepB, voffB); PG8_STAGE(PG8_SA(0, 0), a2, voffA);
;             PG8_WAIT_V(8); PG8_WAIT_L(0); PG8_BAR; PG8_MMA(1, 0, At, B0); PG8_MMA(1, 1, At, B1); PG8_BAR; PG8_SCHED;
;             PG8_LDB(B0, 1, 0); PG8_LDB(B1, 1, 1); PG8_SCHED; PG8_LDA(At, 1, 0); PG8_STAGE(PG8_SA(0, 1), a2 + hstepA, voffA);
;             PG8_WAIT_V(8); PG8_WAIT_L(0); PG8_BAR; PG8_MMA(0, 0, At, B0); PG8_MMA(0, 1, At, B1); PG8_BAR; PG8_SCHED;
	s_add_i32 s65, s56, s48
	v_lshl_add_u64 v[208:209], s[38:39], 0, v[132:133]
	s_mov_b32 m0, s65
	ds_read_b128 v[176:179], v143 offset:16384
	ds_read_b128 v[180:183], v143 offset:17408
	ds_read_b128 v[184:187], v143 offset:18432
	ds_read_b128 v[188:191], v143 offset:19456
	ds_read_b128 v[192:195], v143 offset:20480
	ds_read_b128 v[196:199], v143 offset:21504
	ds_read_b128 v[200:203], v143 offset:22528
	ds_read_b128 v[204:207], v143 offset:23552
	global_load_lds_dwordx4 v[208:209], off
	s_add_i32 m0, s65, 0x2000
	s_add_u32 s66, s38, 0x40000
	v_lshl_add_u64 v[210:211], s[38:39], 0, v[128:129]
	s_addc_u32 s67, s39, 0
	s_add_i32 s65, s57, s48
	global_load_lds_dwordx4 v[210:211], off
	v_lshl_add_u64 v[212:213], s[66:67], 0, v[132:133]
	s_mov_b32 m0, s65
	v_lshl_add_u64 v[214:215], s[40:41], 0, v[130:131]
	global_load_lds_dwordx4 v[212:213], off
	v_lshl_add_u64 v[212:213], s[66:67], 0, v[128:129]
	s_add_i32 m0, s65, 0x2000
	s_nop 0
	global_load_lds_dwordx4 v[212:213], off
	v_lshl_add_u64 v[212:213], s[40:41], 0, v[134:135]
	s_mov_b32 m0, s49
	s_nop 0
	global_load_lds_dwordx4 v[212:213], off
	s_mov_b32 m0, s50
	s_nop 0
	global_load_lds_dwordx4 v[214:215], off
	s_waitcnt vmcnt(8)
	s_waitcnt lgkmcnt(0)
	s_barrier
	s_waitcnt lgkmcnt(0)
	v_mfma_f32_16x16x32_bf16 v[60:63], v[144:147], v[176:179], v[60:63]
	v_mfma_f32_16x16x32_bf16 v[56:59], v[152:155], v[176:179], v[56:59]
	v_mfma_f32_16x16x32_bf16 v[52:55], v[144:147], v[184:187], v[52:55]
	v_mfma_f32_16x16x32_bf16 v[48:51], v[152:155], v[184:187], v[48:51]
	v_mfma_f32_16x16x32_bf16 v[36:39], v[144:147], v[192:195], v[36:39]
	v_mfma_f32_16x16x32_bf16 v[32:35], v[152:155], v[192:195], v[32:35]
	v_mfma_f32_16x16x32_bf16 v[20:23], v[144:147], v[200:203], v[20:23]
	v_mfma_f32_16x16x32_bf16 v[16:19], v[152:155], v[200:203], v[16:19]
	v_mfma_f32_16x16x32_bf16 v[60:63], v[148:151], v[180:183], v[60:63]
	v_mfma_f32_16x16x32_bf16 v[56:59], v[156:159], v[180:183], v[56:59]
	v_mfma_f32_16x16x32_bf16 v[52:55], v[148:151], v[188:191], v[52:55]
	v_mfma_f32_16x16x32_bf16 v[48:51], v[156:159], v[188:191], v[48:51]
	v_mfma_f32_16x16x32_bf16 v[36:39], v[148:151], v[196:199], v[36:39]
	v_mfma_f32_16x16x32_bf16 v[32:35], v[156:159], v[196:199], v[32:35]
	v_mfma_f32_16x16x32_bf16 v[20:23], v[148:151], v[204:207], v[20:23]
	v_mfma_f32_16x16x32_bf16 v[16:19], v[156:159], v[204:207], v[16:19]
	v_mfma_f32_16x16x32_bf16 v[44:47], v[160:163], v[176:179], v[44:47]
	v_mfma_f32_16x16x32_bf16 v[40:43], v[168:171], v[176:179], v[40:43]
	v_mfma_f32_16x16x32_bf16 v[28:31], v[160:163], v[184:187], v[28:31]
	v_mfma_f32_16x16x32_bf16 v[24:27], v[168:171], v[184:187], v[24:27]
	v_mfma_f32_16x16x32_bf16 v[12:15], v[160:163], v[192:195], v[12:15]
	v_mfma_f32_16x16x32_bf16 v[8:11], v[168:171], v[192:195], v[8:11]
	v_mfma_f32_16x16x32_bf16 v[4:7], v[160:163], v[200:203], v[4:7]
	v_mfma_f32_16x16x32_bf16 v[0:3], v[168:171], v[200:203], v[0:3]
	v_mfma_f32_16x16x32_bf16 v[44:47], v[164:167], v[180:183], v[44:47]
	v_mfma_f32_16x16x32_bf16 v[40:43], v[172:175], v[180:183], v[40:43]
	v_mfma_f32_16x16x32_bf16 v[28:31], v[164:167], v[188:191], v[28:31]
	v_mfma_f32_16x16x32_bf16 v[24:27], v[172:175], v[188:191], v[24:27]
	v_mfma_f32_16x16x32_bf16 v[12:15], v[164:167], v[196:199], v[12:15]
	v_mfma_f32_16x16x32_bf16 v[8:11], v[172:175], v[196:199], v[8:11]
	v_mfma_f32_16x16x32_bf16 v[4:7], v[164:167], v[204:207], v[4:7]
	v_mfma_f32_16x16x32_bf16 v[0:3], v[172:175], v[204:207], v[0:3]
	s_barrier
	s_add_i32 s65, 0, 0x18000
	s_add_i32 s66, 0, 0x1c000
	v_add_u32_e32 v156, s65, v140
	v_add_u32_e32 v172, s66, v140
	ds_read_b128 v[144:147], v156
	ds_read_b128 v[148:151], v156 offset:1024
	ds_read_b128 v[152:155], v156 offset:2048
	ds_read_b128 v[156:159], v156 offset:3072
	ds_read_b128 v[160:163], v172
	ds_read_b128 v[164:167], v172 offset:1024
	ds_read_b128 v[168:171], v172 offset:2048
	ds_read_b128 v[172:175], v172 offset:3072
	s_add_u32 s40, s40, 0x40000
	s_addc_u32 s41, s41, 0
	s_mov_b32 m0, s51
	v_lshl_add_u64 v[216:217], s[40:41], 0, v[134:135]
	ds_read_b128 v[176:179], v143 offset:32768
	ds_read_b128 v[180:183], v143 offset:33792
	ds_read_b128 v[184:187], v143 offset:34816
	ds_read_b128 v[188:191], v143 offset:35840
	ds_read_b128 v[192:195], v143 offset:36864
	ds_read_b128 v[196:199], v143 offset:37888
	ds_read_b128 v[200:203], v143 offset:38912
	ds_read_b128 v[204:207], v143 offset:39936
	global_load_lds_dwordx4 v[216:217], off
	v_lshl_add_u64 v[216:217], s[40:41], 0, v[130:131]
	s_mov_b32 m0, s52
	s_nop 0
	global_load_lds_dwordx4 v[216:217], off
	s_waitcnt vmcnt(8)
	s_waitcnt lgkmcnt(0)
	s_barrier
; #define PG8_STAGE(bufoff, gbase, voff) do { _Pragma("unroll") for (int _i = 0; _i < 2; ++_i) \
;         __builtin_amdgcn_global_load_lds((const unsigned*)((const char*)(gbase) + (voff)[_i]), (LAS unsigned*)(lds + (bufoff) + ldsw + _i * 8192), 16, 0, 0); } while (0)
; #define PG8_LDA(dst, b, h) do { _Pragma("unroll") for (int m = 0; m < 4; ++m) _Pragma("unroll") for (int k = 0; k < 2; ++k) dst[m][k] = *(const LAS bf16x8*)(lds + PG8_SA(b, h) + aoff + m * 2048 + k * 1024); } while (0)
; #define PG8_MMA(ai, bj, At, Bt) do { __builtin_amdgcn_s_setprio(1); _Pragma("unroll") for (int m = 0; m < 4; ++m) _Pragma("unroll") for (int n = 0; n < 2; ++n) _Pragma("unroll") for (int k = 0; k < 2; ++k) \
;         acc[ai][bj][m][n] = __builtin_amdgcn_mfma_f32_16x16x32_bf16(Bt[n][k], At[m][k], acc[ai][bj][m][n], 0, 0, 0); __builtin_amdgcn_s_setprio(0); } while (0)
; #define PG8_WAIT_V(n) asm volatile("s_waitcnt vmcnt(" #n ")" ::: "memory")
; #define PG8_WAIT_L(n) asm volatile("s_waitcnt lgkmcnt(" #n ")" ::: "memory")
; #define PG8_BAR __builtin_amdgcn_s_barrier()
; #define PG8_SCHED __builtin_amdgcn_sched_barrier(0)
; template <class Epi, class Sched>
; __device__ __forceinline__ void gemm_phase(LAS unsigned char* lds, const GemmP g, const Sched& S, const Epi& E, int tid) {
;     ...
;             PG8_WAIT_V(8); PG8_WAIT_L(0); PG8_BAR; PG8_MMA(0, 0, At, B0); PG8_MMA(0, 1, At, B1); PG8_BAR; PG8_SCHED;
;             PG8_LDA(At, 1, 1); PG8_STAGE(PG8_SB(1, 0), b3, voffB); PG8_STAGE(PG8_SB(1, 1), b3 + hstepB, voffB); PG8_STAGE(PG8_SA(1, 0), a3, voffA);
;             PG8_WAIT_V(8); PG8_WAIT_L(0); PG8_BAR; PG8_MMA(1, 0, At, B0); PG8_MMA(1, 1, At, B1); PG8_BAR; PG8_SCHED;
;         }
	s_waitcnt lgkmcnt(0)
	v_mfma_f32_16x16x32_bf16 v[124:127], v[144:147], v[176:179], v[124:127]
	v_mfma_f32_16x16x32_bf16 v[120:123], v[152:155], v[176:179], v[120:123]
	v_mfma_f32_16x16x32_bf16 v[116:119], v[144:147], v[184:187], v[116:119]
	v_mfma_f32_16x16x32_bf16 v[112:115], v[152:155], v[184:187], v[112:115]
	v_mfma_f32_16x16x32_bf16 v[100:103], v[144:147], v[192:195], v[100:103]
	v_mfma_f32_16x16x32_bf16 v[96:99], v[152:155], v[192:195], v[96:99]
	v_mfma_f32_16x16x32_bf16 v[84:87], v[144:147], v[200:203], v[84:87]
	v_mfma_f32_16x16x32_bf16 v[80:83], v[152:155], v[200:203], v[80:83]
	v_mfma_f32_16x16x32_bf16 v[124:127], v[148:151], v[180:183], v[124:127]
	v_mfma_f32_16x16x32_bf16 v[120:123], v[156:159], v[180:183], v[120:123]
	v_mfma_f32_16x16x32_bf16 v[116:119], v[148:151], v[188:191], v[116:119]
	v_mfma_f32_16x16x32_bf16 v[112:115], v[156:159], v[188:191], v[112:115]
	v_mfma_f32_16x16x32_bf16 v[100:103], v[148:151], v[196:199], v[100:103]
	v_mfma_f32_16x16x32_bf16 v[96:99], v[156:159], v[196:199], v[96:99]
	v_mfma_f32_16x16x32_bf16 v[84:87], v[148:151], v[204:207], v[84:87]
	v_mfma_f32_16x16x32_bf16 v[80:83], v[156:159], v[204:207], v[80:83]
	v_mfma_f32_16x16x32_bf16 v[108:111], v[160:163], v[176:179], v[108:111]
	v_mfma_f32_16x16x32_bf16 v[104:107], v[168:171], v[176:179], v[104:107]
	v_mfma_f32_16x16x32_bf16 v[92:95], v[160:163], v[184:187], v[92:95]
	v_mfma_f32_16x16x32_bf16 v[88:91], v[168:171], v[184:187], v[88:91]
	v_mfma_f32_16x16x32_bf16 v[76:79], v[160:163], v[192:195], v[76:79]
	v_mfma_f32_16x16x32_bf16 v[72:75], v[168:171], v[192:195], v[72:75]
	v_mfma_f32_16x16x32_bf16 v[68:71], v[160:163], v[200:203], v[68:71]
	v_mfma_f32_16x16x32_bf16 v[64:67], v[168:171], v[200:203], v[64:67]
	v_mfma_f32_16x16x32_bf16 v[108:111], v[164:167], v[180:183], v[108:111]
	v_mfma_f32_16x16x32_bf16 v[104:107], v[172:175], v[180:183], v[104:107]
	v_mfma_f32_16x16x32_bf16 v[92:95], v[164:167], v[188:191], v[92:95]
	v_mfma_f32_16x16x32_bf16 v[88:91], v[172:175], v[188:191], v[88:91]
	v_mfma_f32_16x16x32_bf16 v[76:79], v[164:167], v[196:199], v[76:79]
	v_mfma_f32_16x16x32_bf16 v[72:75], v[172:175], v[196:199], v[72:75]
	v_mfma_f32_16x16x32_bf16 v[68:71], v[164:167], v[204:207], v[68:71]
	v_mfma_f32_16x16x32_bf16 v[64:67], v[172:175], v[204:207], v[64:67]
	s_barrier
	s_add_i32 s40, s65, s48
	v_lshl_add_u64 v[208:209], v[208:209], 0, s[10:11]
	s_mov_b32 m0, s40
	ds_read_b128 v[176:179], v143 offset:49152
	ds_read_b128 v[180:183], v143 offset:50176
	ds_read_b128 v[184:187], v143 offset:51200
	ds_read_b128 v[188:191], v143 offset:52224
	ds_read_b128 v[192:195], v143 offset:53248
	ds_read_b128 v[196:199], v143 offset:54272
	ds_read_b128 v[200:203], v143 offset:55296
	ds_read_b128 v[204:207], v143 offset:56320
	global_load_lds_dwordx4 v[208:209], off
	s_add_i32 m0, s40, 0x2000
	s_add_u32 s38, s38, 0x40080
	v_lshl_add_u64 v[208:209], v[210:211], 0, s[10:11]
	s_addc_u32 s39, s39, 0
	s_add_i32 s40, s66, s48
	global_load_lds_dwordx4 v[208:209], off
	v_lshl_add_u64 v[208:209], s[38:39], 0, v[132:133]
	s_mov_b32 m0, s40
	s_nop 0
	global_load_lds_dwordx4 v[208:209], off
	v_lshl_add_u64 v[208:209], s[38:39], 0, v[128:129]
	s_add_i32 m0, s40, 0x2000
	s_nop 0
	global_load_lds_dwordx4 v[208:209], off
	v_lshl_add_u64 v[208:209], v[212:213], 0, s[10:11]
	s_mov_b32 m0, s54
	s_nop 0
	global_load_lds_dwordx4 v[208:209], off
	v_lshl_add_u64 v[208:209], v[214:215], 0, s[10:11]
	s_mov_b32 m0, s55
	s_nop 0
	global_load_lds_dwordx4 v[208:209], off
	s_waitcnt vmcnt(8)
	s_waitcnt lgkmcnt(0)
	s_barrier
	s_waitcnt lgkmcnt(0)
	v_mfma_f32_16x16x32_bf16 v[60:63], v[144:147], v[176:179], v[60:63]
	v_mfma_f32_16x16x32_bf16 v[56:59], v[152:155], v[176:179], v[56:59]
	v_mfma_f32_16x16x32_bf16 v[52:55], v[144:147], v[184:187], v[52:55]
	v_mfma_f32_16x16x32_bf16 v[48:51], v[152:155], v[184:187], v[48:51]
	v_mfma_f32_16x16x32_bf16 v[36:39], v[144:147], v[192:195], v[36:39]
	v_mfma_f32_16x16x32_bf16 v[32:35], v[152:155], v[192:195], v[32:35]
	v_mfma_f32_16x16x32_bf16 v[20:23], v[144:147], v[200:203], v[20:23]
	v_mfma_f32_16x16x32_bf16 v[16:19], v[152:155], v[200:203], v[16:19]
	v_mfma_f32_16x16x32_bf16 v[60:63], v[148:151], v[180:183], v[60:63]
	v_mfma_f32_16x16x32_bf16 v[56:59], v[156:159], v[180:183], v[56:59]
	v_mfma_f32_16x16x32_bf16 v[52:55], v[148:151], v[188:191], v[52:55]
	v_mfma_f32_16x16x32_bf16 v[48:51], v[156:159], v[188:191], v[48:51]
	v_mfma_f32_16x16x32_bf16 v[36:39], v[148:151], v[196:199], v[36:39]
	v_mfma_f32_16x16x32_bf16 v[32:35], v[156:159], v[196:199], v[32:35]
	v_mfma_f32_16x16x32_bf16 v[20:23], v[148:151], v[204:207], v[20:23]
	v_mfma_f32_16x16x32_bf16 v[16:19], v[156:159], v[204:207], v[16:19]
	v_mfma_f32_16x16x32_bf16 v[44:47], v[160:163], v[176:179], v[44:47]
	v_mfma_f32_16x16x32_bf16 v[40:43], v[168:171], v[176:179], v[40:43]
	v_mfma_f32_16x16x32_bf16 v[28:31], v[160:163], v[184:187], v[28:31]
	v_mfma_f32_16x16x32_bf16 v[24:27], v[168:171], v[184:187], v[24:27]
	v_mfma_f32_16x16x32_bf16 v[12:15], v[160:163], v[192:195], v[12:15]
	v_mfma_f32_16x16x32_bf16 v[8:11], v[168:171], v[192:195], v[8:11]
	v_mfma_f32_16x16x32_bf16 v[4:7], v[160:163], v[200:203], v[4:7]
	v_mfma_f32_16x16x32_bf16 v[0:3], v[168:171], v[200:203], v[0:3]
	v_mfma_f32_16x16x32_bf16 v[44:47], v[164:167], v[180:183], v[44:47]
	v_mfma_f32_16x16x32_bf16 v[40:43], v[172:175], v[180:183], v[40:43]
	v_mfma_f32_16x16x32_bf16 v[28:31], v[164:167], v[188:191], v[28:31]
	v_mfma_f32_16x16x32_bf16 v[24:27], v[172:175], v[188:191], v[24:27]
	v_mfma_f32_16x16x32_bf16 v[12:15], v[164:167], v[196:199], v[12:15]
	v_mfma_f32_16x16x32_bf16 v[8:11], v[172:175], v[196:199], v[8:11]
	v_mfma_f32_16x16x32_bf16 v[4:7], v[164:167], v[204:207], v[4:7]
	v_mfma_f32_16x16x32_bf16 v[0:3], v[172:175], v[204:207], v[0:3]
	s_barrier
	s_add_i32 s64, s64, 2
	s_add_u32 s62, s62, 0x100
	s_addc_u32 s63, s63, 0
	s_add_u32 s36, s36, 0x100
	s_addc_u32 s37, s37, 0
	s_cmp_gt_u32 s64, 13
	s_cbranch_scc0 .LBB0_243
	s_setprio 0
	s_and_b64 vcc, exec, s[12:13]
	s_cbranch_vccz .LBB0_246
	s_barrier

; #define PG8_STAGE(bufoff, gbase, voff) do { _Pragma("unroll") for (int _i = 0; _i < 2; ++_i) \
;         __builtin_amdgcn_global_load_lds((const unsigned*)((const char*)(gbase) + (voff)[_i]), (LAS unsigned*)(lds + (bufoff) + ldsw + _i * 8192), 16, 0, 0); } while (0)
; #define PG8_LDA(dst, b, h) do { _Pragma("unroll") for (int m = 0; m < 4; ++m) _Pragma("unroll") for (int k = 0; k < 2; ++k) dst[m][k] = *(const LAS bf16x8*)(lds + PG8_SA(b, h) + aoff + m * 2048 + k * 1024); } while (0)
; #define PG8_LDB(dst, b, h) do { _Pragma("unroll") for (int n = 0; n < 2; ++n) _Pragma("unroll") for (int k = 0; k < 2; ++k) dst[n][k] = *(const LAS bf16x8*)(lds + PG8_SB(b, h) + boff + n * 2048 + k * 1024); } while (0)
; #define PG8_MMA(ai, bj, At, Bt) do { __builtin_amdgcn_s_setprio(1); _Pragma("unroll") for (int m = 0; m < 4; ++m) _Pragma("unroll") for (int n = 0; n < 2; ++n) _Pragma("unroll") for (int k = 0; k < 2; ++k) \
;         acc[ai][bj][m][n] = __builtin_amdgcn_mfma_f32_16x16x32_bf16(Bt[n][k], At[m][k], acc[ai][bj][m][n], 0, 0, 0); __builtin_amdgcn_s_setprio(0); } while (0)
; #define PG8_WAIT_V(n) asm volatile("s_waitcnt vmcnt(" #n ")" ::: "memory")
; #define PG8_WAIT_L(n) asm volatile("s_waitcnt lgkmcnt(" #n ")" ::: "memory")
; #define PG8_BAR __builtin_amdgcn_s_barrier()
; template <class Epi, class Sched>
; __device__ __forceinline__ void gemm_phase(LAS unsigned char* lds, const GemmP g, const Sched& S, const Epi& E, int tid) {
;     ...
;         for (int t = 0; t < nt; t += 2) {
;             const bool last = (t == nt - 2);
;             const char* a1 = cA + (size_t)(t + 1) * kstep;
;             const char* a2 = last ? nA : cA + (size_t)(t + 2) * kstep; const char* b2 = last ? nB : cB + (size_t)(t + 2) * kstep;
;             const char* a3 = a2 + kstep; const char* b3 = b2 + kstep;
;             PG8_LDB(B0, 0, 0); PG8_LDB(B1, 0, 1); PG8_SCHED; PG8_LDA(At, 0, 0); PG8_STAGE(PG8_SA(1, 1), a1 + hstepA, voffA);
;             PG8_WAIT_V(8); PG8_WAIT_L(0); PG8_BAR; PG8_MMA(0, 0, At, B0); PG8_MMA(0, 1, At, B1); PG8_BAR; PG8_SCHED;
;     ...
; #pragma unroll
;         for (int a = 0; a < 2; ++a)
; #pragma unroll
;             for (int b = 0; b < 2; ++b)
; #pragma unroll
;                 for (int m = 0; m < 4; ++m)
; #pragma unroll
;                     for (int n = 0; n < 2; ++n) acc[a][b][m][n] = (f32x4){0.f, 0.f, 0.f, 0.f};
;         cur = nxt; cA = nA; cB = nB; ++ui;
.LBB0_444:
	s_add_u32 s12, s6, 0x100
	s_addc_u32 s13, s7, 0
	s_add_u32 s4, s4, 0x40080
	v_mov_b32_e32 v0, 0
	s_addc_u32 s5, s5, 0
	s_mov_b32 s14, -2
	s_waitcnt lgkmcnt(0)
	v_mov_b32_e32 v1, v0
	v_mov_b32_e32 v2, v0
	v_mov_b32_e32 v3, v0
	v_mov_b32_e32 v4, v0
	v_mov_b32_e32 v5, v0
	v_mov_b32_e32 v6, v0
	v_mov_b32_e32 v7, v0
	v_mov_b32_e32 v8, v0
	v_mov_b32_e32 v9, v0
	v_mov_b32_e32 v10, v0
	v_mov_b32_e32 v11, v0
	v_mov_b32_e32 v12, v0
	v_mov_b32_e32 v13, v0
	v_mov_b32_e32 v14, v0
	v_mov_b32_e32 v15, v0
	v_mov_b32_e32 v16, v0
	v_mov_b32_e32 v17, v0
	v_mov_b32_e32 v18, v0
	v_mov_b32_e32 v19, v0
	v_mov_b32_e32 v20, v0
	v_mov_b32_e32 v21, v0
	v_mov_b32_e32 v22, v0
	v_mov_b32_e32 v23, v0
	v_mov_b32_e32 v24, v0
	v_mov_b32_e32 v25, v0
	v_mov_b32_e32 v26, v0
	v_mov_b32_e32 v27, v0
	v_mov_b32_e32 v28, v0
	v_mov_b32_e32 v29, v0
	v_mov_b32_e32 v30, v0
	v_mov_b32_e32 v31, v0
	v_mov_b32_e32 v56, v0
	v_mov_b32_e32 v57, v0
	v_mov_b32_e32 v58, v0
	v_mov_b32_e32 v59, v0
	v_mov_b32_e32 v64, v0
	v_mov_b32_e32 v65, v0
	v_mov_b32_e32 v66, v0
	v_mov_b32_e32 v67, v0
	v_mov_b32_e32 v72, v0
	v_mov_b32_e32 v73, v0
	v_mov_b32_e32 v74, v0
	v_mov_b32_e32 v75, v0
	v_mov_b32_e32 v76, v0
	v_mov_b32_e32 v77, v0
	v_mov_b32_e32 v78, v0
	v_mov_b32_e32 v79, v0
	v_mov_b32_e32 v80, v0
	v_mov_b32_e32 v81, v0
	v_mov_b32_e32 v82, v0
	v_mov_b32_e32 v83, v0
	v_mov_b32_e32 v84, v0
	v_mov_b32_e32 v85, v0
	v_mov_b32_e32 v86, v0
	v_mov_b32_e32 v87, v0
	v_mov_b32_e32 v88, v0
	v_mov_b32_e32 v89, v0
	v_mov_b32_e32 v90, v0
	v_mov_b32_e32 v91, v0
	v_mov_b32_e32 v92, v0
	v_mov_b32_e32 v93, v0
	v_mov_b32_e32 v94, v0
	v_mov_b32_e32 v95, v0
	v_mov_b32_e32 v32, v0
	v_mov_b32_e32 v33, v0
	v_mov_b32_e32 v34, v0
	v_mov_b32_e32 v35, v0
	v_mov_b32_e32 v36, v0
	v_mov_b32_e32 v37, v0
	v_mov_b32_e32 v38, v0
	v_mov_b32_e32 v39, v0
	v_mov_b32_e32 v40, v0
	v_mov_b32_e32 v41, v0
	v_mov_b32_e32 v42, v0
	v_mov_b32_e32 v43, v0
	v_mov_b32_e32 v44, v0
	v_mov_b32_e32 v45, v0
	v_mov_b32_e32 v46, v0
	v_mov_b32_e32 v47, v0
	v_mov_b32_e32 v48, v0
	v_mov_b32_e32 v49, v0
	v_mov_b32_e32 v50, v0
	v_mov_b32_e32 v51, v0
	v_mov_b32_e32 v52, v0
	v_mov_b32_e32 v53, v0
	v_mov_b32_e32 v54, v0
	v_mov_b32_e32 v55, v0
	v_mov_b32_e32 v60, v0
	v_mov_b32_e32 v61, v0
	v_mov_b32_e32 v62, v0
	v_mov_b32_e32 v63, v0
	v_mov_b32_e32 v68, v0
	v_mov_b32_e32 v69, v0
	v_mov_b32_e32 v70, v0
	v_mov_b32_e32 v71, v0
	v_mov_b32_e32 v96, v0
	v_mov_b32_e32 v97, v0
	v_mov_b32_e32 v98, v0
	v_mov_b32_e32 v99, v0
	v_mov_b32_e32 v100, v0
	v_mov_b32_e32 v101, v0
	v_mov_b32_e32 v102, v0
	v_mov_b32_e32 v103, v0
	v_mov_b32_e32 v104, v0
	v_mov_b32_e32 v105, v0
	v_mov_b32_e32 v106, v0
	v_mov_b32_e32 v107, v0
	v_mov_b32_e32 v108, v0
	v_mov_b32_e32 v109, v0
	v_mov_b32_e32 v110, v0
	v_mov_b32_e32 v111, v0
	v_mov_b32_e32 v112, v0
	v_mov_b32_e32 v113, v0
	v_mov_b32_e32 v114, v0
	v_mov_b32_e32 v115, v0
	v_mov_b32_e32 v116, v0
	v_mov_b32_e32 v117, v0
	v_mov_b32_e32 v118, v0
	v_mov_b32_e32 v119, v0
	v_mov_b32_e32 v120, v0
	v_mov_b32_e32 v121, v0
	v_mov_b32_e32 v122, v0
	v_mov_b32_e32 v123, v0
	v_mov_b32_e32 v124, v0
	v_mov_b32_e32 v125, v0
	v_mov_b32_e32 v126, v0
	v_mov_b32_e32 v127, v0
	s_cmp_lg_u64 s[48:49], 0
	s_cbranch_scc1 .Lsp_445
	s_setprio 1
.Lsp_445:
.LBB0_445:
	ds_read_b128 v[128:131], v209
	ds_read_b128 v[132:135], v209 offset:1024
	ds_read_b128 v[136:139], v209 offset:2048
	ds_read_b128 v[140:143], v209 offset:3072
	ds_read_b128 v[144:147], v210
	ds_read_b128 v[148:151], v210 offset:1024
	ds_read_b128 v[152:155], v210 offset:2048
	ds_read_b128 v[156:159], v210 offset:3072
	s_add_u32 s6, s4, 0xfffc0080
	s_addc_u32 s7, s5, -1
	s_cmp_eq_u32 s14, 12
	s_cselect_b32 s9, s51, s7
	s_cselect_b32 s8, s50, s6
	s_cselect_b32 s7, s53, s13
	s_cselect_b32 s6, s52, s12
	v_lshl_add_u64 v[212:213], s[4:5], 0, v[198:199]
	s_add_i32 m0, s75, 0xc000
	ds_read_b128 v[160:163], v211
	ds_read_b128 v[164:167], v211 offset:1024
	ds_read_b128 v[168:171], v211 offset:2048
	ds_read_b128 v[172:175], v211 offset:3072
	ds_read_b128 v[176:179], v211 offset:4096
	ds_read_b128 v[180:183], v211 offset:5120
	ds_read_b128 v[184:187], v211 offset:6144
	ds_read_b128 v[204:207], v211 offset:7168
	global_load_lds_dwordx4 v[212:213], off
	v_lshl_add_u64 v[212:213], s[4:5], 0, v[196:197]
	s_add_i32 m0, s75, 0xe000
	s_nop 0
	global_load_lds_dwordx4 v[212:213], off
	s_cmp_eq_u32 s14, -2
	s_cbranch_scc1 .Lfirstit_2
	s_waitcnt vmcnt(8)
; #define PG8_STAGE(bufoff, gbase, voff) do { _Pragma("unroll") for (int _i = 0; _i < 2; ++_i) \
;         __builtin_amdgcn_global_load_lds((const unsigned*)((const char*)(gbase) + (voff)[_i]), (LAS unsigned*)(lds + (bufoff) + ldsw + _i * 8192), 16, 0, 0); } while (0)
; #define PG8_LDA(dst, b, h) do { _Pragma("unroll") for (int m = 0; m < 4; ++m) _Pragma("unroll") for (int k = 0; k < 2; ++k) dst[m][k] = *(const LAS bf16x8*)(lds + PG8_SA(b, h) + aoff + m * 2048 + k * 1024); } while (0)
; #define PG8_MMA(ai, bj, At, Bt) do { __builtin_amdgcn_s_setprio(1); _Pragma("unroll") for (int m = 0; m < 4; ++m) _Pragma("unroll") for (int n = 0; n < 2; ++n) _Pragma("unroll") for (int k = 0; k < 2; ++k) \
;         acc[ai][bj][m][n] = __builtin_amdgcn_mfma_f32_16x16x32_bf16(Bt[n][k], At[m][k], acc[ai][bj][m][n], 0, 0, 0); __builtin_amdgcn_s_setprio(0); } while (0)
; #define PG8_WAIT_V(n) asm volatile("s_waitcnt vmcnt(" #n ")" ::: "memory")
; #define PG8_WAIT_L(n) asm volatile("s_waitcnt lgkmcnt(" #n ")" ::: "memory")
; #define PG8_BAR __builtin_amdgcn_s_barrier()
; #define PG8_SCHED __builtin_amdgcn_sched_barrier(0)
; template <class Epi, class Sched>
; __device__ __forceinline__ void gemm_phase(LAS unsigned char* lds, const GemmP g, const Sched& S, const Epi& E, int tid) {
;     ...
;             PG8_WAIT_V(8); PG8_WAIT_L(0); PG8_BAR; PG8_MMA(0, 0, At, B0); PG8_MMA(0, 1, At, B1); PG8_BAR; PG8_SCHED;
;             PG8_LDA(At, 0, 1); PG8_STAGE(PG8_SB(0, 0), b2, voffB); PG8_STAGE(PG8_SB(0, 1), b2 + hstepB, voffB); PG8_STAGE(PG8_SA(0, 0), a2, voffA);
;             PG8_WAIT_V(8); PG8_WAIT_L(0); PG8_BAR; PG8_MMA(1, 0, At, B0); PG8_MMA(1, 1, At, B1); PG8_BAR; PG8_SCHED;
.Lfirstit_2:
	s_waitcnt lgkmcnt(0)
	s_barrier
	s_waitcnt lgkmcnt(0)
	v_mfma_f32_16x16x32_bf16 v[124:127], v[128:131], v[160:163], v[124:127]
	v_mfma_f32_16x16x32_bf16 v[120:123], v[136:139], v[160:163], v[120:123]
	v_mfma_f32_16x16x32_bf16 v[116:119], v[128:131], v[168:171], v[116:119]
	v_mfma_f32_16x16x32_bf16 v[112:115], v[136:139], v[168:171], v[112:115]
	v_mfma_f32_16x16x32_bf16 v[108:111], v[128:131], v[176:179], v[108:111]
	v_mfma_f32_16x16x32_bf16 v[104:107], v[136:139], v[176:179], v[104:107]
	v_mfma_f32_16x16x32_bf16 v[100:103], v[128:131], v[184:187], v[100:103]
	v_mfma_f32_16x16x32_bf16 v[96:99], v[136:139], v[184:187], v[96:99]
	v_mfma_f32_16x16x32_bf16 v[124:127], v[132:135], v[164:167], v[124:127]
	v_mfma_f32_16x16x32_bf16 v[120:123], v[140:143], v[164:167], v[120:123]
	v_mfma_f32_16x16x32_bf16 v[116:119], v[132:135], v[172:175], v[116:119]
	v_mfma_f32_16x16x32_bf16 v[112:115], v[140:143], v[172:175], v[112:115]
	v_mfma_f32_16x16x32_bf16 v[108:111], v[132:135], v[180:183], v[108:111]
	v_mfma_f32_16x16x32_bf16 v[104:107], v[140:143], v[180:183], v[104:107]
	v_mfma_f32_16x16x32_bf16 v[100:103], v[132:135], v[204:207], v[100:103]
	v_mfma_f32_16x16x32_bf16 v[96:99], v[140:143], v[204:207], v[96:99]
	v_mfma_f32_16x16x32_bf16 v[68:71], v[144:147], v[160:163], v[68:71]
	v_mfma_f32_16x16x32_bf16 v[60:63], v[152:155], v[160:163], v[60:63]
	v_mfma_f32_16x16x32_bf16 v[52:55], v[144:147], v[168:171], v[52:55]
	v_mfma_f32_16x16x32_bf16 v[48:51], v[152:155], v[168:171], v[48:51]
	v_mfma_f32_16x16x32_bf16 v[44:47], v[144:147], v[176:179], v[44:47]
	v_mfma_f32_16x16x32_bf16 v[40:43], v[152:155], v[176:179], v[40:43]
	v_mfma_f32_16x16x32_bf16 v[36:39], v[144:147], v[184:187], v[36:39]
	v_mfma_f32_16x16x32_bf16 v[32:35], v[152:155], v[184:187], v[32:35]
	v_mfma_f32_16x16x32_bf16 v[68:71], v[148:151], v[164:167], v[68:71]
	v_mfma_f32_16x16x32_bf16 v[60:63], v[156:159], v[164:167], v[60:63]
	v_mfma_f32_16x16x32_bf16 v[52:55], v[148:151], v[172:175], v[52:55]
	v_mfma_f32_16x16x32_bf16 v[48:51], v[156:159], v[172:175], v[48:51]
	v_mfma_f32_16x16x32_bf16 v[44:47], v[148:151], v[180:183], v[44:47]
	v_mfma_f32_16x16x32_bf16 v[40:43], v[156:159], v[180:183], v[40:43]
	v_mfma_f32_16x16x32_bf16 v[36:39], v[148:151], v[204:207], v[36:39]
	v_mfma_f32_16x16x32_bf16 v[32:35], v[156:159], v[204:207], v[32:35]
	s_barrier
	s_add_i32 s15, s86, s74
	v_lshl_add_u64 v[212:213], s[6:7], 0, v[190:191]
	s_mov_b32 m0, s15
	ds_read_b128 v[160:163], v211 offset:16384
	ds_read_b128 v[164:167], v211 offset:17408
	ds_read_b128 v[168:171], v211 offset:18432
	ds_read_b128 v[172:175], v211 offset:19456
	ds_read_b128 v[176:179], v211 offset:20480
	ds_read_b128 v[180:183], v211 offset:21504
	ds_read_b128 v[184:187], v211 offset:22528
	ds_read_b128 v[204:207], v211 offset:23552
	global_load_lds_dwordx4 v[212:213], off
	s_add_i32 m0, s15, 0x2000
	s_add_u32 s16, s6, 0x40000
	v_lshl_add_u64 v[214:215], s[6:7], 0, v[194:195]
	s_addc_u32 s17, s7, 0
	s_add_i32 s15, s87, s74
	global_load_lds_dwordx4 v[214:215], off
	v_lshl_add_u64 v[216:217], s[16:17], 0, v[190:191]
	s_mov_b32 m0, s15
	v_lshl_add_u64 v[218:219], s[8:9], 0, v[192:193]
	global_load_lds_dwordx4 v[216:217], off
	v_lshl_add_u64 v[216:217], s[16:17], 0, v[194:195]
	s_add_i32 m0, s15, 0x2000
	s_nop 0
	global_load_lds_dwordx4 v[216:217], off
	v_lshl_add_u64 v[216:217], s[8:9], 0, v[188:189]
	s_mov_b32 m0, s75
	s_nop 0
	global_load_lds_dwordx4 v[216:217], off
	s_mov_b32 m0, s76
	s_nop 0
	global_load_lds_dwordx4 v[218:219], off
	s_waitcnt vmcnt(8)
	s_waitcnt lgkmcnt(0)
	s_barrier
	s_waitcnt lgkmcnt(0)
	v_mfma_f32_16x16x32_bf16 v[92:95], v[128:131], v[160:163], v[92:95]
	v_mfma_f32_16x16x32_bf16 v[88:91], v[136:139], v[160:163], v[88:91]
	v_mfma_f32_16x16x32_bf16 v[84:87], v[128:131], v[168:171], v[84:87]
	v_mfma_f32_16x16x32_bf16 v[80:83], v[136:139], v[168:171], v[80:83]
	v_mfma_f32_16x16x32_bf16 v[76:79], v[128:131], v[176:179], v[76:79]
	v_mfma_f32_16x16x32_bf16 v[72:75], v[136:139], v[176:179], v[72:75]
	v_mfma_f32_16x16x32_bf16 v[64:67], v[128:131], v[184:187], v[64:67]
	v_mfma_f32_16x16x32_bf16 v[56:59], v[136:139], v[184:187], v[56:59]
	v_mfma_f32_16x16x32_bf16 v[92:95], v[132:135], v[164:167], v[92:95]
	v_mfma_f32_16x16x32_bf16 v[88:91], v[140:143], v[164:167], v[88:91]
	v_mfma_f32_16x16x32_bf16 v[84:87], v[132:135], v[172:175], v[84:87]
	v_mfma_f32_16x16x32_bf16 v[80:83], v[140:143], v[172:175], v[80:83]
	v_mfma_f32_16x16x32_bf16 v[76:79], v[132:135], v[180:183], v[76:79]
	v_mfma_f32_16x16x32_bf16 v[72:75], v[140:143], v[180:183], v[72:75]
	v_mfma_f32_16x16x32_bf16 v[64:67], v[132:135], v[204:207], v[64:67]
	v_mfma_f32_16x16x32_bf16 v[56:59], v[140:143], v[204:207], v[56:59]
	v_mfma_f32_16x16x32_bf16 v[28:31], v[144:147], v[160:163], v[28:31]
	v_mfma_f32_16x16x32_bf16 v[24:27], v[152:155], v[160:163], v[24:27]
	v_mfma_f32_16x16x32_bf16 v[20:23], v[144:147], v[168:171], v[20:23]
	v_mfma_f32_16x16x32_bf16 v[16:19], v[152:155], v[168:171], v[16:19]
	v_mfma_f32_16x16x32_bf16 v[12:15], v[144:147], v[176:179], v[12:15]
	v_mfma_f32_16x16x32_bf16 v[8:11], v[152:155], v[176:179], v[8:11]
	v_mfma_f32_16x16x32_bf16 v[4:7], v[144:147], v[184:187], v[4:7]
	v_mfma_f32_16x16x32_bf16 v[0:3], v[152:155], v[184:187], v[0:3]
	v_mfma_f32_16x16x32_bf16 v[28:31], v[148:151], v[164:167], v[28:31]
	v_mfma_f32_16x16x32_bf16 v[24:27], v[156:159], v[164:167], v[24:27]
	v_mfma_f32_16x16x32_bf16 v[20:23], v[148:151], v[172:175], v[20:23]
	v_mfma_f32_16x16x32_bf16 v[16:19], v[156:159], v[172:175], v[16:19]
	v_mfma_f32_16x16x32_bf16 v[12:15], v[148:151], v[180:183], v[12:15]
	v_mfma_f32_16x16x32_bf16 v[8:11], v[156:159], v[180:183], v[8:11]
	v_mfma_f32_16x16x32_bf16 v[4:7], v[148:151], v[204:207], v[4:7]
	v_mfma_f32_16x16x32_bf16 v[0:3], v[156:159], v[204:207], v[0:3]
	s_barrier
; #define PG8_STAGE(bufoff, gbase, voff) do { _Pragma("unroll") for (int _i = 0; _i < 2; ++_i) \
;         __builtin_amdgcn_global_load_lds((const unsigned*)((const char*)(gbase) + (voff)[_i]), (LAS unsigned*)(lds + (bufoff) + ldsw + _i * 8192), 16, 0, 0); } while (0)
; #define PG8_LDA(dst, b, h) do { _Pragma("unroll") for (int m = 0; m < 4; ++m) _Pragma("unroll") for (int k = 0; k < 2; ++k) dst[m][k] = *(const LAS bf16x8*)(lds + PG8_SA(b, h) + aoff + m * 2048 + k * 1024); } while (0)
; #define PG8_LDB(dst, b, h) do { _Pragma("unroll") for (int n = 0; n < 2; ++n) _Pragma("unroll") for (int k = 0; k < 2; ++k) dst[n][k] = *(const LAS bf16x8*)(lds + PG8_SB(b, h) + boff + n * 2048 + k * 1024); } while (0)
; #define PG8_MMA(ai, bj, At, Bt) do { __builtin_amdgcn_s_setprio(1); _Pragma("unroll") for (int m = 0; m < 4; ++m) _Pragma("unroll") for (int n = 0; n < 2; ++n) _Pragma("unroll") for (int k = 0; k < 2; ++k) \
;         acc[ai][bj][m][n] = __builtin_amdgcn_mfma_f32_16x16x32_bf16(Bt[n][k], At[m][k], acc[ai][bj][m][n], 0, 0, 0); __builtin_amdgcn_s_setprio(0); } while (0)
; #define PG8_WAIT_V(n) asm volatile("s_waitcnt vmcnt(" #n ")" ::: "memory")
; #define PG8_WAIT_L(n) asm volatile("s_waitcnt lgkmcnt(" #n ")" ::: "memory")
; #define PG8_BAR __builtin_amdgcn_s_barrier()
; #define PG8_SCHED __builtin_amdgcn_sched_barrier(0)
; template <class Epi, class Sched>
; __device__ __forceinline__ void gemm_phase(LAS unsigned char* lds, const GemmP g, const Sched& S, const Epi& E, int tid) {
;     ...
;             PG8_LDB(B0, 1, 0); PG8_LDB(B1, 1, 1); PG8_SCHED; PG8_LDA(At, 1, 0); PG8_STAGE(PG8_SA(0, 1), a2 + hstepA, voffA);
;             PG8_WAIT_V(8); PG8_WAIT_L(0); PG8_BAR; PG8_MMA(0, 0, At, B0); PG8_MMA(0, 1, At, B1); PG8_BAR; PG8_SCHED;
	s_add_i32 s15, 0, 0x18000
	s_add_i32 s16, 0, 0x1c000
	v_add_u32_e32 v140, s15, v208
	v_add_u32_e32 v156, s16, v208
	ds_read_b128 v[128:131], v140
	ds_read_b128 v[132:135], v140 offset:1024
	ds_read_b128 v[136:139], v140 offset:2048
	ds_read_b128 v[140:143], v140 offset:3072
	ds_read_b128 v[144:147], v156
	ds_read_b128 v[148:151], v156 offset:1024
	ds_read_b128 v[152:155], v156 offset:2048
	ds_read_b128 v[156:159], v156 offset:3072
	s_add_u32 s8, s8, 0x40000
	s_addc_u32 s9, s9, 0
	s_mov_b32 m0, s77
	v_lshl_add_u64 v[220:221], s[8:9], 0, v[188:189]
	ds_read_b128 v[160:163], v211 offset:32768
	ds_read_b128 v[164:167], v211 offset:33792
	ds_read_b128 v[168:171], v211 offset:34816
	ds_read_b128 v[172:175], v211 offset:35840
	ds_read_b128 v[176:179], v211 offset:36864
	ds_read_b128 v[180:183], v211 offset:37888
	ds_read_b128 v[184:187], v211 offset:38912
	ds_read_b128 v[204:207], v211 offset:39936
	global_load_lds_dwordx4 v[220:221], off
	v_lshl_add_u64 v[220:221], s[8:9], 0, v[192:193]
	s_mov_b32 m0, s78
	s_nop 0
	global_load_lds_dwordx4 v[220:221], off
	s_waitcnt vmcnt(8)
	s_waitcnt lgkmcnt(0)
	s_barrier
	s_waitcnt lgkmcnt(0)
	v_mfma_f32_16x16x32_bf16 v[124:127], v[128:131], v[160:163], v[124:127]
	v_mfma_f32_16x16x32_bf16 v[120:123], v[136:139], v[160:163], v[120:123]
	v_mfma_f32_16x16x32_bf16 v[116:119], v[128:131], v[168:171], v[116:119]
	v_mfma_f32_16x16x32_bf16 v[112:115], v[136:139], v[168:171], v[112:115]
	v_mfma_f32_16x16x32_bf16 v[108:111], v[128:131], v[176:179], v[108:111]
	v_mfma_f32_16x16x32_bf16 v[104:107], v[136:139], v[176:179], v[104:107]
	v_mfma_f32_16x16x32_bf16 v[100:103], v[128:131], v[184:187], v[100:103]
	v_mfma_f32_16x16x32_bf16 v[96:99], v[136:139], v[184:187], v[96:99]
	v_mfma_f32_16x16x32_bf16 v[124:127], v[132:135], v[164:167], v[124:127]
	v_mfma_f32_16x16x32_bf16 v[120:123], v[140:143], v[164:167], v[120:123]
	v_mfma_f32_16x16x32_bf16 v[116:119], v[132:135], v[172:175], v[116:119]
	v_mfma_f32_16x16x32_bf16 v[112:115], v[140:143], v[172:175], v[112:115]
	v_mfma_f32_16x16x32_bf16 v[108:111], v[132:135], v[180:183], v[108:111]
	v_mfma_f32_16x16x32_bf16 v[104:107], v[140:143], v[180:183], v[104:107]
	v_mfma_f32_16x16x32_bf16 v[100:103], v[132:135], v[204:207], v[100:103]
	v_mfma_f32_16x16x32_bf16 v[96:99], v[140:143], v[204:207], v[96:99]
	v_mfma_f32_16x16x32_bf16 v[68:71], v[144:147], v[160:163], v[68:71]
	v_mfma_f32_16x16x32_bf16 v[60:63], v[152:155], v[160:163], v[60:63]
	v_mfma_f32_16x16x32_bf16 v[52:55], v[144:147], v[168:171], v[52:55]
	v_mfma_f32_16x16x32_bf16 v[48:51], v[152:155], v[168:171], v[48:51]
	v_mfma_f32_16x16x32_bf16 v[44:47], v[144:147], v[176:179], v[44:47]
	v_mfma_f32_16x16x32_bf16 v[40:43], v[152:155], v[176:179], v[40:43]
	v_mfma_f32_16x16x32_bf16 v[36:39], v[144:147], v[184:187], v[36:39]
	v_mfma_f32_16x16x32_bf16 v[32:35], v[152:155], v[184:187], v[32:35]
	v_mfma_f32_16x16x32_bf16 v[68:71], v[148:151], v[164:167], v[68:71]
	v_mfma_f32_16x16x32_bf16 v[60:63], v[156:159], v[164:167], v[60:63]
	v_mfma_f32_16x16x32_bf16 v[52:55], v[148:151], v[172:175], v[52:55]
	v_mfma_f32_16x16x32_bf16 v[48:51], v[156:159], v[172:175], v[48:51]
	v_mfma_f32_16x16x32_bf16 v[44:47], v[148:151], v[180:183], v[44:47]
	v_mfma_f32_16x16x32_bf16 v[40:43], v[156:159], v[180:183], v[40:43]
	v_mfma_f32_16x16x32_bf16 v[36:39], v[148:151], v[204:207], v[36:39]
	v_mfma_f32_16x16x32_bf16 v[32:35], v[156:159], v[204:207], v[32:35]
	s_barrier
; #define PG8_STAGE(bufoff, gbase, voff) do { _Pragma("unroll") for (int _i = 0; _i < 2; ++_i) \
;         __builtin_amdgcn_global_load_lds((const unsigned*)((const char*)(gbase) + (voff)[_i]), (LAS unsigned*)(lds + (bufoff) + ldsw + _i * 8192), 16, 0, 0); } while (0)
; #define PG8_LDA(dst, b, h) do { _Pragma("unroll") for (int m = 0; m < 4; ++m) _Pragma("unroll") for (int k = 0; k < 2; ++k) dst[m][k] = *(const LAS bf16x8*)(lds + PG8_SA(b, h) + aoff + m * 2048 + k * 1024); } while (0)
; #define PG8_MMA(ai, bj, At, Bt) do { __builtin_amdgcn_s_setprio(1); _Pragma("unroll") for (int m = 0; m < 4; ++m) _Pragma("unroll") for (int n = 0; n < 2; ++n) _Pragma("unroll") for (int k = 0; k < 2; ++k) \
;         acc[ai][bj][m][n] = __builtin_amdgcn_mfma_f32_16x16x32_bf16(Bt[n][k], At[m][k], acc[ai][bj][m][n], 0, 0, 0); __builtin_amdgcn_s_setprio(0); } while (0)
; #define PG8_WAIT_V(n) asm volatile("s_waitcnt vmcnt(" #n ")" ::: "memory")
; #define PG8_WAIT_L(n) asm volatile("s_waitcnt lgkmcnt(" #n ")" ::: "memory")
; #define PG8_BAR __builtin_amdgcn_s_barrier()
; #define PG8_SCHED __builtin_amdgcn_sched_barrier(0)
; template <class Epi, class Sched>
; __device__ __forceinline__ void gemm_phase(LAS unsigned char* lds, const GemmP g, const Sched& S, const Epi& E, int tid) {
;     ...
;             PG8_LDA(At, 1, 1); PG8_STAGE(PG8_SB(1, 0), b3, voffB); PG8_STAGE(PG8_SB(1, 1), b3 + hstepB, voffB); PG8_STAGE(PG8_SA(1, 0), a3, voffA);
;             PG8_WAIT_V(8); PG8_WAIT_L(0); PG8_BAR; PG8_MMA(1, 0, At, B0); PG8_MMA(1, 1, At, B1); PG8_BAR; PG8_SCHED;
;         }
	s_add_i32 s8, s15, s74
	v_lshl_add_u64 v[212:213], v[212:213], 0, s[46:47]
	s_mov_b32 m0, s8
	ds_read_b128 v[160:163], v211 offset:49152
	ds_read_b128 v[164:167], v211 offset:50176
	ds_read_b128 v[168:171], v211 offset:51200
	ds_read_b128 v[172:175], v211 offset:52224
	ds_read_b128 v[176:179], v211 offset:53248
	ds_read_b128 v[180:183], v211 offset:54272
	ds_read_b128 v[184:187], v211 offset:55296
	ds_read_b128 v[204:207], v211 offset:56320
	global_load_lds_dwordx4 v[212:213], off
	s_add_i32 m0, s8, 0x2000
	s_add_u32 s6, s6, 0x40080
	v_lshl_add_u64 v[212:213], v[214:215], 0, s[46:47]
	s_addc_u32 s7, s7, 0
	s_add_i32 s8, s16, s74
	global_load_lds_dwordx4 v[212:213], off
	v_lshl_add_u64 v[212:213], s[6:7], 0, v[190:191]
	s_mov_b32 m0, s8
	s_nop 0
	global_load_lds_dwordx4 v[212:213], off
	v_lshl_add_u64 v[212:213], s[6:7], 0, v[194:195]
	s_add_i32 m0, s8, 0x2000
	s_nop 0
	global_load_lds_dwordx4 v[212:213], off
	v_lshl_add_u64 v[212:213], v[216:217], 0, s[46:47]
	s_mov_b32 m0, s82
	s_nop 0
	global_load_lds_dwordx4 v[212:213], off
	v_lshl_add_u64 v[212:213], v[218:219], 0, s[46:47]
	s_mov_b32 m0, s83
	s_nop 0
	global_load_lds_dwordx4 v[212:213], off
	s_waitcnt vmcnt(8)
	s_waitcnt lgkmcnt(0)
	s_barrier
	s_waitcnt lgkmcnt(0)
	v_mfma_f32_16x16x32_bf16 v[92:95], v[128:131], v[160:163], v[92:95]
	v_mfma_f32_16x16x32_bf16 v[88:91], v[136:139], v[160:163], v[88:91]
	v_mfma_f32_16x16x32_bf16 v[84:87], v[128:131], v[168:171], v[84:87]
	v_mfma_f32_16x16x32_bf16 v[80:83], v[136:139], v[168:171], v[80:83]
	v_mfma_f32_16x16x32_bf16 v[76:79], v[128:131], v[176:179], v[76:79]
	v_mfma_f32_16x16x32_bf16 v[72:75], v[136:139], v[176:179], v[72:75]
	v_mfma_f32_16x16x32_bf16 v[64:67], v[128:131], v[184:187], v[64:67]
	v_mfma_f32_16x16x32_bf16 v[56:59], v[136:139], v[184:187], v[56:59]
	v_mfma_f32_16x16x32_bf16 v[92:95], v[132:135], v[164:167], v[92:95]
	v_mfma_f32_16x16x32_bf16 v[88:91], v[140:143], v[164:167], v[88:91]
	v_mfma_f32_16x16x32_bf16 v[84:87], v[132:135], v[172:175], v[84:87]
	v_mfma_f32_16x16x32_bf16 v[80:83], v[140:143], v[172:175], v[80:83]
	v_mfma_f32_16x16x32_bf16 v[76:79], v[132:135], v[180:183], v[76:79]
	v_mfma_f32_16x16x32_bf16 v[72:75], v[140:143], v[180:183], v[72:75]
	v_mfma_f32_16x16x32_bf16 v[64:67], v[132:135], v[204:207], v[64:67]
	v_mfma_f32_16x16x32_bf16 v[56:59], v[140:143], v[204:207], v[56:59]
	v_mfma_f32_16x16x32_bf16 v[28:31], v[144:147], v[160:163], v[28:31]
	v_mfma_f32_16x16x32_bf16 v[24:27], v[152:155], v[160:163], v[24:27]
	v_mfma_f32_16x16x32_bf16 v[20:23], v[144:147], v[168:171], v[20:23]
	v_mfma_f32_16x16x32_bf16 v[16:19], v[152:155], v[168:171], v[16:19]
	v_mfma_f32_16x16x32_bf16 v[12:15], v[144:147], v[176:179], v[12:15]
	v_mfma_f32_16x16x32_bf16 v[8:11], v[152:155], v[176:179], v[8:11]
	v_mfma_f32_16x16x32_bf16 v[4:7], v[144:147], v[184:187], v[4:7]
	v_mfma_f32_16x16x32_bf16 v[0:3], v[152:155], v[184:187], v[0:3]
	v_mfma_f32_16x16x32_bf16 v[28:31], v[148:151], v[164:167], v[28:31]
	v_mfma_f32_16x16x32_bf16 v[24:27], v[156:159], v[164:167], v[24:27]
	v_mfma_f32_16x16x32_bf16 v[20:23], v[148:151], v[172:175], v[20:23]
	v_mfma_f32_16x16x32_bf16 v[16:19], v[156:159], v[172:175], v[16:19]
	v_mfma_f32_16x16x32_bf16 v[12:15], v[148:151], v[180:183], v[12:15]
	v_mfma_f32_16x16x32_bf16 v[8:11], v[156:159], v[180:183], v[8:11]
	v_mfma_f32_16x16x32_bf16 v[4:7], v[148:151], v[204:207], v[4:7]
	v_mfma_f32_16x16x32_bf16 v[0:3], v[156:159], v[204:207], v[0:3]
	s_barrier
	s_add_i32 s14, s14, 2
	s_add_u32 s12, s12, 0x100
	s_addc_u32 s13, s13, 0
	s_add_u32 s4, s4, 0x100
	s_addc_u32 s5, s5, 0
	s_cmp_gt_u32 s14, 13
	s_cbranch_scc0 .LBB0_445
	s_setprio 0
	s_and_b64 vcc, exec, s[48:49]
	s_cbranch_vccz .LBB0_448
	s_barrier

; #define PG8_STAGE(bufoff, gbase, voff) do { _Pragma("unroll") for (int _i = 0; _i < 2; ++_i) \
;         __builtin_amdgcn_global_load_lds((const unsigned*)((const char*)(gbase) + (voff)[_i]), (LAS unsigned*)(lds + (bufoff) + ldsw + _i * 8192), 16, 0, 0); } while (0)
; #define PG8_LDA(dst, b, h) do { _Pragma("unroll") for (int m = 0; m < 4; ++m) _Pragma("unroll") for (int k = 0; k < 2; ++k) dst[m][k] = *(const LAS bf16x8*)(lds + PG8_SA(b, h) + aoff + m * 2048 + k * 1024); } while (0)
; #define PG8_LDB(dst, b, h) do { _Pragma("unroll") for (int n = 0; n < 2; ++n) _Pragma("unroll") for (int k = 0; k < 2; ++k) dst[n][k] = *(const LAS bf16x8*)(lds + PG8_SB(b, h) + boff + n * 2048 + k * 1024); } while (0)
; #define PG8_SCHED __builtin_amdgcn_sched_barrier(0)
; template <class Epi, class Sched>
; __device__ __forceinline__ void gemm_phase(LAS unsigned char* lds, const GemmP g, const Sched& S, const Epi& E, int tid) {
;     ...
;         for (int t = 0; t < nt; t += 2) {
;             const bool last = (t == nt - 2);
;             const char* a1 = cA + (size_t)(t + 1) * kstep;
;             const char* a2 = last ? nA : cA + (size_t)(t + 2) * kstep; const char* b2 = last ? nB : cB + (size_t)(t + 2) * kstep;
;             const char* a3 = a2 + kstep; const char* b3 = b2 + kstep;
;             PG8_LDB(B0, 0, 0); PG8_LDB(B1, 0, 1); PG8_SCHED; PG8_LDA(At, 0, 0); PG8_STAGE(PG8_SA(1, 1), a1 + hstepA, voffA);
;     ...
; #pragma unroll
;         for (int a = 0; a < 2; ++a)
; #pragma unroll
;             for (int b = 0; b < 2; ++b)
; #pragma unroll
;                 for (int m = 0; m < 4; ++m)
; #pragma unroll
;                     for (int n = 0; n < 2; ++n) acc[a][b][m][n] = (f32x4){0.f, 0.f, 0.f, 0.f};
;         cur = nxt; cA = nA; cB = nB; ++ui;
.LBB0_995:
	s_add_u32 s5, s28, 0x100
	s_addc_u32 s56, s29, 0
	s_add_u32 s26, s26, 0x40080
	v_mov_b32_e32 v0, 0
	s_addc_u32 s27, s27, 0
	s_mov_b32 s57, -2
	v_mov_b32_e32 v1, v0
	v_mov_b32_e32 v2, v0
	v_mov_b32_e32 v3, v0
	v_mov_b32_e32 v4, v0
	v_mov_b32_e32 v5, v0
	v_mov_b32_e32 v6, v0
	v_mov_b32_e32 v7, v0
	v_mov_b32_e32 v16, v0
	v_mov_b32_e32 v17, v0
	v_mov_b32_e32 v18, v0
	v_mov_b32_e32 v19, v0
	v_mov_b32_e32 v20, v0
	v_mov_b32_e32 v21, v0
	v_mov_b32_e32 v22, v0
	v_mov_b32_e32 v23, v0
	v_mov_b32_e32 v32, v0
	v_mov_b32_e32 v33, v0
	v_mov_b32_e32 v34, v0
	v_mov_b32_e32 v35, v0
	v_mov_b32_e32 v36, v0
	v_mov_b32_e32 v37, v0
	v_mov_b32_e32 v38, v0
	v_mov_b32_e32 v39, v0
	v_mov_b32_e32 v48, v0
	v_mov_b32_e32 v49, v0
	v_mov_b32_e32 v50, v0
	v_mov_b32_e32 v51, v0
	v_mov_b32_e32 v52, v0
	v_mov_b32_e32 v53, v0
	v_mov_b32_e32 v54, v0
	v_mov_b32_e32 v55, v0
	v_mov_b32_e32 v8, v0
	v_mov_b32_e32 v9, v0
	v_mov_b32_e32 v10, v0
	v_mov_b32_e32 v11, v0
	v_mov_b32_e32 v12, v0
	v_mov_b32_e32 v13, v0
	v_mov_b32_e32 v14, v0
	v_mov_b32_e32 v15, v0
	v_mov_b32_e32 v24, v0
	v_mov_b32_e32 v25, v0
	v_mov_b32_e32 v26, v0
	v_mov_b32_e32 v27, v0
	v_mov_b32_e32 v28, v0
	v_mov_b32_e32 v29, v0
	v_mov_b32_e32 v30, v0
	v_mov_b32_e32 v31, v0
	v_mov_b32_e32 v40, v0
	v_mov_b32_e32 v41, v0
	v_mov_b32_e32 v42, v0
	v_mov_b32_e32 v43, v0
	v_mov_b32_e32 v44, v0
	v_mov_b32_e32 v45, v0
	v_mov_b32_e32 v46, v0
	v_mov_b32_e32 v47, v0
	v_mov_b32_e32 v56, v0
	v_mov_b32_e32 v57, v0
	v_mov_b32_e32 v58, v0
	v_mov_b32_e32 v59, v0
	v_mov_b32_e32 v60, v0
	v_mov_b32_e32 v61, v0
	v_mov_b32_e32 v62, v0
	v_mov_b32_e32 v63, v0
	v_mov_b32_e32 v64, v0
	v_mov_b32_e32 v65, v0
	v_mov_b32_e32 v66, v0
	v_mov_b32_e32 v67, v0
	v_mov_b32_e32 v68, v0
	v_mov_b32_e32 v69, v0
	v_mov_b32_e32 v70, v0
	v_mov_b32_e32 v71, v0
	v_mov_b32_e32 v80, v0
	v_mov_b32_e32 v81, v0
	v_mov_b32_e32 v82, v0
	v_mov_b32_e32 v83, v0
	v_mov_b32_e32 v84, v0
	v_mov_b32_e32 v85, v0
	v_mov_b32_e32 v86, v0
	v_mov_b32_e32 v87, v0
	v_mov_b32_e32 v96, v0
	v_mov_b32_e32 v97, v0
	v_mov_b32_e32 v98, v0
	v_mov_b32_e32 v99, v0
	v_mov_b32_e32 v100, v0
	v_mov_b32_e32 v101, v0
	v_mov_b32_e32 v102, v0
	v_mov_b32_e32 v103, v0
	v_mov_b32_e32 v112, v0
	v_mov_b32_e32 v113, v0
	v_mov_b32_e32 v114, v0
	v_mov_b32_e32 v115, v0
	v_mov_b32_e32 v116, v0
	v_mov_b32_e32 v117, v0
	v_mov_b32_e32 v118, v0
	v_mov_b32_e32 v119, v0
	v_mov_b32_e32 v72, v0
	v_mov_b32_e32 v73, v0
	v_mov_b32_e32 v74, v0
	v_mov_b32_e32 v75, v0
	v_mov_b32_e32 v76, v0
	v_mov_b32_e32 v77, v0
	v_mov_b32_e32 v78, v0
	v_mov_b32_e32 v79, v0
	v_mov_b32_e32 v88, v0
	v_mov_b32_e32 v89, v0
	v_mov_b32_e32 v90, v0
	v_mov_b32_e32 v91, v0
	v_mov_b32_e32 v92, v0
	v_mov_b32_e32 v93, v0
	v_mov_b32_e32 v94, v0
	v_mov_b32_e32 v95, v0
	v_mov_b32_e32 v104, v0
	v_mov_b32_e32 v105, v0
	v_mov_b32_e32 v106, v0
	v_mov_b32_e32 v107, v0
	v_mov_b32_e32 v108, v0
	v_mov_b32_e32 v109, v0
	v_mov_b32_e32 v110, v0
	v_mov_b32_e32 v111, v0
	v_mov_b32_e32 v120, v0
	v_mov_b32_e32 v121, v0
	v_mov_b32_e32 v122, v0
	v_mov_b32_e32 v123, v0
	v_mov_b32_e32 v124, v0
	v_mov_b32_e32 v125, v0
	v_mov_b32_e32 v126, v0
	v_mov_b32_e32 v127, v0
	s_sub_i32 s32, s44, s4
	s_bfe_u32 s98, s32, 0x10006
	s_bfe_u32 s32, s32, 0x10007
	s_cmp_lg_u64 s[10:11], 0
	s_cselect_b32 s99, 1, 0
	s_xor_b32 s98, s98, s99
	s_or_b32 s99, s98, s32
	s_xor_b32 s32, s32, 1
	s_or_b32 s98, s98, s32
	s_cmp_eq_u32 s43, 0x7fffffff
	s_cselect_b32 s32, 0, s99
	s_cselect_b32 s98, 0, s98
	s_and_b32 s99, s32, s98
	s_cmp_lg_u64 s[16:17], 0
	s_cbranch_scc1 .Lsp_996
	s_setprio 1
.Lsp_996:
.LBB0_996:
	s_add_u32 s28, s26, 0xfffc0080
	s_addc_u32 s29, s27, -1
	s_add_i32 s60, 0, 0x10000
	s_cmp_eq_u32 s57, 12
	s_cselect_b32 s31, s23, s29
	s_cselect_b32 s30, s22, s28
	s_cselect_b32 s29, s25, s56
	s_cselect_b32 s28, s24, s5
	s_add_i32 s62, 0, 0x14000
	v_add_u32_e32 v152, s60, v166
	v_add_u32_e32 v164, s62, v166
	s_cmp_lg_u32 s99, 0
	s_cbranch_scc1 .Lskr_cs_1
	ds_read_b128 v[140:143], v152
	ds_read_b128 v[144:147], v152 offset:1024
	ds_read_b128 v[148:151], v152 offset:2048
	ds_read_b128 v[152:155], v152 offset:3072
	ds_read_b128 v[156:159], v164
	ds_read_b128 v[160:163], v164 offset:1024
	ds_read_b128 v[168:171], v164 offset:2048
	ds_read_b128 v[172:175], v164 offset:3072

; #define PG8_STAGE(bufoff, gbase, voff) do { _Pragma("unroll") for (int _i = 0; _i < 2; ++_i) \
;         __builtin_amdgcn_global_load_lds((const unsigned*)((const char*)(gbase) + (voff)[_i]), (LAS unsigned*)(lds + (bufoff) + ldsw + _i * 8192), 16, 0, 0); } while (0)
; #define PG8_LDA(dst, b, h) do { _Pragma("unroll") for (int m = 0; m < 4; ++m) _Pragma("unroll") for (int k = 0; k < 2; ++k) dst[m][k] = *(const LAS bf16x8*)(lds + PG8_SA(b, h) + aoff + m * 2048 + k * 1024); } while (0)
; #define PG8_LDB(dst, b, h) do { _Pragma("unroll") for (int n = 0; n < 2; ++n) _Pragma("unroll") for (int k = 0; k < 2; ++k) dst[n][k] = *(const LAS bf16x8*)(lds + PG8_SB(b, h) + boff + n * 2048 + k * 1024); } while (0)
; #define PG8_MMA(ai, bj, At, Bt) do { __builtin_amdgcn_s_setprio(1); _Pragma("unroll") for (int m = 0; m < 4; ++m) _Pragma("unroll") for (int n = 0; n < 2; ++n) _Pragma("unroll") for (int k = 0; k < 2; ++k) \
;         acc[ai][bj][m][n] = __builtin_amdgcn_mfma_f32_16x16x32_bf16(Bt[n][k], At[m][k], acc[ai][bj][m][n], 0, 0, 0); __builtin_amdgcn_s_setprio(0); } while (0)
; #define PG8_WAIT_V(n) asm volatile("s_waitcnt vmcnt(" #n ")" ::: "memory")
; #define PG8_WAIT_L(n) asm volatile("s_waitcnt lgkmcnt(" #n ")" ::: "memory")
; #define PG8_BAR __builtin_amdgcn_s_barrier()
; #define PG8_SCHED __builtin_amdgcn_sched_barrier(0)
; template <class Epi, class Sched>
; __device__ __forceinline__ void gemm_phase(LAS unsigned char* lds, const GemmP g, const Sched& S, const Epi& E, int tid) {
;     ...
;             PG8_WAIT_V(8); PG8_WAIT_L(0); PG8_BAR; PG8_MMA(0, 0, At, B0); PG8_MMA(0, 1, At, B1); PG8_BAR; PG8_SCHED;
;             PG8_LDA(At, 0, 1); PG8_STAGE(PG8_SB(0, 0), b2, voffB); PG8_STAGE(PG8_SB(0, 1), b2 + hstepB, voffB); PG8_STAGE(PG8_SA(0, 0), a2, voffA);
;             PG8_WAIT_V(8); PG8_WAIT_L(0); PG8_BAR; PG8_MMA(1, 0, At, B0); PG8_MMA(1, 1, At, B1); PG8_BAR; PG8_SCHED;
;             PG8_LDB(B0, 1, 0); PG8_LDB(B1, 1, 1); PG8_SCHED; PG8_LDA(At, 1, 0); PG8_STAGE(PG8_SA(0, 1), a2 + hstepA, voffA);
.Lfirstit_3:
	s_waitcnt lgkmcnt(0)
	s_barrier
	s_cmp_lg_u32 s32, 0
	s_cbranch_scc1 .Lsk_cs_1
	s_waitcnt lgkmcnt(0)
	v_mfma_f32_16x16x32_bf16 v[124:127], v[140:143], v[176:179], v[124:127]
	v_mfma_f32_16x16x32_bf16 v[120:123], v[148:151], v[176:179], v[120:123]
	v_mfma_f32_16x16x32_bf16 v[108:111], v[140:143], v[184:187], v[108:111]
	v_mfma_f32_16x16x32_bf16 v[104:107], v[148:151], v[184:187], v[104:107]
	v_mfma_f32_16x16x32_bf16 v[92:95], v[140:143], v[192:195], v[92:95]
	v_mfma_f32_16x16x32_bf16 v[88:91], v[148:151], v[192:195], v[88:91]
	v_mfma_f32_16x16x32_bf16 v[76:79], v[140:143], v[210:213], v[76:79]
	v_mfma_f32_16x16x32_bf16 v[72:75], v[148:151], v[210:213], v[72:75]
	v_mfma_f32_16x16x32_bf16 v[124:127], v[144:147], v[180:183], v[124:127]
	v_mfma_f32_16x16x32_bf16 v[120:123], v[152:155], v[180:183], v[120:123]
	v_mfma_f32_16x16x32_bf16 v[108:111], v[144:147], v[188:191], v[108:111]
	v_mfma_f32_16x16x32_bf16 v[104:107], v[152:155], v[188:191], v[104:107]
	v_mfma_f32_16x16x32_bf16 v[92:95], v[144:147], v[206:209], v[92:95]
	v_mfma_f32_16x16x32_bf16 v[88:91], v[152:155], v[206:209], v[88:91]
	v_mfma_f32_16x16x32_bf16 v[76:79], v[144:147], v[214:217], v[76:79]
	v_mfma_f32_16x16x32_bf16 v[72:75], v[152:155], v[214:217], v[72:75]
	v_mfma_f32_16x16x32_bf16 v[116:119], v[156:159], v[176:179], v[116:119]
	v_mfma_f32_16x16x32_bf16 v[112:115], v[168:171], v[176:179], v[112:115]
	v_mfma_f32_16x16x32_bf16 v[100:103], v[156:159], v[184:187], v[100:103]
	v_mfma_f32_16x16x32_bf16 v[96:99], v[168:171], v[184:187], v[96:99]
	v_mfma_f32_16x16x32_bf16 v[84:87], v[156:159], v[192:195], v[84:87]
	v_mfma_f32_16x16x32_bf16 v[80:83], v[168:171], v[192:195], v[80:83]
	v_mfma_f32_16x16x32_bf16 v[68:71], v[156:159], v[210:213], v[68:71]
	v_mfma_f32_16x16x32_bf16 v[64:67], v[168:171], v[210:213], v[64:67]
	v_mfma_f32_16x16x32_bf16 v[116:119], v[160:163], v[180:183], v[116:119]
	v_mfma_f32_16x16x32_bf16 v[112:115], v[172:175], v[180:183], v[112:115]
	v_mfma_f32_16x16x32_bf16 v[100:103], v[160:163], v[188:191], v[100:103]
	v_mfma_f32_16x16x32_bf16 v[96:99], v[172:175], v[188:191], v[96:99]
	v_mfma_f32_16x16x32_bf16 v[84:87], v[160:163], v[206:209], v[84:87]
	v_mfma_f32_16x16x32_bf16 v[80:83], v[172:175], v[206:209], v[80:83]
	v_mfma_f32_16x16x32_bf16 v[68:71], v[160:163], v[214:217], v[68:71]
	v_mfma_f32_16x16x32_bf16 v[64:67], v[172:175], v[214:217], v[64:67]
.Lsk_cs_1:
	s_barrier
	s_add_i32 s60, s60, s41
	v_lshl_add_u64 v[164:165], s[28:29], 0, v[130:131]
	s_mov_b32 m0, s60
	s_cmp_lg_u32 s98, 0
	s_cbranch_scc1 .Lskr_cs_3
	ds_read_b128 v[176:179], v167 offset:16384
	ds_read_b128 v[180:183], v167 offset:17408
	ds_read_b128 v[184:187], v167 offset:18432
	ds_read_b128 v[188:191], v167 offset:19456
	ds_read_b128 v[192:195], v167 offset:20480
	ds_read_b128 v[206:209], v167 offset:21504
	ds_read_b128 v[210:213], v167 offset:22528
	ds_read_b128 v[214:217], v167 offset:23552
.Lskr_cs_3:
	global_load_lds_dwordx4 v[164:165], off
	s_add_i32 m0, s60, 0x2000
	s_add_u32 s60, s28, 0x40000
	v_lshl_add_u64 v[198:199], s[28:29], 0, v[134:135]
	s_addc_u32 s61, s29, 0
	s_add_i32 s62, s62, s41
	global_load_lds_dwordx4 v[198:199], off
	v_lshl_add_u64 v[200:201], s[60:61], 0, v[130:131]
	s_mov_b32 m0, s62
	v_lshl_add_u64 v[220:221], s[30:31], 0, v[132:133]
	global_load_lds_dwordx4 v[200:201], off
	v_lshl_add_u64 v[200:201], s[60:61], 0, v[134:135]
	s_add_i32 m0, s62, 0x2000
	s_nop 0
	global_load_lds_dwordx4 v[200:201], off
	v_lshl_add_u64 v[200:201], s[30:31], 0, v[128:129]
	s_mov_b32 m0, s42
	s_nop 0
	global_load_lds_dwordx4 v[200:201], off
	s_mov_b32 m0, s45
	s_nop 0
	global_load_lds_dwordx4 v[220:221], off
	s_waitcnt vmcnt(8)
	s_waitcnt lgkmcnt(0)
	s_barrier
	s_cmp_lg_u32 s98, 0
	s_cbranch_scc1 .Lsk_cs_2
	s_waitcnt lgkmcnt(0)
	v_mfma_f32_16x16x32_bf16 v[60:63], v[140:143], v[176:179], v[60:63]
	v_mfma_f32_16x16x32_bf16 v[56:59], v[148:151], v[176:179], v[56:59]
	v_mfma_f32_16x16x32_bf16 v[44:47], v[140:143], v[184:187], v[44:47]
	v_mfma_f32_16x16x32_bf16 v[40:43], v[148:151], v[184:187], v[40:43]
	v_mfma_f32_16x16x32_bf16 v[28:31], v[140:143], v[192:195], v[28:31]
	v_mfma_f32_16x16x32_bf16 v[24:27], v[148:151], v[192:195], v[24:27]
	v_mfma_f32_16x16x32_bf16 v[12:15], v[140:143], v[210:213], v[12:15]
	v_mfma_f32_16x16x32_bf16 v[8:11], v[148:151], v[210:213], v[8:11]
	v_mfma_f32_16x16x32_bf16 v[60:63], v[144:147], v[180:183], v[60:63]
	v_mfma_f32_16x16x32_bf16 v[56:59], v[152:155], v[180:183], v[56:59]
	v_mfma_f32_16x16x32_bf16 v[44:47], v[144:147], v[188:191], v[44:47]
	v_mfma_f32_16x16x32_bf16 v[40:43], v[152:155], v[188:191], v[40:43]
	v_mfma_f32_16x16x32_bf16 v[28:31], v[144:147], v[206:209], v[28:31]
	v_mfma_f32_16x16x32_bf16 v[24:27], v[152:155], v[206:209], v[24:27]
	v_mfma_f32_16x16x32_bf16 v[12:15], v[144:147], v[214:217], v[12:15]
	v_mfma_f32_16x16x32_bf16 v[8:11], v[152:155], v[214:217], v[8:11]
	v_mfma_f32_16x16x32_bf16 v[52:55], v[156:159], v[176:179], v[52:55]
	v_mfma_f32_16x16x32_bf16 v[48:51], v[168:171], v[176:179], v[48:51]
	v_mfma_f32_16x16x32_bf16 v[36:39], v[156:159], v[184:187], v[36:39]
	v_mfma_f32_16x16x32_bf16 v[32:35], v[168:171], v[184:187], v[32:35]
	v_mfma_f32_16x16x32_bf16 v[20:23], v[156:159], v[192:195], v[20:23]
	v_mfma_f32_16x16x32_bf16 v[16:19], v[168:171], v[192:195], v[16:19]
	v_mfma_f32_16x16x32_bf16 v[4:7], v[156:159], v[210:213], v[4:7]
	v_mfma_f32_16x16x32_bf16 v[0:3], v[168:171], v[210:213], v[0:3]
	v_mfma_f32_16x16x32_bf16 v[52:55], v[160:163], v[180:183], v[52:55]
	v_mfma_f32_16x16x32_bf16 v[48:51], v[172:175], v[180:183], v[48:51]
	v_mfma_f32_16x16x32_bf16 v[36:39], v[160:163], v[188:191], v[36:39]
	v_mfma_f32_16x16x32_bf16 v[32:35], v[172:175], v[188:191], v[32:35]
	v_mfma_f32_16x16x32_bf16 v[20:23], v[160:163], v[206:209], v[20:23]
	v_mfma_f32_16x16x32_bf16 v[16:19], v[172:175], v[206:209], v[16:19]
	v_mfma_f32_16x16x32_bf16 v[4:7], v[160:163], v[214:217], v[4:7]
	v_mfma_f32_16x16x32_bf16 v[0:3], v[172:175], v[214:217], v[0:3]
.Lsk_cs_2:
	s_barrier
	s_add_i32 s60, 0, 0x18000
	s_add_i32 s61, 0, 0x1c000
	v_add_u32_e32 v152, s60, v166
	v_add_u32_e32 v172, s61, v166
	s_cmp_lg_u32 s99, 0
	s_cbranch_scc1 .Lskr_cs_4
	ds_read_b128 v[140:143], v152
	ds_read_b128 v[144:147], v152 offset:1024
	ds_read_b128 v[148:151], v152 offset:2048
	ds_read_b128 v[152:155], v152 offset:3072
	ds_read_b128 v[156:159], v172
	ds_read_b128 v[160:163], v172 offset:1024
	ds_read_b128 v[168:171], v172 offset:2048
	ds_read_b128 v[172:175], v172 offset:3072

; #define PG8_STAGE(bufoff, gbase, voff) do { _Pragma("unroll") for (int _i = 0; _i < 2; ++_i) \
;         __builtin_amdgcn_global_load_lds((const unsigned*)((const char*)(gbase) + (voff)[_i]), (LAS unsigned*)(lds + (bufoff) + ldsw + _i * 8192), 16, 0, 0); } while (0)
; #define PG8_LDA(dst, b, h) do { _Pragma("unroll") for (int m = 0; m < 4; ++m) _Pragma("unroll") for (int k = 0; k < 2; ++k) dst[m][k] = *(const LAS bf16x8*)(lds + PG8_SA(b, h) + aoff + m * 2048 + k * 1024); } while (0)
; #define PG8_LDB(dst, b, h) do { _Pragma("unroll") for (int n = 0; n < 2; ++n) _Pragma("unroll") for (int k = 0; k < 2; ++k) dst[n][k] = *(const LAS bf16x8*)(lds + PG8_SB(b, h) + boff + n * 2048 + k * 1024); } while (0)
; #define PG8_MMA(ai, bj, At, Bt) do { __builtin_amdgcn_s_setprio(1); _Pragma("unroll") for (int m = 0; m < 4; ++m) _Pragma("unroll") for (int n = 0; n < 2; ++n) _Pragma("unroll") for (int k = 0; k < 2; ++k) \
;         acc[ai][bj][m][n] = __builtin_amdgcn_mfma_f32_16x16x32_bf16(Bt[n][k], At[m][k], acc[ai][bj][m][n], 0, 0, 0); __builtin_amdgcn_s_setprio(0); } while (0)
; #define PG8_WAIT_V(n) asm volatile("s_waitcnt vmcnt(" #n ")" ::: "memory")
; #define PG8_WAIT_L(n) asm volatile("s_waitcnt lgkmcnt(" #n ")" ::: "memory")
; #define PG8_BAR __builtin_amdgcn_s_barrier()
; #define PG8_SCHED __builtin_amdgcn_sched_barrier(0)
; template <class Epi, class Sched>
; __device__ __forceinline__ void gemm_phase(LAS unsigned char* lds, const GemmP g, const Sched& S, const Epi& E, int tid) {
;     ...
;             PG8_LDB(B0, 1, 0); PG8_LDB(B1, 1, 1); PG8_SCHED; PG8_LDA(At, 1, 0); PG8_STAGE(PG8_SA(0, 1), a2 + hstepA, voffA);
;             PG8_WAIT_V(8); PG8_WAIT_L(0); PG8_BAR; PG8_MMA(0, 0, At, B0); PG8_MMA(0, 1, At, B1); PG8_BAR; PG8_SCHED;
;             PG8_LDA(At, 1, 1); PG8_STAGE(PG8_SB(1, 0), b3, voffB); PG8_STAGE(PG8_SB(1, 1), b3 + hstepB, voffB); PG8_STAGE(PG8_SA(1, 0), a3, voffA);
;             PG8_WAIT_V(8); PG8_WAIT_L(0); PG8_BAR; PG8_MMA(1, 0, At, B0); PG8_MMA(1, 1, At, B1); PG8_BAR; PG8_SCHED;
;         }
.Lskr_cs_5:
	global_load_lds_dwordx4 v[222:223], off
	v_lshl_add_u64 v[222:223], s[30:31], 0, v[132:133]
	s_mov_b32 m0, s47
	s_nop 0
	global_load_lds_dwordx4 v[222:223], off
	s_waitcnt vmcnt(8)
	s_waitcnt lgkmcnt(0)
	s_barrier
	s_cmp_lg_u32 s32, 0
	s_cbranch_scc1 .Lsk_cs_3
	s_waitcnt lgkmcnt(0)
	v_mfma_f32_16x16x32_bf16 v[124:127], v[140:143], v[176:179], v[124:127]
	v_mfma_f32_16x16x32_bf16 v[120:123], v[148:151], v[176:179], v[120:123]
	v_mfma_f32_16x16x32_bf16 v[108:111], v[140:143], v[184:187], v[108:111]
	v_mfma_f32_16x16x32_bf16 v[104:107], v[148:151], v[184:187], v[104:107]
	v_mfma_f32_16x16x32_bf16 v[92:95], v[140:143], v[192:195], v[92:95]
	v_mfma_f32_16x16x32_bf16 v[88:91], v[148:151], v[192:195], v[88:91]
	v_mfma_f32_16x16x32_bf16 v[76:79], v[140:143], v[210:213], v[76:79]
	v_mfma_f32_16x16x32_bf16 v[72:75], v[148:151], v[210:213], v[72:75]
	v_mfma_f32_16x16x32_bf16 v[124:127], v[144:147], v[180:183], v[124:127]
	v_mfma_f32_16x16x32_bf16 v[120:123], v[152:155], v[180:183], v[120:123]
	v_mfma_f32_16x16x32_bf16 v[108:111], v[144:147], v[188:191], v[108:111]
	v_mfma_f32_16x16x32_bf16 v[104:107], v[152:155], v[188:191], v[104:107]
	v_mfma_f32_16x16x32_bf16 v[92:95], v[144:147], v[206:209], v[92:95]
	v_mfma_f32_16x16x32_bf16 v[88:91], v[152:155], v[206:209], v[88:91]
	v_mfma_f32_16x16x32_bf16 v[76:79], v[144:147], v[214:217], v[76:79]
	v_mfma_f32_16x16x32_bf16 v[72:75], v[152:155], v[214:217], v[72:75]
	v_mfma_f32_16x16x32_bf16 v[116:119], v[156:159], v[176:179], v[116:119]
	v_mfma_f32_16x16x32_bf16 v[112:115], v[168:171], v[176:179], v[112:115]
	v_mfma_f32_16x16x32_bf16 v[100:103], v[156:159], v[184:187], v[100:103]
	v_mfma_f32_16x16x32_bf16 v[96:99], v[168:171], v[184:187], v[96:99]
	v_mfma_f32_16x16x32_bf16 v[84:87], v[156:159], v[192:195], v[84:87]
	v_mfma_f32_16x16x32_bf16 v[80:83], v[168:171], v[192:195], v[80:83]
	v_mfma_f32_16x16x32_bf16 v[68:71], v[156:159], v[210:213], v[68:71]
	v_mfma_f32_16x16x32_bf16 v[64:67], v[168:171], v[210:213], v[64:67]
	v_mfma_f32_16x16x32_bf16 v[116:119], v[160:163], v[180:183], v[116:119]
	v_mfma_f32_16x16x32_bf16 v[112:115], v[172:175], v[180:183], v[112:115]
	v_mfma_f32_16x16x32_bf16 v[100:103], v[160:163], v[188:191], v[100:103]
	v_mfma_f32_16x16x32_bf16 v[96:99], v[172:175], v[188:191], v[96:99]
	v_mfma_f32_16x16x32_bf16 v[84:87], v[160:163], v[206:209], v[84:87]
	v_mfma_f32_16x16x32_bf16 v[80:83], v[172:175], v[206:209], v[80:83]
	v_mfma_f32_16x16x32_bf16 v[68:71], v[160:163], v[214:217], v[68:71]
	v_mfma_f32_16x16x32_bf16 v[64:67], v[172:175], v[214:217], v[64:67]
.Lsk_cs_3:
	s_barrier
	s_add_i32 s30, s60, s41
	v_lshl_add_u64 v[164:165], v[164:165], 0, s[80:81]
	s_mov_b32 m0, s30
	s_cmp_lg_u32 s98, 0
	s_cbranch_scc1 .Lskr_cs_6
	ds_read_b128 v[176:179], v167 offset:49152
	ds_read_b128 v[180:183], v167 offset:50176
	ds_read_b128 v[184:187], v167 offset:51200
	ds_read_b128 v[188:191], v167 offset:52224
	ds_read_b128 v[192:195], v167 offset:53248
	ds_read_b128 v[206:209], v167 offset:54272
	ds_read_b128 v[210:213], v167 offset:55296
	ds_read_b128 v[214:217], v167 offset:56320
.Lskr_cs_6:
	global_load_lds_dwordx4 v[164:165], off
	s_add_i32 m0, s30, 0x2000
	s_add_u32 s28, s28, 0x40080
	v_lshl_add_u64 v[164:165], v[198:199], 0, s[80:81]
	s_addc_u32 s29, s29, 0
	s_add_i32 s30, s61, s41
	global_load_lds_dwordx4 v[164:165], off
	v_lshl_add_u64 v[164:165], s[28:29], 0, v[130:131]
	s_mov_b32 m0, s30
	s_nop 0
	global_load_lds_dwordx4 v[164:165], off
	v_lshl_add_u64 v[164:165], s[28:29], 0, v[134:135]
	s_add_i32 m0, s30, 0x2000
	s_nop 0
	global_load_lds_dwordx4 v[164:165], off
	v_lshl_add_u64 v[164:165], v[200:201], 0, s[80:81]
	s_mov_b32 m0, s51
	s_nop 0
	global_load_lds_dwordx4 v[164:165], off
	v_lshl_add_u64 v[164:165], v[220:221], 0, s[80:81]
	s_mov_b32 m0, s52
	s_nop 0
	global_load_lds_dwordx4 v[164:165], off
	s_waitcnt vmcnt(8)
	s_waitcnt lgkmcnt(0)
	s_barrier
	s_cmp_lg_u32 s98, 0
	s_cbranch_scc1 .Lsk_cs_4
	s_waitcnt lgkmcnt(0)
	v_mfma_f32_16x16x32_bf16 v[60:63], v[140:143], v[176:179], v[60:63]
	v_mfma_f32_16x16x32_bf16 v[56:59], v[148:151], v[176:179], v[56:59]
	v_mfma_f32_16x16x32_bf16 v[44:47], v[140:143], v[184:187], v[44:47]
	v_mfma_f32_16x16x32_bf16 v[40:43], v[148:151], v[184:187], v[40:43]
	v_mfma_f32_16x16x32_bf16 v[28:31], v[140:143], v[192:195], v[28:31]
	v_mfma_f32_16x16x32_bf16 v[24:27], v[148:151], v[192:195], v[24:27]
	v_mfma_f32_16x16x32_bf16 v[12:15], v[140:143], v[210:213], v[12:15]
	v_mfma_f32_16x16x32_bf16 v[8:11], v[148:151], v[210:213], v[8:11]
	v_mfma_f32_16x16x32_bf16 v[60:63], v[144:147], v[180:183], v[60:63]
	v_mfma_f32_16x16x32_bf16 v[56:59], v[152:155], v[180:183], v[56:59]
	v_mfma_f32_16x16x32_bf16 v[44:47], v[144:147], v[188:191], v[44:47]
	v_mfma_f32_16x16x32_bf16 v[40:43], v[152:155], v[188:191], v[40:43]
	v_mfma_f32_16x16x32_bf16 v[28:31], v[144:147], v[206:209], v[28:31]
	v_mfma_f32_16x16x32_bf16 v[24:27], v[152:155], v[206:209], v[24:27]
	v_mfma_f32_16x16x32_bf16 v[12:15], v[144:147], v[214:217], v[12:15]
	v_mfma_f32_16x16x32_bf16 v[8:11], v[152:155], v[214:217], v[8:11]
	v_mfma_f32_16x16x32_bf16 v[52:55], v[156:159], v[176:179], v[52:55]
	v_mfma_f32_16x16x32_bf16 v[48:51], v[168:171], v[176:179], v[48:51]
	v_mfma_f32_16x16x32_bf16 v[36:39], v[156:159], v[184:187], v[36:39]
	v_mfma_f32_16x16x32_bf16 v[32:35], v[168:171], v[184:187], v[32:35]
	v_mfma_f32_16x16x32_bf16 v[20:23], v[156:159], v[192:195], v[20:23]
	v_mfma_f32_16x16x32_bf16 v[16:19], v[168:171], v[192:195], v[16:19]
	v_mfma_f32_16x16x32_bf16 v[4:7], v[156:159], v[210:213], v[4:7]
	v_mfma_f32_16x16x32_bf16 v[0:3], v[168:171], v[210:213], v[0:3]
	v_mfma_f32_16x16x32_bf16 v[52:55], v[160:163], v[180:183], v[52:55]
	v_mfma_f32_16x16x32_bf16 v[48:51], v[172:175], v[180:183], v[48:51]
	v_mfma_f32_16x16x32_bf16 v[36:39], v[160:163], v[188:191], v[36:39]
	v_mfma_f32_16x16x32_bf16 v[32:35], v[172:175], v[188:191], v[32:35]
	v_mfma_f32_16x16x32_bf16 v[20:23], v[160:163], v[206:209], v[20:23]
	v_mfma_f32_16x16x32_bf16 v[16:19], v[172:175], v[206:209], v[16:19]
	v_mfma_f32_16x16x32_bf16 v[4:7], v[160:163], v[214:217], v[4:7]
	v_mfma_f32_16x16x32_bf16 v[0:3], v[172:175], v[214:217], v[0:3]
.Lsk_cs_4:
	s_barrier
	s_add_i32 s57, s57, 2
	s_add_u32 s5, s5, 0x100
	s_addc_u32 s56, s56, 0
	s_add_u32 s26, s26, 0x100
	s_addc_u32 s27, s27, 0
	s_cmp_gt_u32 s57, 13
	s_cbranch_scc0 .LBB0_996
	s_setprio 0
	s_and_b64 vcc, exec, s[16:17]
	s_cbranch_vccz .LBB0_999
	s_barrier

; #define PG8_STAGE(bufoff, gbase, voff) do { _Pragma("unroll") for (int _i = 0; _i < 2; ++_i) \
;         __builtin_amdgcn_global_load_lds((const unsigned*)((const char*)(gbase) + (voff)[_i]), (LAS unsigned*)(lds + (bufoff) + ldsw + _i * 8192), 16, 0, 0); } while (0)
; #define PG8_LDA(dst, b, h) do { _Pragma("unroll") for (int m = 0; m < 4; ++m) _Pragma("unroll") for (int k = 0; k < 2; ++k) dst[m][k] = *(const LAS bf16x8*)(lds + PG8_SA(b, h) + aoff + m * 2048 + k * 1024); } while (0)
; #define PG8_LDB(dst, b, h) do { _Pragma("unroll") for (int n = 0; n < 2; ++n) _Pragma("unroll") for (int k = 0; k < 2; ++k) dst[n][k] = *(const LAS bf16x8*)(lds + PG8_SB(b, h) + boff + n * 2048 + k * 1024); } while (0)
; #define PG8_MMA(ai, bj, At, Bt) do { __builtin_amdgcn_s_setprio(1); _Pragma("unroll") for (int m = 0; m < 4; ++m) _Pragma("unroll") for (int n = 0; n < 2; ++n) _Pragma("unroll") for (int k = 0; k < 2; ++k) \
;         acc[ai][bj][m][n] = __builtin_amdgcn_mfma_f32_16x16x32_bf16(Bt[n][k], At[m][k], acc[ai][bj][m][n], 0, 0, 0); __builtin_amdgcn_s_setprio(0); } while (0)
; #define PG8_WAIT_V(n) asm volatile("s_waitcnt vmcnt(" #n ")" ::: "memory")
; #define PG8_WAIT_L(n) asm volatile("s_waitcnt lgkmcnt(" #n ")" ::: "memory")
; #define PG8_BAR __builtin_amdgcn_s_barrier()
; template <class Epi, class Sched>
; __device__ __forceinline__ void gemm_phase(LAS unsigned char* lds, const GemmP g, const Sched& S, const Epi& E, int tid) {
;     ...
;         for (int t = 0; t < nt; t += 2) {
;             const bool last = (t == nt - 2);
;             const char* a1 = cA + (size_t)(t + 1) * kstep;
;             const char* a2 = last ? nA : cA + (size_t)(t + 2) * kstep; const char* b2 = last ? nB : cB + (size_t)(t + 2) * kstep;
;             const char* a3 = a2 + kstep; const char* b3 = b2 + kstep;
;             PG8_LDB(B0, 0, 0); PG8_LDB(B1, 0, 1); PG8_SCHED; PG8_LDA(At, 0, 0); PG8_STAGE(PG8_SA(1, 1), a1 + hstepA, voffA);
;             PG8_WAIT_V(8); PG8_WAIT_L(0); PG8_BAR; PG8_MMA(0, 0, At, B0); PG8_MMA(0, 1, At, B1); PG8_BAR; PG8_SCHED;
;     ...
; #pragma unroll
;         for (int a = 0; a < 2; ++a)
; #pragma unroll
;             for (int b = 0; b < 2; ++b)
; #pragma unroll
;                 for (int m = 0; m < 4; ++m)
; #pragma unroll
;                     for (int n = 0; n < 2; ++n) acc[a][b][m][n] = (f32x4){0.f, 0.f, 0.f, 0.f};
;         cur = nxt; cA = nA; cB = nB; ++ui;
.LBB0_1052:
	s_add_u32 s52, s22, 0x100
	s_addc_u32 s53, s23, 0
	s_add_u32 s20, s20, 0x40080
	v_mov_b32_e32 v0, 0
	s_addc_u32 s21, s21, 0
	s_mov_b32 s54, -2
	v_mov_b32_e32 v1, v0
	v_mov_b32_e32 v2, v0
	v_mov_b32_e32 v3, v0
	v_mov_b32_e32 v4, v0
	v_mov_b32_e32 v5, v0
	v_mov_b32_e32 v6, v0
	v_mov_b32_e32 v7, v0
	v_mov_b32_e32 v8, v0
	v_mov_b32_e32 v9, v0
	v_mov_b32_e32 v10, v0
	v_mov_b32_e32 v11, v0
	v_mov_b32_e32 v12, v0
	v_mov_b32_e32 v13, v0
	v_mov_b32_e32 v14, v0
	v_mov_b32_e32 v15, v0
	v_mov_b32_e32 v24, v0
	v_mov_b32_e32 v25, v0
	v_mov_b32_e32 v26, v0
	v_mov_b32_e32 v27, v0
	v_mov_b32_e32 v28, v0
	v_mov_b32_e32 v29, v0
	v_mov_b32_e32 v30, v0
	v_mov_b32_e32 v31, v0
	v_mov_b32_e32 v40, v0
	v_mov_b32_e32 v41, v0
	v_mov_b32_e32 v42, v0
	v_mov_b32_e32 v43, v0
	v_mov_b32_e32 v44, v0
	v_mov_b32_e32 v45, v0
	v_mov_b32_e32 v46, v0
	v_mov_b32_e32 v47, v0
	v_mov_b32_e32 v16, v0
	v_mov_b32_e32 v17, v0
	v_mov_b32_e32 v18, v0
	v_mov_b32_e32 v19, v0
	v_mov_b32_e32 v20, v0
	v_mov_b32_e32 v21, v0
	v_mov_b32_e32 v22, v0
	v_mov_b32_e32 v23, v0
	v_mov_b32_e32 v32, v0
	v_mov_b32_e32 v33, v0
	v_mov_b32_e32 v34, v0
	v_mov_b32_e32 v35, v0
	v_mov_b32_e32 v36, v0
	v_mov_b32_e32 v37, v0
	v_mov_b32_e32 v38, v0
	v_mov_b32_e32 v39, v0
	v_mov_b32_e32 v48, v0
	v_mov_b32_e32 v49, v0
	v_mov_b32_e32 v50, v0
	v_mov_b32_e32 v51, v0
	v_mov_b32_e32 v52, v0
	v_mov_b32_e32 v53, v0
	v_mov_b32_e32 v54, v0
	v_mov_b32_e32 v55, v0
	v_mov_b32_e32 v56, v0
	v_mov_b32_e32 v57, v0
	v_mov_b32_e32 v58, v0
	v_mov_b32_e32 v59, v0
	v_mov_b32_e32 v60, v0
	v_mov_b32_e32 v61, v0
	v_mov_b32_e32 v62, v0
	v_mov_b32_e32 v63, v0
	v_mov_b32_e32 v64, v0
	v_mov_b32_e32 v65, v0
	v_mov_b32_e32 v66, v0
	v_mov_b32_e32 v67, v0
	v_mov_b32_e32 v68, v0
	v_mov_b32_e32 v69, v0
	v_mov_b32_e32 v70, v0
	v_mov_b32_e32 v71, v0
	v_mov_b32_e32 v72, v0
	v_mov_b32_e32 v73, v0
	v_mov_b32_e32 v74, v0
	v_mov_b32_e32 v75, v0
	v_mov_b32_e32 v76, v0
	v_mov_b32_e32 v77, v0
	v_mov_b32_e32 v78, v0
	v_mov_b32_e32 v79, v0
	v_mov_b32_e32 v88, v0
	v_mov_b32_e32 v89, v0
	v_mov_b32_e32 v90, v0
	v_mov_b32_e32 v91, v0
	v_mov_b32_e32 v92, v0
	v_mov_b32_e32 v93, v0
	v_mov_b32_e32 v94, v0
	v_mov_b32_e32 v95, v0
	v_mov_b32_e32 v104, v0
	v_mov_b32_e32 v105, v0
	v_mov_b32_e32 v106, v0
	v_mov_b32_e32 v107, v0
	v_mov_b32_e32 v108, v0
	v_mov_b32_e32 v109, v0
	v_mov_b32_e32 v110, v0
	v_mov_b32_e32 v111, v0
	v_mov_b32_e32 v80, v0
	v_mov_b32_e32 v81, v0
	v_mov_b32_e32 v82, v0
	v_mov_b32_e32 v83, v0
	v_mov_b32_e32 v84, v0
	v_mov_b32_e32 v85, v0
	v_mov_b32_e32 v86, v0
	v_mov_b32_e32 v87, v0
	v_mov_b32_e32 v96, v0
	v_mov_b32_e32 v97, v0
	v_mov_b32_e32 v98, v0
	v_mov_b32_e32 v99, v0
	v_mov_b32_e32 v100, v0
	v_mov_b32_e32 v101, v0
	v_mov_b32_e32 v102, v0
	v_mov_b32_e32 v103, v0
	v_mov_b32_e32 v112, v0
	v_mov_b32_e32 v113, v0
	v_mov_b32_e32 v114, v0
	v_mov_b32_e32 v115, v0
	v_mov_b32_e32 v116, v0
	v_mov_b32_e32 v117, v0
	v_mov_b32_e32 v118, v0
	v_mov_b32_e32 v119, v0
	v_mov_b32_e32 v120, v0
	v_mov_b32_e32 v121, v0
	v_mov_b32_e32 v122, v0
	v_mov_b32_e32 v123, v0
	v_mov_b32_e32 v124, v0
	v_mov_b32_e32 v125, v0
	v_mov_b32_e32 v126, v0
	v_mov_b32_e32 v127, v0
	s_cmp_lg_u64 s[12:13], 0
	s_cbranch_scc1 .Lsp_1053
	s_setprio 1
.Lsp_1053:
.LBB0_1053:
	s_add_u32 s22, s20, 0xfffc0080
	s_addc_u32 s23, s21, -1
	s_add_i32 s56, 0, 0x10000
	s_cmp_eq_u32 s54, 12
	s_cselect_b32 s25, s17, s23
	s_cselect_b32 s24, s16, s22
	v_add_u32_e32 v141, s56, v139
	s_cselect_b32 s23, s19, s53
	s_cselect_b32 s22, s18, s52
	s_add_i32 s58, 0, 0x14000
	ds_read_b128 v[142:145], v141
	ds_read_b128 v[146:149], v141 offset:1024
	ds_read_b128 v[150:153], v141 offset:2048
	ds_read_b128 v[154:157], v141 offset:3072
	v_add_u32_e32 v141, s58, v139
	ds_read_b128 v[158:161], v141
	ds_read_b128 v[162:165], v141 offset:1024
	ds_read_b128 v[166:169], v141 offset:2048
	ds_read_b128 v[170:173], v141 offset:3072
	v_lshl_add_u64 v[194:195], s[20:21], 0, v[136:137]
	s_add_i32 m0, s39, 0xc000
	ds_read_b128 v[174:177], v140
	ds_read_b128 v[178:181], v140 offset:1024
	ds_read_b128 v[182:185], v140 offset:2048
	ds_read_b128 v[186:189], v140 offset:3072
	ds_read_b128 v[190:193], v140 offset:4096
	ds_read_b128 v[206:209], v140 offset:5120
	ds_read_b128 v[210:213], v140 offset:6144
	ds_read_b128 v[214:217], v140 offset:7168
	global_load_lds_dwordx4 v[194:195], off
	v_lshl_add_u64 v[194:195], s[20:21], 0, v[134:135]
	s_add_i32 m0, s39, 0xe000
	s_nop 0
	global_load_lds_dwordx4 v[194:195], off
	s_waitcnt vmcnt(8)
	s_waitcnt lgkmcnt(0)
	s_barrier
	s_waitcnt lgkmcnt(0)
	v_mfma_f32_16x16x32_bf16 v[124:127], v[142:145], v[174:177], v[124:127]
	v_mfma_f32_16x16x32_bf16 v[120:123], v[150:153], v[174:177], v[120:123]
	v_mfma_f32_16x16x32_bf16 v[116:119], v[142:145], v[182:185], v[116:119]
	v_mfma_f32_16x16x32_bf16 v[112:115], v[150:153], v[182:185], v[112:115]
	v_mfma_f32_16x16x32_bf16 v[100:103], v[142:145], v[190:193], v[100:103]
	v_mfma_f32_16x16x32_bf16 v[96:99], v[150:153], v[190:193], v[96:99]
	v_mfma_f32_16x16x32_bf16 v[84:87], v[142:145], v[210:213], v[84:87]
	v_mfma_f32_16x16x32_bf16 v[80:83], v[150:153], v[210:213], v[80:83]
	v_mfma_f32_16x16x32_bf16 v[124:127], v[146:149], v[178:181], v[124:127]
	v_mfma_f32_16x16x32_bf16 v[120:123], v[154:157], v[178:181], v[120:123]
	v_mfma_f32_16x16x32_bf16 v[116:119], v[146:149], v[186:189], v[116:119]
	v_mfma_f32_16x16x32_bf16 v[112:115], v[154:157], v[186:189], v[112:115]
	v_mfma_f32_16x16x32_bf16 v[100:103], v[146:149], v[206:209], v[100:103]
	v_mfma_f32_16x16x32_bf16 v[96:99], v[154:157], v[206:209], v[96:99]
	v_mfma_f32_16x16x32_bf16 v[84:87], v[146:149], v[214:217], v[84:87]
	v_mfma_f32_16x16x32_bf16 v[80:83], v[154:157], v[214:217], v[80:83]
	v_mfma_f32_16x16x32_bf16 v[108:111], v[158:161], v[174:177], v[108:111]
	v_mfma_f32_16x16x32_bf16 v[104:107], v[166:169], v[174:177], v[104:107]
	v_mfma_f32_16x16x32_bf16 v[92:95], v[158:161], v[182:185], v[92:95]
	v_mfma_f32_16x16x32_bf16 v[88:91], v[166:169], v[182:185], v[88:91]
	v_mfma_f32_16x16x32_bf16 v[76:79], v[158:161], v[190:193], v[76:79]
	v_mfma_f32_16x16x32_bf16 v[72:75], v[166:169], v[190:193], v[72:75]
	v_mfma_f32_16x16x32_bf16 v[68:71], v[158:161], v[210:213], v[68:71]
	v_mfma_f32_16x16x32_bf16 v[64:67], v[166:169], v[210:213], v[64:67]
	v_mfma_f32_16x16x32_bf16 v[108:111], v[162:165], v[178:181], v[108:111]
	v_mfma_f32_16x16x32_bf16 v[104:107], v[170:173], v[178:181], v[104:107]
	v_mfma_f32_16x16x32_bf16 v[92:95], v[162:165], v[186:189], v[92:95]
	v_mfma_f32_16x16x32_bf16 v[88:91], v[170:173], v[186:189], v[88:91]
	v_mfma_f32_16x16x32_bf16 v[76:79], v[162:165], v[206:209], v[76:79]
	v_mfma_f32_16x16x32_bf16 v[72:75], v[170:173], v[206:209], v[72:75]
	v_mfma_f32_16x16x32_bf16 v[68:71], v[162:165], v[214:217], v[68:71]
	v_mfma_f32_16x16x32_bf16 v[64:67], v[170:173], v[214:217], v[64:67]
	s_barrier
; #define PG8_STAGE(bufoff, gbase, voff) do { _Pragma("unroll") for (int _i = 0; _i < 2; ++_i) \
;         __builtin_amdgcn_global_load_lds((const unsigned*)((const char*)(gbase) + (voff)[_i]), (LAS unsigned*)(lds + (bufoff) + ldsw + _i * 8192), 16, 0, 0); } while (0)
; #define PG8_LDA(dst, b, h) do { _Pragma("unroll") for (int m = 0; m < 4; ++m) _Pragma("unroll") for (int k = 0; k < 2; ++k) dst[m][k] = *(const LAS bf16x8*)(lds + PG8_SA(b, h) + aoff + m * 2048 + k * 1024); } while (0)
; #define PG8_LDB(dst, b, h) do { _Pragma("unroll") for (int n = 0; n < 2; ++n) _Pragma("unroll") for (int k = 0; k < 2; ++k) dst[n][k] = *(const LAS bf16x8*)(lds + PG8_SB(b, h) + boff + n * 2048 + k * 1024); } while (0)
; #define PG8_MMA(ai, bj, At, Bt) do { __builtin_amdgcn_s_setprio(1); _Pragma("unroll") for (int m = 0; m < 4; ++m) _Pragma("unroll") for (int n = 0; n < 2; ++n) _Pragma("unroll") for (int k = 0; k < 2; ++k) \
;         acc[ai][bj][m][n] = __builtin_amdgcn_mfma_f32_16x16x32_bf16(Bt[n][k], At[m][k], acc[ai][bj][m][n], 0, 0, 0); __builtin_amdgcn_s_setprio(0); } while (0)
; #define PG8_WAIT_V(n) asm volatile("s_waitcnt vmcnt(" #n ")" ::: "memory")
; #define PG8_WAIT_L(n) asm volatile("s_waitcnt lgkmcnt(" #n ")" ::: "memory")
; #define PG8_BAR __builtin_amdgcn_s_barrier()
; #define PG8_SCHED __builtin_amdgcn_sched_barrier(0)
; template <class Epi, class Sched>
; __device__ __forceinline__ void gemm_phase(LAS unsigned char* lds, const GemmP g, const Sched& S, const Epi& E, int tid) {
;     ...
;             PG8_LDA(At, 0, 1); PG8_STAGE(PG8_SB(0, 0), b2, voffB); PG8_STAGE(PG8_SB(0, 1), b2 + hstepB, voffB); PG8_STAGE(PG8_SA(0, 0), a2, voffA);
;             PG8_WAIT_V(8); PG8_WAIT_L(0); PG8_BAR; PG8_MMA(1, 0, At, B0); PG8_MMA(1, 1, At, B1); PG8_BAR; PG8_SCHED;
;             PG8_LDB(B0, 1, 0); PG8_LDB(B1, 1, 1); PG8_SCHED; PG8_LDA(At, 1, 0); PG8_STAGE(PG8_SA(0, 1), a2 + hstepA, voffA);
;             PG8_WAIT_V(8); PG8_WAIT_L(0); PG8_BAR; PG8_MMA(0, 0, At, B0); PG8_MMA(0, 1, At, B1); PG8_BAR; PG8_SCHED;
	s_add_i32 s56, s56, s38
	v_lshl_add_u64 v[194:195], s[22:23], 0, v[196:197]
	s_mov_b32 m0, s56
	ds_read_b128 v[174:177], v140 offset:16384
	ds_read_b128 v[178:181], v140 offset:17408
	ds_read_b128 v[182:185], v140 offset:18432
	ds_read_b128 v[186:189], v140 offset:19456
	ds_read_b128 v[190:193], v140 offset:20480
	ds_read_b128 v[206:209], v140 offset:21504
	ds_read_b128 v[210:213], v140 offset:22528
	ds_read_b128 v[214:217], v140 offset:23552
	global_load_lds_dwordx4 v[194:195], off
	s_add_i32 m0, s56, 0x2000
	s_add_u32 s56, s22, 0x40000
	v_lshl_add_u64 v[198:199], s[22:23], 0, v[128:129]
	s_addc_u32 s57, s23, 0
	s_add_i32 s58, s58, s38
	global_load_lds_dwordx4 v[198:199], off
	v_lshl_add_u64 v[200:201], s[56:57], 0, v[196:197]
	s_mov_b32 m0, s58
	v_lshl_add_u64 v[220:221], s[24:25], 0, v[130:131]
	global_load_lds_dwordx4 v[200:201], off
	v_lshl_add_u64 v[200:201], s[56:57], 0, v[128:129]
	s_add_i32 m0, s58, 0x2000
	s_nop 0
	global_load_lds_dwordx4 v[200:201], off
	v_lshl_add_u64 v[200:201], s[24:25], 0, v[132:133]
	s_mov_b32 m0, s39
	s_nop 0
	global_load_lds_dwordx4 v[200:201], off
	s_mov_b32 m0, s40
	s_nop 0
	global_load_lds_dwordx4 v[220:221], off
	s_waitcnt vmcnt(8)
	s_waitcnt lgkmcnt(0)
	s_barrier
	s_waitcnt lgkmcnt(0)
	v_mfma_f32_16x16x32_bf16 v[60:63], v[142:145], v[174:177], v[60:63]
	v_mfma_f32_16x16x32_bf16 v[56:59], v[150:153], v[174:177], v[56:59]
	v_mfma_f32_16x16x32_bf16 v[52:55], v[142:145], v[182:185], v[52:55]
	v_mfma_f32_16x16x32_bf16 v[48:51], v[150:153], v[182:185], v[48:51]
	v_mfma_f32_16x16x32_bf16 v[36:39], v[142:145], v[190:193], v[36:39]
	v_mfma_f32_16x16x32_bf16 v[32:35], v[150:153], v[190:193], v[32:35]
	v_mfma_f32_16x16x32_bf16 v[20:23], v[142:145], v[210:213], v[20:23]
	v_mfma_f32_16x16x32_bf16 v[16:19], v[150:153], v[210:213], v[16:19]
	v_mfma_f32_16x16x32_bf16 v[60:63], v[146:149], v[178:181], v[60:63]
	v_mfma_f32_16x16x32_bf16 v[56:59], v[154:157], v[178:181], v[56:59]
	v_mfma_f32_16x16x32_bf16 v[52:55], v[146:149], v[186:189], v[52:55]
	v_mfma_f32_16x16x32_bf16 v[48:51], v[154:157], v[186:189], v[48:51]
	v_mfma_f32_16x16x32_bf16 v[36:39], v[146:149], v[206:209], v[36:39]
	v_mfma_f32_16x16x32_bf16 v[32:35], v[154:157], v[206:209], v[32:35]
	v_mfma_f32_16x16x32_bf16 v[20:23], v[146:149], v[214:217], v[20:23]
	v_mfma_f32_16x16x32_bf16 v[16:19], v[154:157], v[214:217], v[16:19]
	v_mfma_f32_16x16x32_bf16 v[44:47], v[158:161], v[174:177], v[44:47]
	v_mfma_f32_16x16x32_bf16 v[40:43], v[166:169], v[174:177], v[40:43]
	v_mfma_f32_16x16x32_bf16 v[28:31], v[158:161], v[182:185], v[28:31]
	v_mfma_f32_16x16x32_bf16 v[24:27], v[166:169], v[182:185], v[24:27]
	v_mfma_f32_16x16x32_bf16 v[12:15], v[158:161], v[190:193], v[12:15]
	v_mfma_f32_16x16x32_bf16 v[8:11], v[166:169], v[190:193], v[8:11]
	v_mfma_f32_16x16x32_bf16 v[4:7], v[158:161], v[210:213], v[4:7]
	v_mfma_f32_16x16x32_bf16 v[0:3], v[166:169], v[210:213], v[0:3]
	v_mfma_f32_16x16x32_bf16 v[44:47], v[162:165], v[178:181], v[44:47]
	v_mfma_f32_16x16x32_bf16 v[40:43], v[170:173], v[178:181], v[40:43]
	v_mfma_f32_16x16x32_bf16 v[28:31], v[162:165], v[186:189], v[28:31]
	v_mfma_f32_16x16x32_bf16 v[24:27], v[170:173], v[186:189], v[24:27]
	v_mfma_f32_16x16x32_bf16 v[12:15], v[162:165], v[206:209], v[12:15]
	v_mfma_f32_16x16x32_bf16 v[8:11], v[170:173], v[206:209], v[8:11]
	v_mfma_f32_16x16x32_bf16 v[4:7], v[162:165], v[214:217], v[4:7]
	v_mfma_f32_16x16x32_bf16 v[0:3], v[170:173], v[214:217], v[0:3]
	s_barrier
	s_add_i32 s56, 0, 0x18000
	v_add_u32_e32 v141, s56, v139
	s_add_i32 s57, 0, 0x1c000
	ds_read_b128 v[142:145], v141
	ds_read_b128 v[146:149], v141 offset:1024
	ds_read_b128 v[150:153], v141 offset:2048
	ds_read_b128 v[154:157], v141 offset:3072
	v_add_u32_e32 v141, s57, v139
	ds_read_b128 v[158:161], v141
	ds_read_b128 v[162:165], v141 offset:1024
	ds_read_b128 v[166:169], v141 offset:2048
	ds_read_b128 v[170:173], v141 offset:3072
	s_add_u32 s24, s24, 0x40000
	s_addc_u32 s25, s25, 0
	s_mov_b32 m0, s41
	v_lshl_add_u64 v[222:223], s[24:25], 0, v[132:133]
	ds_read_b128 v[174:177], v140 offset:32768
	ds_read_b128 v[178:181], v140 offset:33792
	ds_read_b128 v[182:185], v140 offset:34816
	ds_read_b128 v[186:189], v140 offset:35840
	ds_read_b128 v[190:193], v140 offset:36864
	ds_read_b128 v[206:209], v140 offset:37888
	ds_read_b128 v[210:213], v140 offset:38912
	ds_read_b128 v[214:217], v140 offset:39936
	global_load_lds_dwordx4 v[222:223], off
	v_lshl_add_u64 v[222:223], s[24:25], 0, v[130:131]
	s_mov_b32 m0, s42
	s_nop 0
	global_load_lds_dwordx4 v[222:223], off
	s_waitcnt vmcnt(8)
	s_waitcnt lgkmcnt(0)
	s_barrier
; #define PG8_STAGE(bufoff, gbase, voff) do { _Pragma("unroll") for (int _i = 0; _i < 2; ++_i) \
;         __builtin_amdgcn_global_load_lds((const unsigned*)((const char*)(gbase) + (voff)[_i]), (LAS unsigned*)(lds + (bufoff) + ldsw + _i * 8192), 16, 0, 0); } while (0)
; #define PG8_LDA(dst, b, h) do { _Pragma("unroll") for (int m = 0; m < 4; ++m) _Pragma("unroll") for (int k = 0; k < 2; ++k) dst[m][k] = *(const LAS bf16x8*)(lds + PG8_SA(b, h) + aoff + m * 2048 + k * 1024); } while (0)
; #define PG8_MMA(ai, bj, At, Bt) do { __builtin_amdgcn_s_setprio(1); _Pragma("unroll") for (int m = 0; m < 4; ++m) _Pragma("unroll") for (int n = 0; n < 2; ++n) _Pragma("unroll") for (int k = 0; k < 2; ++k) \
;         acc[ai][bj][m][n] = __builtin_amdgcn_mfma_f32_16x16x32_bf16(Bt[n][k], At[m][k], acc[ai][bj][m][n], 0, 0, 0); __builtin_amdgcn_s_setprio(0); } while (0)
; #define PG8_WAIT_V(n) asm volatile("s_waitcnt vmcnt(" #n ")" ::: "memory")
; #define PG8_WAIT_L(n) asm volatile("s_waitcnt lgkmcnt(" #n ")" ::: "memory")
; #define PG8_BAR __builtin_amdgcn_s_barrier()
; #define PG8_SCHED __builtin_amdgcn_sched_barrier(0)
; template <class Epi, class Sched>
; __device__ __forceinline__ void gemm_phase(LAS unsigned char* lds, const GemmP g, const Sched& S, const Epi& E, int tid) {
;     ...
;             PG8_WAIT_V(8); PG8_WAIT_L(0); PG8_BAR; PG8_MMA(0, 0, At, B0); PG8_MMA(0, 1, At, B1); PG8_BAR; PG8_SCHED;
;             PG8_LDA(At, 1, 1); PG8_STAGE(PG8_SB(1, 0), b3, voffB); PG8_STAGE(PG8_SB(1, 1), b3 + hstepB, voffB); PG8_STAGE(PG8_SA(1, 0), a3, voffA);
;             PG8_WAIT_V(8); PG8_WAIT_L(0); PG8_BAR; PG8_MMA(1, 0, At, B0); PG8_MMA(1, 1, At, B1); PG8_BAR; PG8_SCHED;
;         }
	s_waitcnt lgkmcnt(0)
	v_mfma_f32_16x16x32_bf16 v[124:127], v[142:145], v[174:177], v[124:127]
	v_mfma_f32_16x16x32_bf16 v[120:123], v[150:153], v[174:177], v[120:123]
	v_mfma_f32_16x16x32_bf16 v[116:119], v[142:145], v[182:185], v[116:119]
	v_mfma_f32_16x16x32_bf16 v[112:115], v[150:153], v[182:185], v[112:115]
	v_mfma_f32_16x16x32_bf16 v[100:103], v[142:145], v[190:193], v[100:103]
	v_mfma_f32_16x16x32_bf16 v[96:99], v[150:153], v[190:193], v[96:99]
	v_mfma_f32_16x16x32_bf16 v[84:87], v[142:145], v[210:213], v[84:87]
	v_mfma_f32_16x16x32_bf16 v[80:83], v[150:153], v[210:213], v[80:83]
	v_mfma_f32_16x16x32_bf16 v[124:127], v[146:149], v[178:181], v[124:127]
	v_mfma_f32_16x16x32_bf16 v[120:123], v[154:157], v[178:181], v[120:123]
	v_mfma_f32_16x16x32_bf16 v[116:119], v[146:149], v[186:189], v[116:119]
	v_mfma_f32_16x16x32_bf16 v[112:115], v[154:157], v[186:189], v[112:115]
	v_mfma_f32_16x16x32_bf16 v[100:103], v[146:149], v[206:209], v[100:103]
	v_mfma_f32_16x16x32_bf16 v[96:99], v[154:157], v[206:209], v[96:99]
	v_mfma_f32_16x16x32_bf16 v[84:87], v[146:149], v[214:217], v[84:87]
	v_mfma_f32_16x16x32_bf16 v[80:83], v[154:157], v[214:217], v[80:83]
	v_mfma_f32_16x16x32_bf16 v[108:111], v[158:161], v[174:177], v[108:111]
	v_mfma_f32_16x16x32_bf16 v[104:107], v[166:169], v[174:177], v[104:107]
	v_mfma_f32_16x16x32_bf16 v[92:95], v[158:161], v[182:185], v[92:95]
	v_mfma_f32_16x16x32_bf16 v[88:91], v[166:169], v[182:185], v[88:91]
	v_mfma_f32_16x16x32_bf16 v[76:79], v[158:161], v[190:193], v[76:79]
	v_mfma_f32_16x16x32_bf16 v[72:75], v[166:169], v[190:193], v[72:75]
	v_mfma_f32_16x16x32_bf16 v[68:71], v[158:161], v[210:213], v[68:71]
	v_mfma_f32_16x16x32_bf16 v[64:67], v[166:169], v[210:213], v[64:67]
	v_mfma_f32_16x16x32_bf16 v[108:111], v[162:165], v[178:181], v[108:111]
	v_mfma_f32_16x16x32_bf16 v[104:107], v[170:173], v[178:181], v[104:107]
	v_mfma_f32_16x16x32_bf16 v[92:95], v[162:165], v[186:189], v[92:95]
	v_mfma_f32_16x16x32_bf16 v[88:91], v[170:173], v[186:189], v[88:91]
	v_mfma_f32_16x16x32_bf16 v[76:79], v[162:165], v[206:209], v[76:79]
	v_mfma_f32_16x16x32_bf16 v[72:75], v[170:173], v[206:209], v[72:75]
	v_mfma_f32_16x16x32_bf16 v[68:71], v[162:165], v[214:217], v[68:71]
	v_mfma_f32_16x16x32_bf16 v[64:67], v[170:173], v[214:217], v[64:67]
	s_barrier
	s_add_i32 s24, s56, s38
	v_lshl_add_u64 v[194:195], v[194:195], 0, s[80:81]
	s_mov_b32 m0, s24
	ds_read_b128 v[174:177], v140 offset:49152
	ds_read_b128 v[178:181], v140 offset:50176
	ds_read_b128 v[182:185], v140 offset:51200
	ds_read_b128 v[186:189], v140 offset:52224
	ds_read_b128 v[190:193], v140 offset:53248
	ds_read_b128 v[206:209], v140 offset:54272
	ds_read_b128 v[210:213], v140 offset:55296
	ds_read_b128 v[214:217], v140 offset:56320
	global_load_lds_dwordx4 v[194:195], off
	s_add_i32 m0, s24, 0x2000
	s_add_u32 s22, s22, 0x40080
	v_lshl_add_u64 v[194:195], v[198:199], 0, s[80:81]
	s_addc_u32 s23, s23, 0
	s_add_i32 s24, s57, s38
	global_load_lds_dwordx4 v[194:195], off
	v_lshl_add_u64 v[194:195], s[22:23], 0, v[196:197]
	s_mov_b32 m0, s24
	s_nop 0
	global_load_lds_dwordx4 v[194:195], off
	v_lshl_add_u64 v[194:195], s[22:23], 0, v[128:129]
	s_add_i32 m0, s24, 0x2000
	s_nop 0
	global_load_lds_dwordx4 v[194:195], off
	v_lshl_add_u64 v[194:195], v[200:201], 0, s[80:81]
	s_mov_b32 m0, s45
	s_nop 0
	global_load_lds_dwordx4 v[194:195], off
	v_lshl_add_u64 v[194:195], v[220:221], 0, s[80:81]
	s_mov_b32 m0, s46
	s_nop 0
	global_load_lds_dwordx4 v[194:195], off
	s_waitcnt vmcnt(8)
	s_waitcnt lgkmcnt(0)
	s_barrier
	s_waitcnt lgkmcnt(0)
	v_mfma_f32_16x16x32_bf16 v[60:63], v[142:145], v[174:177], v[60:63]
	v_mfma_f32_16x16x32_bf16 v[56:59], v[150:153], v[174:177], v[56:59]
	v_mfma_f32_16x16x32_bf16 v[52:55], v[142:145], v[182:185], v[52:55]
	v_mfma_f32_16x16x32_bf16 v[48:51], v[150:153], v[182:185], v[48:51]
	v_mfma_f32_16x16x32_bf16 v[36:39], v[142:145], v[190:193], v[36:39]
	v_mfma_f32_16x16x32_bf16 v[32:35], v[150:153], v[190:193], v[32:35]
	v_mfma_f32_16x16x32_bf16 v[20:23], v[142:145], v[210:213], v[20:23]
	v_mfma_f32_16x16x32_bf16 v[16:19], v[150:153], v[210:213], v[16:19]
	v_mfma_f32_16x16x32_bf16 v[60:63], v[146:149], v[178:181], v[60:63]
	v_mfma_f32_16x16x32_bf16 v[56:59], v[154:157], v[178:181], v[56:59]
	v_mfma_f32_16x16x32_bf16 v[52:55], v[146:149], v[186:189], v[52:55]
	v_mfma_f32_16x16x32_bf16 v[48:51], v[154:157], v[186:189], v[48:51]
	v_mfma_f32_16x16x32_bf16 v[36:39], v[146:149], v[206:209], v[36:39]
	v_mfma_f32_16x16x32_bf16 v[32:35], v[154:157], v[206:209], v[32:35]
	v_mfma_f32_16x16x32_bf16 v[20:23], v[146:149], v[214:217], v[20:23]
	v_mfma_f32_16x16x32_bf16 v[16:19], v[154:157], v[214:217], v[16:19]
	v_mfma_f32_16x16x32_bf16 v[44:47], v[158:161], v[174:177], v[44:47]
	v_mfma_f32_16x16x32_bf16 v[40:43], v[166:169], v[174:177], v[40:43]
	v_mfma_f32_16x16x32_bf16 v[28:31], v[158:161], v[182:185], v[28:31]
	v_mfma_f32_16x16x32_bf16 v[24:27], v[166:169], v[182:185], v[24:27]
	v_mfma_f32_16x16x32_bf16 v[12:15], v[158:161], v[190:193], v[12:15]
	v_mfma_f32_16x16x32_bf16 v[8:11], v[166:169], v[190:193], v[8:11]
	v_mfma_f32_16x16x32_bf16 v[4:7], v[158:161], v[210:213], v[4:7]
	v_mfma_f32_16x16x32_bf16 v[0:3], v[166:169], v[210:213], v[0:3]
	v_mfma_f32_16x16x32_bf16 v[44:47], v[162:165], v[178:181], v[44:47]
	v_mfma_f32_16x16x32_bf16 v[40:43], v[170:173], v[178:181], v[40:43]
	v_mfma_f32_16x16x32_bf16 v[28:31], v[162:165], v[186:189], v[28:31]
	v_mfma_f32_16x16x32_bf16 v[24:27], v[170:173], v[186:189], v[24:27]
	v_mfma_f32_16x16x32_bf16 v[12:15], v[162:165], v[206:209], v[12:15]
	v_mfma_f32_16x16x32_bf16 v[8:11], v[170:173], v[206:209], v[8:11]
	v_mfma_f32_16x16x32_bf16 v[4:7], v[162:165], v[214:217], v[4:7]
	v_mfma_f32_16x16x32_bf16 v[0:3], v[170:173], v[214:217], v[0:3]
	s_barrier
	s_add_i32 s54, s54, 2
	s_add_u32 s52, s52, 0x100
	s_addc_u32 s53, s53, 0
	s_add_u32 s20, s20, 0x100
	s_addc_u32 s21, s21, 0
	s_cmp_gt_u32 s54, 13
	s_cbranch_scc0 .LBB0_1053
	s_setprio 0
	s_and_b64 vcc, exec, s[12:13]
	s_cbranch_vccz .LBB0_1056
	s_barrier

; #define PG8_STAGE(bufoff, gbase, voff) do { _Pragma("unroll") for (int _i = 0; _i < 2; ++_i) \
;         __builtin_amdgcn_global_load_lds((const unsigned*)((const char*)(gbase) + (voff)[_i]), (LAS unsigned*)(lds + (bufoff) + ldsw + _i * 8192), 16, 0, 0); } while (0)
; #define PG8_LDA(dst, b, h) do { _Pragma("unroll") for (int m = 0; m < 4; ++m) _Pragma("unroll") for (int k = 0; k < 2; ++k) dst[m][k] = *(const LAS bf16x8*)(lds + PG8_SA(b, h) + aoff + m * 2048 + k * 1024); } while (0)
; #define PG8_LDB(dst, b, h) do { _Pragma("unroll") for (int n = 0; n < 2; ++n) _Pragma("unroll") for (int k = 0; k < 2; ++k) dst[n][k] = *(const LAS bf16x8*)(lds + PG8_SB(b, h) + boff + n * 2048 + k * 1024); } while (0)
; #define PG8_MMA(ai, bj, At, Bt) do { __builtin_amdgcn_s_setprio(1); _Pragma("unroll") for (int m = 0; m < 4; ++m) _Pragma("unroll") for (int n = 0; n < 2; ++n) _Pragma("unroll") for (int k = 0; k < 2; ++k) \
;         acc[ai][bj][m][n] = __builtin_amdgcn_mfma_f32_16x16x32_bf16(Bt[n][k], At[m][k], acc[ai][bj][m][n], 0, 0, 0); __builtin_amdgcn_s_setprio(0); } while (0)
; #define PG8_WAIT_V(n) asm volatile("s_waitcnt vmcnt(" #n ")" ::: "memory")
; #define PG8_WAIT_L(n) asm volatile("s_waitcnt lgkmcnt(" #n ")" ::: "memory")
; #define PG8_BAR __builtin_amdgcn_s_barrier()
; template <class Epi, class Sched>
; __device__ __forceinline__ void gemm_phase(LAS unsigned char* lds, const GemmP g, const Sched& S, const Epi& E, int tid) {
;     ...
;         for (int t = 0; t < nt; t += 2) {
;             const bool last = (t == nt - 2);
;             const char* a1 = cA + (size_t)(t + 1) * kstep;
;             const char* a2 = last ? nA : cA + (size_t)(t + 2) * kstep; const char* b2 = last ? nB : cB + (size_t)(t + 2) * kstep;
;             const char* a3 = a2 + kstep; const char* b3 = b2 + kstep;
;             PG8_LDB(B0, 0, 0); PG8_LDB(B1, 0, 1); PG8_SCHED; PG8_LDA(At, 0, 0); PG8_STAGE(PG8_SA(1, 1), a1 + hstepA, voffA);
;             PG8_WAIT_V(8); PG8_WAIT_L(0); PG8_BAR; PG8_MMA(0, 0, At, B0); PG8_MMA(0, 1, At, B1); PG8_BAR; PG8_SCHED;
;     ...
; #pragma unroll
;         for (int a = 0; a < 2; ++a)
; #pragma unroll
;             for (int b = 0; b < 2; ++b)
; #pragma unroll
;                 for (int m = 0; m < 4; ++m)
; #pragma unroll
;                     for (int n = 0; n < 2; ++n) acc[a][b][m][n] = (f32x4){0.f, 0.f, 0.f, 0.f};
;         cur = nxt; cA = nA; cB = nB; ++ui;
.LBB0_1072:
	s_add_u32 s45, s18, 0x100
	s_addc_u32 s46, s19, 0
	s_add_u32 s16, s16, 0x40080
	v_mov_b32_e32 v0, 0
	s_addc_u32 s17, s17, 0
	s_mov_b32 s47, -2
	v_mov_b32_e32 v1, v0
	v_mov_b32_e32 v2, v0
	v_mov_b32_e32 v3, v0
	v_mov_b32_e32 v4, v0
	v_mov_b32_e32 v5, v0
	v_mov_b32_e32 v6, v0
	v_mov_b32_e32 v7, v0
	v_mov_b32_e32 v8, v0
	v_mov_b32_e32 v9, v0
	v_mov_b32_e32 v10, v0
	v_mov_b32_e32 v11, v0
	v_mov_b32_e32 v12, v0
	v_mov_b32_e32 v13, v0
	v_mov_b32_e32 v14, v0
	v_mov_b32_e32 v15, v0
	v_mov_b32_e32 v24, v0
	v_mov_b32_e32 v25, v0
	v_mov_b32_e32 v26, v0
	v_mov_b32_e32 v27, v0
	v_mov_b32_e32 v28, v0
	v_mov_b32_e32 v29, v0
	v_mov_b32_e32 v30, v0
	v_mov_b32_e32 v31, v0
	v_mov_b32_e32 v40, v0
	v_mov_b32_e32 v41, v0
	v_mov_b32_e32 v42, v0
	v_mov_b32_e32 v43, v0
	v_mov_b32_e32 v44, v0
	v_mov_b32_e32 v45, v0
	v_mov_b32_e32 v46, v0
	v_mov_b32_e32 v47, v0
	v_mov_b32_e32 v16, v0
	v_mov_b32_e32 v17, v0
	v_mov_b32_e32 v18, v0
	v_mov_b32_e32 v19, v0
	v_mov_b32_e32 v20, v0
	v_mov_b32_e32 v21, v0
	v_mov_b32_e32 v22, v0
	v_mov_b32_e32 v23, v0
	v_mov_b32_e32 v32, v0
	v_mov_b32_e32 v33, v0
	v_mov_b32_e32 v34, v0
	v_mov_b32_e32 v35, v0
	v_mov_b32_e32 v36, v0
	v_mov_b32_e32 v37, v0
	v_mov_b32_e32 v38, v0
	v_mov_b32_e32 v39, v0
	v_mov_b32_e32 v48, v0
	v_mov_b32_e32 v49, v0
	v_mov_b32_e32 v50, v0
	v_mov_b32_e32 v51, v0
	v_mov_b32_e32 v52, v0
	v_mov_b32_e32 v53, v0
	v_mov_b32_e32 v54, v0
	v_mov_b32_e32 v55, v0
	v_mov_b32_e32 v56, v0
	v_mov_b32_e32 v57, v0
	v_mov_b32_e32 v58, v0
	v_mov_b32_e32 v59, v0
	v_mov_b32_e32 v60, v0
	v_mov_b32_e32 v61, v0
	v_mov_b32_e32 v62, v0
	v_mov_b32_e32 v63, v0
	v_mov_b32_e32 v64, v0
	v_mov_b32_e32 v65, v0
	v_mov_b32_e32 v66, v0
	v_mov_b32_e32 v67, v0
	v_mov_b32_e32 v68, v0
	v_mov_b32_e32 v69, v0
	v_mov_b32_e32 v70, v0
	v_mov_b32_e32 v71, v0
	v_mov_b32_e32 v72, v0
	v_mov_b32_e32 v73, v0
	v_mov_b32_e32 v74, v0
	v_mov_b32_e32 v75, v0
	v_mov_b32_e32 v76, v0
	v_mov_b32_e32 v77, v0
	v_mov_b32_e32 v78, v0
	v_mov_b32_e32 v79, v0
	v_mov_b32_e32 v88, v0
	v_mov_b32_e32 v89, v0
	v_mov_b32_e32 v90, v0
	v_mov_b32_e32 v91, v0
	v_mov_b32_e32 v92, v0
	v_mov_b32_e32 v93, v0
	v_mov_b32_e32 v94, v0
	v_mov_b32_e32 v95, v0
	v_mov_b32_e32 v104, v0
	v_mov_b32_e32 v105, v0
	v_mov_b32_e32 v106, v0
	v_mov_b32_e32 v107, v0
	v_mov_b32_e32 v108, v0
	v_mov_b32_e32 v109, v0
	v_mov_b32_e32 v110, v0
	v_mov_b32_e32 v111, v0
	v_mov_b32_e32 v80, v0
	v_mov_b32_e32 v81, v0
	v_mov_b32_e32 v82, v0
	v_mov_b32_e32 v83, v0
	v_mov_b32_e32 v84, v0
	v_mov_b32_e32 v85, v0
	v_mov_b32_e32 v86, v0
	v_mov_b32_e32 v87, v0
	v_mov_b32_e32 v96, v0
	v_mov_b32_e32 v97, v0
	v_mov_b32_e32 v98, v0
	v_mov_b32_e32 v99, v0
	v_mov_b32_e32 v100, v0
	v_mov_b32_e32 v101, v0
	v_mov_b32_e32 v102, v0
	v_mov_b32_e32 v103, v0
	v_mov_b32_e32 v112, v0
	v_mov_b32_e32 v113, v0
	v_mov_b32_e32 v114, v0
	v_mov_b32_e32 v115, v0
	v_mov_b32_e32 v116, v0
	v_mov_b32_e32 v117, v0
	v_mov_b32_e32 v118, v0
	v_mov_b32_e32 v119, v0
	v_mov_b32_e32 v120, v0
	v_mov_b32_e32 v121, v0
	v_mov_b32_e32 v122, v0
	v_mov_b32_e32 v123, v0
	v_mov_b32_e32 v124, v0
	v_mov_b32_e32 v125, v0
	v_mov_b32_e32 v126, v0
	v_mov_b32_e32 v127, v0
	s_cmp_lg_u64 s[8:9], 0
	s_cbranch_scc1 .Lsp_1073
	s_setprio 1
.Lsp_1073:
.LBB0_1073:
	s_add_u32 s18, s16, 0xfffc0080
	s_addc_u32 s19, s17, -1
	s_add_i32 s48, 0, 0x10000
	s_cmp_eq_u32 s47, 12
	s_cselect_b32 s21, s13, s19
	s_cselect_b32 s20, s12, s18
	s_cselect_b32 s19, s15, s46
	s_cselect_b32 s18, s14, s45
	s_add_i32 s50, 0, 0x14000
	v_add_u32_e32 v152, s48, v138
	v_add_u32_e32 v168, s50, v138
	ds_read_b128 v[140:143], v152
	ds_read_b128 v[144:147], v152 offset:1024
	ds_read_b128 v[148:151], v152 offset:2048
	ds_read_b128 v[152:155], v152 offset:3072
	ds_read_b128 v[156:159], v168
	ds_read_b128 v[160:163], v168 offset:1024
	ds_read_b128 v[164:167], v168 offset:2048
	ds_read_b128 v[168:171], v168 offset:3072
	v_lshl_add_u64 v[198:199], s[16:17], 0, v[136:137]
	s_add_i32 m0, s30, 0xc000
	ds_read_b128 v[172:175], v139
	ds_read_b128 v[176:179], v139 offset:1024
	ds_read_b128 v[180:183], v139 offset:2048
	ds_read_b128 v[184:187], v139 offset:3072
	ds_read_b128 v[188:191], v139 offset:4096
	ds_read_b128 v[192:195], v139 offset:5120
	ds_read_b128 v[206:209], v139 offset:6144
	ds_read_b128 v[210:213], v139 offset:7168
	global_load_lds_dwordx4 v[198:199], off
	v_lshl_add_u64 v[198:199], s[16:17], 0, v[134:135]
	s_add_i32 m0, s30, 0xe000
	s_nop 0
	global_load_lds_dwordx4 v[198:199], off
	s_waitcnt vmcnt(8)
	s_waitcnt lgkmcnt(0)
	s_barrier
	s_waitcnt lgkmcnt(0)
	v_mfma_f32_16x16x32_bf16 v[124:127], v[140:143], v[172:175], v[124:127]
	v_mfma_f32_16x16x32_bf16 v[120:123], v[148:151], v[172:175], v[120:123]
	v_mfma_f32_16x16x32_bf16 v[116:119], v[140:143], v[180:183], v[116:119]
	v_mfma_f32_16x16x32_bf16 v[112:115], v[148:151], v[180:183], v[112:115]
	v_mfma_f32_16x16x32_bf16 v[100:103], v[140:143], v[188:191], v[100:103]
	v_mfma_f32_16x16x32_bf16 v[96:99], v[148:151], v[188:191], v[96:99]
	v_mfma_f32_16x16x32_bf16 v[84:87], v[140:143], v[206:209], v[84:87]
	v_mfma_f32_16x16x32_bf16 v[80:83], v[148:151], v[206:209], v[80:83]
	v_mfma_f32_16x16x32_bf16 v[124:127], v[144:147], v[176:179], v[124:127]
	v_mfma_f32_16x16x32_bf16 v[120:123], v[152:155], v[176:179], v[120:123]
	v_mfma_f32_16x16x32_bf16 v[116:119], v[144:147], v[184:187], v[116:119]
	v_mfma_f32_16x16x32_bf16 v[112:115], v[152:155], v[184:187], v[112:115]
	v_mfma_f32_16x16x32_bf16 v[100:103], v[144:147], v[192:195], v[100:103]
	v_mfma_f32_16x16x32_bf16 v[96:99], v[152:155], v[192:195], v[96:99]
	v_mfma_f32_16x16x32_bf16 v[84:87], v[144:147], v[210:213], v[84:87]
	v_mfma_f32_16x16x32_bf16 v[80:83], v[152:155], v[210:213], v[80:83]
	v_mfma_f32_16x16x32_bf16 v[108:111], v[156:159], v[172:175], v[108:111]
	v_mfma_f32_16x16x32_bf16 v[104:107], v[164:167], v[172:175], v[104:107]
	v_mfma_f32_16x16x32_bf16 v[92:95], v[156:159], v[180:183], v[92:95]
	v_mfma_f32_16x16x32_bf16 v[88:91], v[164:167], v[180:183], v[88:91]
	v_mfma_f32_16x16x32_bf16 v[76:79], v[156:159], v[188:191], v[76:79]
	v_mfma_f32_16x16x32_bf16 v[72:75], v[164:167], v[188:191], v[72:75]
	v_mfma_f32_16x16x32_bf16 v[68:71], v[156:159], v[206:209], v[68:71]
	v_mfma_f32_16x16x32_bf16 v[64:67], v[164:167], v[206:209], v[64:67]
	v_mfma_f32_16x16x32_bf16 v[108:111], v[160:163], v[176:179], v[108:111]
	v_mfma_f32_16x16x32_bf16 v[104:107], v[168:171], v[176:179], v[104:107]
	v_mfma_f32_16x16x32_bf16 v[92:95], v[160:163], v[184:187], v[92:95]
	v_mfma_f32_16x16x32_bf16 v[88:91], v[168:171], v[184:187], v[88:91]
	v_mfma_f32_16x16x32_bf16 v[76:79], v[160:163], v[192:195], v[76:79]
	v_mfma_f32_16x16x32_bf16 v[72:75], v[168:171], v[192:195], v[72:75]
	v_mfma_f32_16x16x32_bf16 v[68:71], v[160:163], v[210:213], v[68:71]
	v_mfma_f32_16x16x32_bf16 v[64:67], v[168:171], v[210:213], v[64:67]
	s_barrier
; #define PG8_STAGE(bufoff, gbase, voff) do { _Pragma("unroll") for (int _i = 0; _i < 2; ++_i) \
;         __builtin_amdgcn_global_load_lds((const unsigned*)((const char*)(gbase) + (voff)[_i]), (LAS unsigned*)(lds + (bufoff) + ldsw + _i * 8192), 16, 0, 0); } while (0)
; #define PG8_LDA(dst, b, h) do { _Pragma("unroll") for (int m = 0; m < 4; ++m) _Pragma("unroll") for (int k = 0; k < 2; ++k) dst[m][k] = *(const LAS bf16x8*)(lds + PG8_SA(b, h) + aoff + m * 2048 + k * 1024); } while (0)
; #define PG8_LDB(dst, b, h) do { _Pragma("unroll") for (int n = 0; n < 2; ++n) _Pragma("unroll") for (int k = 0; k < 2; ++k) dst[n][k] = *(const LAS bf16x8*)(lds + PG8_SB(b, h) + boff + n * 2048 + k * 1024); } while (0)
; #define PG8_MMA(ai, bj, At, Bt) do { __builtin_amdgcn_s_setprio(1); _Pragma("unroll") for (int m = 0; m < 4; ++m) _Pragma("unroll") for (int n = 0; n < 2; ++n) _Pragma("unroll") for (int k = 0; k < 2; ++k) \
;         acc[ai][bj][m][n] = __builtin_amdgcn_mfma_f32_16x16x32_bf16(Bt[n][k], At[m][k], acc[ai][bj][m][n], 0, 0, 0); __builtin_amdgcn_s_setprio(0); } while (0)
; #define PG8_WAIT_V(n) asm volatile("s_waitcnt vmcnt(" #n ")" ::: "memory")
; #define PG8_WAIT_L(n) asm volatile("s_waitcnt lgkmcnt(" #n ")" ::: "memory")
; #define PG8_BAR __builtin_amdgcn_s_barrier()
; #define PG8_SCHED __builtin_amdgcn_sched_barrier(0)
; template <class Epi, class Sched>
; __device__ __forceinline__ void gemm_phase(LAS unsigned char* lds, const GemmP g, const Sched& S, const Epi& E, int tid) {
;     ...
;             PG8_LDA(At, 0, 1); PG8_STAGE(PG8_SB(0, 0), b2, voffB); PG8_STAGE(PG8_SB(0, 1), b2 + hstepB, voffB); PG8_STAGE(PG8_SA(0, 0), a2, voffA);
;             PG8_WAIT_V(8); PG8_WAIT_L(0); PG8_BAR; PG8_MMA(1, 0, At, B0); PG8_MMA(1, 1, At, B1); PG8_BAR; PG8_SCHED;
;             PG8_LDB(B0, 1, 0); PG8_LDB(B1, 1, 1); PG8_SCHED; PG8_LDA(At, 1, 0); PG8_STAGE(PG8_SA(0, 1), a2 + hstepA, voffA);
	s_add_i32 s48, s48, s25
	v_lshl_add_u64 v[198:199], s[18:19], 0, v[196:197]
	s_mov_b32 m0, s48
	ds_read_b128 v[172:175], v139 offset:16384
	ds_read_b128 v[176:179], v139 offset:17408
	ds_read_b128 v[180:183], v139 offset:18432
	ds_read_b128 v[184:187], v139 offset:19456
	ds_read_b128 v[188:191], v139 offset:20480
	ds_read_b128 v[192:195], v139 offset:21504
	ds_read_b128 v[206:209], v139 offset:22528
	ds_read_b128 v[210:213], v139 offset:23552
	global_load_lds_dwordx4 v[198:199], off
	s_add_i32 m0, s48, 0x2000
	s_add_u32 s48, s18, 0x40000
	v_lshl_add_u64 v[200:201], s[18:19], 0, v[128:129]
	s_addc_u32 s49, s19, 0
	s_add_i32 s50, s50, s25
	global_load_lds_dwordx4 v[200:201], off
	v_lshl_add_u64 v[214:215], s[48:49], 0, v[196:197]
	s_mov_b32 m0, s50
	v_lshl_add_u64 v[216:217], s[20:21], 0, v[130:131]
	global_load_lds_dwordx4 v[214:215], off
	v_lshl_add_u64 v[214:215], s[48:49], 0, v[128:129]
	s_add_i32 m0, s50, 0x2000
	s_nop 0
	global_load_lds_dwordx4 v[214:215], off
	v_lshl_add_u64 v[214:215], s[20:21], 0, v[132:133]
	s_mov_b32 m0, s30
	s_nop 0
	global_load_lds_dwordx4 v[214:215], off
	s_mov_b32 m0, s31
	s_nop 0
	global_load_lds_dwordx4 v[216:217], off
	s_waitcnt vmcnt(8)
	s_waitcnt lgkmcnt(0)
	s_barrier
	s_waitcnt lgkmcnt(0)
	v_mfma_f32_16x16x32_bf16 v[60:63], v[140:143], v[172:175], v[60:63]
	v_mfma_f32_16x16x32_bf16 v[56:59], v[148:151], v[172:175], v[56:59]
	v_mfma_f32_16x16x32_bf16 v[52:55], v[140:143], v[180:183], v[52:55]
	v_mfma_f32_16x16x32_bf16 v[48:51], v[148:151], v[180:183], v[48:51]
	v_mfma_f32_16x16x32_bf16 v[36:39], v[140:143], v[188:191], v[36:39]
	v_mfma_f32_16x16x32_bf16 v[32:35], v[148:151], v[188:191], v[32:35]
	v_mfma_f32_16x16x32_bf16 v[20:23], v[140:143], v[206:209], v[20:23]
	v_mfma_f32_16x16x32_bf16 v[16:19], v[148:151], v[206:209], v[16:19]
	v_mfma_f32_16x16x32_bf16 v[60:63], v[144:147], v[176:179], v[60:63]
	v_mfma_f32_16x16x32_bf16 v[56:59], v[152:155], v[176:179], v[56:59]
	v_mfma_f32_16x16x32_bf16 v[52:55], v[144:147], v[184:187], v[52:55]
	v_mfma_f32_16x16x32_bf16 v[48:51], v[152:155], v[184:187], v[48:51]
	v_mfma_f32_16x16x32_bf16 v[36:39], v[144:147], v[192:195], v[36:39]
	v_mfma_f32_16x16x32_bf16 v[32:35], v[152:155], v[192:195], v[32:35]
	v_mfma_f32_16x16x32_bf16 v[20:23], v[144:147], v[210:213], v[20:23]
	v_mfma_f32_16x16x32_bf16 v[16:19], v[152:155], v[210:213], v[16:19]
	v_mfma_f32_16x16x32_bf16 v[44:47], v[156:159], v[172:175], v[44:47]
	v_mfma_f32_16x16x32_bf16 v[40:43], v[164:167], v[172:175], v[40:43]
	v_mfma_f32_16x16x32_bf16 v[28:31], v[156:159], v[180:183], v[28:31]
	v_mfma_f32_16x16x32_bf16 v[24:27], v[164:167], v[180:183], v[24:27]
	v_mfma_f32_16x16x32_bf16 v[12:15], v[156:159], v[188:191], v[12:15]
	v_mfma_f32_16x16x32_bf16 v[8:11], v[164:167], v[188:191], v[8:11]
	v_mfma_f32_16x16x32_bf16 v[4:7], v[156:159], v[206:209], v[4:7]
	v_mfma_f32_16x16x32_bf16 v[0:3], v[164:167], v[206:209], v[0:3]
	v_mfma_f32_16x16x32_bf16 v[44:47], v[160:163], v[176:179], v[44:47]
	v_mfma_f32_16x16x32_bf16 v[40:43], v[168:171], v[176:179], v[40:43]
	v_mfma_f32_16x16x32_bf16 v[28:31], v[160:163], v[184:187], v[28:31]
	v_mfma_f32_16x16x32_bf16 v[24:27], v[168:171], v[184:187], v[24:27]
	v_mfma_f32_16x16x32_bf16 v[12:15], v[160:163], v[192:195], v[12:15]
	v_mfma_f32_16x16x32_bf16 v[8:11], v[168:171], v[192:195], v[8:11]
	v_mfma_f32_16x16x32_bf16 v[4:7], v[160:163], v[210:213], v[4:7]
	v_mfma_f32_16x16x32_bf16 v[0:3], v[168:171], v[210:213], v[0:3]
	s_barrier
	s_add_i32 s48, 0, 0x18000
	s_add_i32 s49, 0, 0x1c000
	v_add_u32_e32 v152, s48, v138
	v_add_u32_e32 v168, s49, v138
	ds_read_b128 v[140:143], v152
	ds_read_b128 v[144:147], v152 offset:1024
	ds_read_b128 v[148:151], v152 offset:2048
	ds_read_b128 v[152:155], v152 offset:3072
	ds_read_b128 v[156:159], v168
	ds_read_b128 v[160:163], v168 offset:1024
	ds_read_b128 v[164:167], v168 offset:2048
	ds_read_b128 v[168:171], v168 offset:3072
	s_add_u32 s20, s20, 0x40000
	s_addc_u32 s21, s21, 0
	s_mov_b32 m0, s34
	v_lshl_add_u64 v[220:221], s[20:21], 0, v[132:133]
	ds_read_b128 v[172:175], v139 offset:32768
	ds_read_b128 v[176:179], v139 offset:33792
	ds_read_b128 v[180:183], v139 offset:34816
	ds_read_b128 v[184:187], v139 offset:35840
	ds_read_b128 v[188:191], v139 offset:36864
	ds_read_b128 v[192:195], v139 offset:37888
	ds_read_b128 v[206:209], v139 offset:38912
	ds_read_b128 v[210:213], v139 offset:39936
	global_load_lds_dwordx4 v[220:221], off
	v_lshl_add_u64 v[220:221], s[20:21], 0, v[130:131]
	s_mov_b32 m0, s35
	s_nop 0
	global_load_lds_dwordx4 v[220:221], off
	s_waitcnt vmcnt(8)
	s_waitcnt lgkmcnt(0)
	s_barrier
; #define PG8_STAGE(bufoff, gbase, voff) do { _Pragma("unroll") for (int _i = 0; _i < 2; ++_i) \
;         __builtin_amdgcn_global_load_lds((const unsigned*)((const char*)(gbase) + (voff)[_i]), (LAS unsigned*)(lds + (bufoff) + ldsw + _i * 8192), 16, 0, 0); } while (0)
; #define PG8_LDA(dst, b, h) do { _Pragma("unroll") for (int m = 0; m < 4; ++m) _Pragma("unroll") for (int k = 0; k < 2; ++k) dst[m][k] = *(const LAS bf16x8*)(lds + PG8_SA(b, h) + aoff + m * 2048 + k * 1024); } while (0)
; #define PG8_MMA(ai, bj, At, Bt) do { __builtin_amdgcn_s_setprio(1); _Pragma("unroll") for (int m = 0; m < 4; ++m) _Pragma("unroll") for (int n = 0; n < 2; ++n) _Pragma("unroll") for (int k = 0; k < 2; ++k) \
;         acc[ai][bj][m][n] = __builtin_amdgcn_mfma_f32_16x16x32_bf16(Bt[n][k], At[m][k], acc[ai][bj][m][n], 0, 0, 0); __builtin_amdgcn_s_setprio(0); } while (0)
; #define PG8_WAIT_V(n) asm volatile("s_waitcnt vmcnt(" #n ")" ::: "memory")
; #define PG8_WAIT_L(n) asm volatile("s_waitcnt lgkmcnt(" #n ")" ::: "memory")
; #define PG8_BAR __builtin_amdgcn_s_barrier()
; #define PG8_SCHED __builtin_amdgcn_sched_barrier(0)
; template <class Epi, class Sched>
; __device__ __forceinline__ void gemm_phase(LAS unsigned char* lds, const GemmP g, const Sched& S, const Epi& E, int tid) {
;     ...
;             PG8_WAIT_V(8); PG8_WAIT_L(0); PG8_BAR; PG8_MMA(0, 0, At, B0); PG8_MMA(0, 1, At, B1); PG8_BAR; PG8_SCHED;
;             PG8_LDA(At, 1, 1); PG8_STAGE(PG8_SB(1, 0), b3, voffB); PG8_STAGE(PG8_SB(1, 1), b3 + hstepB, voffB); PG8_STAGE(PG8_SA(1, 0), a3, voffA);
;             PG8_WAIT_V(8); PG8_WAIT_L(0); PG8_BAR; PG8_MMA(1, 0, At, B0); PG8_MMA(1, 1, At, B1); PG8_BAR; PG8_SCHED;
;         }
;         if (wr == 0) PG8_BAR;
	s_waitcnt lgkmcnt(0)
	v_mfma_f32_16x16x32_bf16 v[124:127], v[140:143], v[172:175], v[124:127]
	v_mfma_f32_16x16x32_bf16 v[120:123], v[148:151], v[172:175], v[120:123]
	v_mfma_f32_16x16x32_bf16 v[116:119], v[140:143], v[180:183], v[116:119]
	v_mfma_f32_16x16x32_bf16 v[112:115], v[148:151], v[180:183], v[112:115]
	v_mfma_f32_16x16x32_bf16 v[100:103], v[140:143], v[188:191], v[100:103]
	v_mfma_f32_16x16x32_bf16 v[96:99], v[148:151], v[188:191], v[96:99]
	v_mfma_f32_16x16x32_bf16 v[84:87], v[140:143], v[206:209], v[84:87]
	v_mfma_f32_16x16x32_bf16 v[80:83], v[148:151], v[206:209], v[80:83]
	v_mfma_f32_16x16x32_bf16 v[124:127], v[144:147], v[176:179], v[124:127]
	v_mfma_f32_16x16x32_bf16 v[120:123], v[152:155], v[176:179], v[120:123]
	v_mfma_f32_16x16x32_bf16 v[116:119], v[144:147], v[184:187], v[116:119]
	v_mfma_f32_16x16x32_bf16 v[112:115], v[152:155], v[184:187], v[112:115]
	v_mfma_f32_16x16x32_bf16 v[100:103], v[144:147], v[192:195], v[100:103]
	v_mfma_f32_16x16x32_bf16 v[96:99], v[152:155], v[192:195], v[96:99]
	v_mfma_f32_16x16x32_bf16 v[84:87], v[144:147], v[210:213], v[84:87]
	v_mfma_f32_16x16x32_bf16 v[80:83], v[152:155], v[210:213], v[80:83]
	v_mfma_f32_16x16x32_bf16 v[108:111], v[156:159], v[172:175], v[108:111]
	v_mfma_f32_16x16x32_bf16 v[104:107], v[164:167], v[172:175], v[104:107]
	v_mfma_f32_16x16x32_bf16 v[92:95], v[156:159], v[180:183], v[92:95]
	v_mfma_f32_16x16x32_bf16 v[88:91], v[164:167], v[180:183], v[88:91]
	v_mfma_f32_16x16x32_bf16 v[76:79], v[156:159], v[188:191], v[76:79]
	v_mfma_f32_16x16x32_bf16 v[72:75], v[164:167], v[188:191], v[72:75]
	v_mfma_f32_16x16x32_bf16 v[68:71], v[156:159], v[206:209], v[68:71]
	v_mfma_f32_16x16x32_bf16 v[64:67], v[164:167], v[206:209], v[64:67]
	v_mfma_f32_16x16x32_bf16 v[108:111], v[160:163], v[176:179], v[108:111]
	v_mfma_f32_16x16x32_bf16 v[104:107], v[168:171], v[176:179], v[104:107]
	v_mfma_f32_16x16x32_bf16 v[92:95], v[160:163], v[184:187], v[92:95]
	v_mfma_f32_16x16x32_bf16 v[88:91], v[168:171], v[184:187], v[88:91]
	v_mfma_f32_16x16x32_bf16 v[76:79], v[160:163], v[192:195], v[76:79]
	v_mfma_f32_16x16x32_bf16 v[72:75], v[168:171], v[192:195], v[72:75]
	v_mfma_f32_16x16x32_bf16 v[68:71], v[160:163], v[210:213], v[68:71]
	v_mfma_f32_16x16x32_bf16 v[64:67], v[168:171], v[210:213], v[64:67]
	s_barrier
	s_add_i32 s20, s48, s25
	v_lshl_add_u64 v[198:199], v[198:199], 0, s[80:81]
	s_mov_b32 m0, s20
	ds_read_b128 v[172:175], v139 offset:49152
	ds_read_b128 v[176:179], v139 offset:50176
	ds_read_b128 v[180:183], v139 offset:51200
	ds_read_b128 v[184:187], v139 offset:52224
	ds_read_b128 v[188:191], v139 offset:53248
	ds_read_b128 v[192:195], v139 offset:54272
	ds_read_b128 v[206:209], v139 offset:55296
	ds_read_b128 v[210:213], v139 offset:56320
	global_load_lds_dwordx4 v[198:199], off
	s_add_i32 m0, s20, 0x2000
	s_add_u32 s18, s18, 0x40080
	v_lshl_add_u64 v[198:199], v[200:201], 0, s[80:81]
	s_addc_u32 s19, s19, 0
	s_add_i32 s20, s49, s25
	global_load_lds_dwordx4 v[198:199], off
	v_lshl_add_u64 v[198:199], s[18:19], 0, v[196:197]
	s_mov_b32 m0, s20
	s_nop 0
	global_load_lds_dwordx4 v[198:199], off
	v_lshl_add_u64 v[198:199], s[18:19], 0, v[128:129]
	s_add_i32 m0, s20, 0x2000
	s_nop 0
	global_load_lds_dwordx4 v[198:199], off
	v_lshl_add_u64 v[198:199], v[214:215], 0, s[80:81]
	s_mov_b32 m0, s38
	s_nop 0
	global_load_lds_dwordx4 v[198:199], off
	v_lshl_add_u64 v[198:199], v[216:217], 0, s[80:81]
	s_mov_b32 m0, s39
	s_nop 0
	global_load_lds_dwordx4 v[198:199], off
	s_waitcnt vmcnt(8)
	s_waitcnt lgkmcnt(0)
	s_barrier
	s_waitcnt lgkmcnt(0)
	v_mfma_f32_16x16x32_bf16 v[60:63], v[140:143], v[172:175], v[60:63]
	v_mfma_f32_16x16x32_bf16 v[56:59], v[148:151], v[172:175], v[56:59]
	v_mfma_f32_16x16x32_bf16 v[52:55], v[140:143], v[180:183], v[52:55]
	v_mfma_f32_16x16x32_bf16 v[48:51], v[148:151], v[180:183], v[48:51]
	v_mfma_f32_16x16x32_bf16 v[36:39], v[140:143], v[188:191], v[36:39]
	v_mfma_f32_16x16x32_bf16 v[32:35], v[148:151], v[188:191], v[32:35]
	v_mfma_f32_16x16x32_bf16 v[20:23], v[140:143], v[206:209], v[20:23]
	v_mfma_f32_16x16x32_bf16 v[16:19], v[148:151], v[206:209], v[16:19]
	v_mfma_f32_16x16x32_bf16 v[60:63], v[144:147], v[176:179], v[60:63]
	v_mfma_f32_16x16x32_bf16 v[56:59], v[152:155], v[176:179], v[56:59]
	v_mfma_f32_16x16x32_bf16 v[52:55], v[144:147], v[184:187], v[52:55]
	v_mfma_f32_16x16x32_bf16 v[48:51], v[152:155], v[184:187], v[48:51]
	v_mfma_f32_16x16x32_bf16 v[36:39], v[144:147], v[192:195], v[36:39]
	v_mfma_f32_16x16x32_bf16 v[32:35], v[152:155], v[192:195], v[32:35]
	v_mfma_f32_16x16x32_bf16 v[20:23], v[144:147], v[210:213], v[20:23]
	v_mfma_f32_16x16x32_bf16 v[16:19], v[152:155], v[210:213], v[16:19]
	v_mfma_f32_16x16x32_bf16 v[44:47], v[156:159], v[172:175], v[44:47]
	v_mfma_f32_16x16x32_bf16 v[40:43], v[164:167], v[172:175], v[40:43]
	v_mfma_f32_16x16x32_bf16 v[28:31], v[156:159], v[180:183], v[28:31]
	v_mfma_f32_16x16x32_bf16 v[24:27], v[164:167], v[180:183], v[24:27]
	v_mfma_f32_16x16x32_bf16 v[12:15], v[156:159], v[188:191], v[12:15]
	v_mfma_f32_16x16x32_bf16 v[8:11], v[164:167], v[188:191], v[8:11]
	v_mfma_f32_16x16x32_bf16 v[4:7], v[156:159], v[206:209], v[4:7]
	v_mfma_f32_16x16x32_bf16 v[0:3], v[164:167], v[206:209], v[0:3]
	v_mfma_f32_16x16x32_bf16 v[44:47], v[160:163], v[176:179], v[44:47]
	v_mfma_f32_16x16x32_bf16 v[40:43], v[168:171], v[176:179], v[40:43]
	v_mfma_f32_16x16x32_bf16 v[28:31], v[160:163], v[184:187], v[28:31]
	v_mfma_f32_16x16x32_bf16 v[24:27], v[168:171], v[184:187], v[24:27]
	v_mfma_f32_16x16x32_bf16 v[12:15], v[160:163], v[192:195], v[12:15]
	v_mfma_f32_16x16x32_bf16 v[8:11], v[168:171], v[192:195], v[8:11]
	v_mfma_f32_16x16x32_bf16 v[4:7], v[160:163], v[210:213], v[4:7]
	v_mfma_f32_16x16x32_bf16 v[0:3], v[168:171], v[210:213], v[0:3]
	s_barrier
	s_add_i32 s47, s47, 2
	s_add_u32 s45, s45, 0x100
	s_addc_u32 s46, s46, 0
	s_add_u32 s16, s16, 0x100
	s_addc_u32 s17, s17, 0
	s_cmp_gt_u32 s47, 13
	s_cbranch_scc0 .LBB0_1073
	s_setprio 0
	s_and_b64 vcc, exec, s[8:9]
	s_cbranch_vccz .LBB0_1076
	s_barrier

; #define PG8_STAGE(bufoff, gbase, voff) do { _Pragma("unroll") for (int _i = 0; _i < 2; ++_i) \
;         __builtin_amdgcn_global_load_lds((const unsigned*)((const char*)(gbase) + (voff)[_i]), (LAS unsigned*)(lds + (bufoff) + ldsw + _i * 8192), 16, 0, 0); } while (0)
; #define PG8_LDA(dst, b, h) do { _Pragma("unroll") for (int m = 0; m < 4; ++m) _Pragma("unroll") for (int k = 0; k < 2; ++k) dst[m][k] = *(const LAS bf16x8*)(lds + PG8_SA(b, h) + aoff + m * 2048 + k * 1024); } while (0)
; #define PG8_LDB(dst, b, h) do { _Pragma("unroll") for (int n = 0; n < 2; ++n) _Pragma("unroll") for (int k = 0; k < 2; ++k) dst[n][k] = *(const LAS bf16x8*)(lds + PG8_SB(b, h) + boff + n * 2048 + k * 1024); } while (0)
; #define PG8_SCHED __builtin_amdgcn_sched_barrier(0)
; template <class Epi, class Sched>
; __device__ __forceinline__ void gemm_phase(LAS unsigned char* lds, const GemmP g, const Sched& S, const Epi& E, int tid) {
;     ...
;         for (int t = 0; t < nt; t += 2) {
;             const bool last = (t == nt - 2);
;             const char* a1 = cA + (size_t)(t + 1) * kstep;
;             const char* a2 = last ? nA : cA + (size_t)(t + 2) * kstep; const char* b2 = last ? nB : cB + (size_t)(t + 2) * kstep;
;             const char* a3 = a2 + kstep; const char* b3 = b2 + kstep;
;             PG8_LDB(B0, 0, 0); PG8_LDB(B1, 0, 1); PG8_SCHED; PG8_LDA(At, 0, 0); PG8_STAGE(PG8_SA(1, 1), a1 + hstepA, voffA);
;     ...
; #pragma unroll
;         for (int a = 0; a < 2; ++a)
; #pragma unroll
;             for (int b = 0; b < 2; ++b)
; #pragma unroll
;                 for (int m = 0; m < 4; ++m)
; #pragma unroll
;                     for (int n = 0; n < 2; ++n) acc[a][b][m][n] = (f32x4){0.f, 0.f, 0.f, 0.f};
;         cur = nxt; cA = nA; cB = nB; ++ui;
.LBB0_1162:
	s_add_u32 s12, s8, 0x100
	s_addc_u32 s13, s9, 0
	s_add_u32 s6, s6, 0x40080
	v_mov_b32_e32 v0, 0
	s_addc_u32 s7, s7, 0
	s_mov_b32 s14, -2
	s_waitcnt lgkmcnt(0)
	v_mov_b32_e32 v1, v0
	v_mov_b32_e32 v2, v0
	v_mov_b32_e32 v3, v0
	v_mov_b32_e32 v4, v0
	v_mov_b32_e32 v5, v0
	v_mov_b32_e32 v6, v0
	v_mov_b32_e32 v7, v0
	v_mov_b32_e32 v8, v0
	v_mov_b32_e32 v9, v0
	v_mov_b32_e32 v10, v0
	v_mov_b32_e32 v11, v0
	v_mov_b32_e32 v12, v0
	v_mov_b32_e32 v13, v0
	v_mov_b32_e32 v14, v0
	v_mov_b32_e32 v15, v0
	v_mov_b32_e32 v16, v0
	v_mov_b32_e32 v17, v0
	v_mov_b32_e32 v18, v0
	v_mov_b32_e32 v19, v0
	v_mov_b32_e32 v20, v0
	v_mov_b32_e32 v21, v0
	v_mov_b32_e32 v22, v0
	v_mov_b32_e32 v23, v0
	v_mov_b32_e32 v24, v0
	v_mov_b32_e32 v25, v0
	v_mov_b32_e32 v26, v0
	v_mov_b32_e32 v27, v0
	v_mov_b32_e32 v28, v0
	v_mov_b32_e32 v29, v0
	v_mov_b32_e32 v30, v0
	v_mov_b32_e32 v31, v0
	v_mov_b32_e32 v56, v0
	v_mov_b32_e32 v57, v0
	v_mov_b32_e32 v58, v0
	v_mov_b32_e32 v59, v0
	v_mov_b32_e32 v64, v0
	v_mov_b32_e32 v65, v0
	v_mov_b32_e32 v66, v0
	v_mov_b32_e32 v67, v0
	v_mov_b32_e32 v72, v0
	v_mov_b32_e32 v73, v0
	v_mov_b32_e32 v74, v0
	v_mov_b32_e32 v75, v0
	v_mov_b32_e32 v76, v0
	v_mov_b32_e32 v77, v0
	v_mov_b32_e32 v78, v0
	v_mov_b32_e32 v79, v0
	v_mov_b32_e32 v80, v0
	v_mov_b32_e32 v81, v0
	v_mov_b32_e32 v82, v0
	v_mov_b32_e32 v83, v0
	v_mov_b32_e32 v84, v0
	v_mov_b32_e32 v85, v0
	v_mov_b32_e32 v86, v0
	v_mov_b32_e32 v87, v0
	v_mov_b32_e32 v88, v0
	v_mov_b32_e32 v89, v0
	v_mov_b32_e32 v90, v0
	v_mov_b32_e32 v91, v0
	v_mov_b32_e32 v92, v0
	v_mov_b32_e32 v93, v0
	v_mov_b32_e32 v94, v0
	v_mov_b32_e32 v95, v0
	v_mov_b32_e32 v32, v0
	v_mov_b32_e32 v33, v0
	v_mov_b32_e32 v34, v0
	v_mov_b32_e32 v35, v0
	v_mov_b32_e32 v36, v0
	v_mov_b32_e32 v37, v0
	v_mov_b32_e32 v38, v0
	v_mov_b32_e32 v39, v0
	v_mov_b32_e32 v40, v0
	v_mov_b32_e32 v41, v0
	v_mov_b32_e32 v42, v0
	v_mov_b32_e32 v43, v0
	v_mov_b32_e32 v44, v0
	v_mov_b32_e32 v45, v0
	v_mov_b32_e32 v46, v0
	v_mov_b32_e32 v47, v0
	v_mov_b32_e32 v48, v0
	v_mov_b32_e32 v49, v0
	v_mov_b32_e32 v50, v0
	v_mov_b32_e32 v51, v0
	v_mov_b32_e32 v52, v0
	v_mov_b32_e32 v53, v0
	v_mov_b32_e32 v54, v0
	v_mov_b32_e32 v55, v0
	v_mov_b32_e32 v60, v0
	v_mov_b32_e32 v61, v0
	v_mov_b32_e32 v62, v0
	v_mov_b32_e32 v63, v0
	v_mov_b32_e32 v68, v0
	v_mov_b32_e32 v69, v0
	v_mov_b32_e32 v70, v0
	v_mov_b32_e32 v71, v0
	v_mov_b32_e32 v96, v0
	v_mov_b32_e32 v97, v0
	v_mov_b32_e32 v98, v0
	v_mov_b32_e32 v99, v0
	v_mov_b32_e32 v100, v0
	v_mov_b32_e32 v101, v0
	v_mov_b32_e32 v102, v0
	v_mov_b32_e32 v103, v0
	v_mov_b32_e32 v104, v0
	v_mov_b32_e32 v105, v0
	v_mov_b32_e32 v106, v0
	v_mov_b32_e32 v107, v0
	v_mov_b32_e32 v108, v0
	v_mov_b32_e32 v109, v0
	v_mov_b32_e32 v110, v0
	v_mov_b32_e32 v111, v0
	v_mov_b32_e32 v112, v0
	v_mov_b32_e32 v113, v0
	v_mov_b32_e32 v114, v0
	v_mov_b32_e32 v115, v0
	v_mov_b32_e32 v116, v0
	v_mov_b32_e32 v117, v0
	v_mov_b32_e32 v118, v0
	v_mov_b32_e32 v119, v0
	v_mov_b32_e32 v128, v0
	v_mov_b32_e32 v129, v0
	v_mov_b32_e32 v130, v0
	v_mov_b32_e32 v131, v0
	v_mov_b32_e32 v120, v0
	v_mov_b32_e32 v121, v0
	v_mov_b32_e32 v122, v0
	v_mov_b32_e32 v123, v0
	s_sub_i32 s32, s41, s4
	s_bfe_u32 s98, s32, 0x10006
	s_bfe_u32 s32, s32, 0x10007
	s_cmp_lg_u64 s[2:3], 0
	s_cselect_b32 s99, 1, 0
	s_xor_b32 s98, s98, s99
	s_or_b32 s99, s98, s32
	s_xor_b32 s32, s32, 1
	s_or_b32 s98, s98, s32
	s_cmp_eq_u32 s40, 0x7fffffff
	s_cselect_b32 s32, 0, s99
	s_cselect_b32 s98, 0, s98
	s_and_b32 s99, s32, s98
	s_cmp_lg_u64 s[78:79], 0
	s_cbranch_scc1 .Lsp_1163
	s_setprio 1
.Lsp_1163:
.LBB0_1163:
	s_add_u32 s8, s6, 0xfffc0080
	s_addc_u32 s9, s7, -1
	s_add_i32 s15, 0, 0x10000
	s_cmp_eq_u32 s14, 12
	s_cselect_b32 s11, s93, s9
	s_cselect_b32 s10, s92, s8
	s_cselect_b32 s9, s95, s13
	s_cselect_b32 s8, s94, s12
	s_add_i32 s18, 0, 0x14000
	v_add_u32_e32 v140, s15, v214
	v_add_u32_e32 v156, s18, v214
	s_cmp_lg_u32 s99, 0
	s_cbranch_scc1 .Lskr_co_1
	ds_read_b128 v[124:127], v140
	ds_read_b128 v[132:135], v140 offset:1024
	ds_read_b128 v[136:139], v140 offset:2048
	ds_read_b128 v[140:143], v140 offset:3072
	ds_read_b128 v[144:147], v156
	ds_read_b128 v[148:151], v156 offset:1024
	ds_read_b128 v[152:155], v156 offset:2048
	ds_read_b128 v[156:159], v156 offset:3072

; #define PG8_STAGE(bufoff, gbase, voff) do { _Pragma("unroll") for (int _i = 0; _i < 2; ++_i) \
;         __builtin_amdgcn_global_load_lds((const unsigned*)((const char*)(gbase) + (voff)[_i]), (LAS unsigned*)(lds + (bufoff) + ldsw + _i * 8192), 16, 0, 0); } while (0)
; #define PG8_LDA(dst, b, h) do { _Pragma("unroll") for (int m = 0; m < 4; ++m) _Pragma("unroll") for (int k = 0; k < 2; ++k) dst[m][k] = *(const LAS bf16x8*)(lds + PG8_SA(b, h) + aoff + m * 2048 + k * 1024); } while (0)
; #define PG8_LDB(dst, b, h) do { _Pragma("unroll") for (int n = 0; n < 2; ++n) _Pragma("unroll") for (int k = 0; k < 2; ++k) dst[n][k] = *(const LAS bf16x8*)(lds + PG8_SB(b, h) + boff + n * 2048 + k * 1024); } while (0)
; #define PG8_MMA(ai, bj, At, Bt) do { __builtin_amdgcn_s_setprio(1); _Pragma("unroll") for (int m = 0; m < 4; ++m) _Pragma("unroll") for (int n = 0; n < 2; ++n) _Pragma("unroll") for (int k = 0; k < 2; ++k) \
;         acc[ai][bj][m][n] = __builtin_amdgcn_mfma_f32_16x16x32_bf16(Bt[n][k], At[m][k], acc[ai][bj][m][n], 0, 0, 0); __builtin_amdgcn_s_setprio(0); } while (0)
; #define PG8_WAIT_V(n) asm volatile("s_waitcnt vmcnt(" #n ")" ::: "memory")
; #define PG8_WAIT_L(n) asm volatile("s_waitcnt lgkmcnt(" #n ")" ::: "memory")
; #define PG8_BAR __builtin_amdgcn_s_barrier()
; #define PG8_SCHED __builtin_amdgcn_sched_barrier(0)
; template <class Epi, class Sched>
; __device__ __forceinline__ void gemm_phase(LAS unsigned char* lds, const GemmP g, const Sched& S, const Epi& E, int tid) {
;     ...
;             PG8_WAIT_V(8); PG8_WAIT_L(0); PG8_BAR; PG8_MMA(0, 0, At, B0); PG8_MMA(0, 1, At, B1); PG8_BAR; PG8_SCHED;
;             PG8_LDA(At, 0, 1); PG8_STAGE(PG8_SB(0, 0), b2, voffB); PG8_STAGE(PG8_SB(0, 1), b2 + hstepB, voffB); PG8_STAGE(PG8_SA(0, 0), a2, voffA);
;             PG8_WAIT_V(8); PG8_WAIT_L(0); PG8_BAR; PG8_MMA(1, 0, At, B0); PG8_MMA(1, 1, At, B1); PG8_BAR; PG8_SCHED;
;             PG8_LDB(B0, 1, 0); PG8_LDB(B1, 1, 1); PG8_SCHED; PG8_LDA(At, 1, 0); PG8_STAGE(PG8_SA(0, 1), a2 + hstepA, voffA);
.Lfirstit_4:
	s_waitcnt lgkmcnt(0)
	s_barrier
	s_cmp_lg_u32 s32, 0
	s_cbranch_scc1 .Lsk_co_1
	s_waitcnt lgkmcnt(0)
	v_mfma_f32_16x16x32_bf16 v[120:123], v[124:127], v[160:163], v[120:123]
	v_mfma_f32_16x16x32_bf16 v[128:131], v[136:139], v[160:163], v[128:131]
	v_mfma_f32_16x16x32_bf16 v[116:119], v[124:127], v[168:171], v[116:119]
	v_mfma_f32_16x16x32_bf16 v[112:115], v[136:139], v[168:171], v[112:115]
	v_mfma_f32_16x16x32_bf16 v[108:111], v[124:127], v[176:179], v[108:111]
	v_mfma_f32_16x16x32_bf16 v[104:107], v[136:139], v[176:179], v[104:107]
	v_mfma_f32_16x16x32_bf16 v[100:103], v[124:127], v[184:187], v[100:103]
	v_mfma_f32_16x16x32_bf16 v[96:99], v[136:139], v[184:187], v[96:99]
	v_mfma_f32_16x16x32_bf16 v[120:123], v[132:135], v[164:167], v[120:123]
	v_mfma_f32_16x16x32_bf16 v[128:131], v[140:143], v[164:167], v[128:131]
	v_mfma_f32_16x16x32_bf16 v[116:119], v[132:135], v[172:175], v[116:119]
	v_mfma_f32_16x16x32_bf16 v[112:115], v[140:143], v[172:175], v[112:115]
	v_mfma_f32_16x16x32_bf16 v[108:111], v[132:135], v[180:183], v[108:111]
	v_mfma_f32_16x16x32_bf16 v[104:107], v[140:143], v[180:183], v[104:107]
	v_mfma_f32_16x16x32_bf16 v[100:103], v[132:135], v[210:213], v[100:103]
	v_mfma_f32_16x16x32_bf16 v[96:99], v[140:143], v[210:213], v[96:99]
	v_mfma_f32_16x16x32_bf16 v[68:71], v[144:147], v[160:163], v[68:71]
	v_mfma_f32_16x16x32_bf16 v[60:63], v[152:155], v[160:163], v[60:63]
	v_mfma_f32_16x16x32_bf16 v[52:55], v[144:147], v[168:171], v[52:55]
	v_mfma_f32_16x16x32_bf16 v[48:51], v[152:155], v[168:171], v[48:51]
	v_mfma_f32_16x16x32_bf16 v[44:47], v[144:147], v[176:179], v[44:47]
	v_mfma_f32_16x16x32_bf16 v[40:43], v[152:155], v[176:179], v[40:43]
	v_mfma_f32_16x16x32_bf16 v[36:39], v[144:147], v[184:187], v[36:39]
	v_mfma_f32_16x16x32_bf16 v[32:35], v[152:155], v[184:187], v[32:35]
	v_mfma_f32_16x16x32_bf16 v[68:71], v[148:151], v[164:167], v[68:71]
	v_mfma_f32_16x16x32_bf16 v[60:63], v[156:159], v[164:167], v[60:63]
	v_mfma_f32_16x16x32_bf16 v[52:55], v[148:151], v[172:175], v[52:55]
	v_mfma_f32_16x16x32_bf16 v[48:51], v[156:159], v[172:175], v[48:51]
	v_mfma_f32_16x16x32_bf16 v[44:47], v[148:151], v[180:183], v[44:47]
	v_mfma_f32_16x16x32_bf16 v[40:43], v[156:159], v[180:183], v[40:43]
	v_mfma_f32_16x16x32_bf16 v[36:39], v[148:151], v[210:213], v[36:39]
	v_mfma_f32_16x16x32_bf16 v[32:35], v[156:159], v[210:213], v[32:35]
.Lsk_co_1:
	s_barrier
	s_add_i32 s15, s15, s62
	v_lshl_add_u64 v[198:199], s[8:9], 0, v[190:191]
	s_mov_b32 m0, s15
	s_cmp_lg_u32 s98, 0
	s_cbranch_scc1 .Lskr_co_3
	ds_read_b128 v[160:163], v215 offset:16384
	ds_read_b128 v[164:167], v215 offset:17408
	ds_read_b128 v[168:171], v215 offset:18432
	ds_read_b128 v[172:175], v215 offset:19456
	ds_read_b128 v[176:179], v215 offset:20480
	ds_read_b128 v[180:183], v215 offset:21504
	ds_read_b128 v[184:187], v215 offset:22528
	ds_read_b128 v[210:213], v215 offset:23552
.Lskr_co_3:
	global_load_lds_dwordx4 v[198:199], off
	s_add_i32 m0, s15, 0x2000
	s_add_u32 s16, s8, 0x40000
	v_lshl_add_u64 v[200:201], s[8:9], 0, v[194:195]
	s_addc_u32 s17, s9, 0
	s_add_i32 s15, s18, s62
	global_load_lds_dwordx4 v[200:201], off
	v_lshl_add_u64 v[216:217], s[16:17], 0, v[190:191]
	s_mov_b32 m0, s15
	v_lshl_add_u64 v[220:221], s[10:11], 0, v[192:193]
	global_load_lds_dwordx4 v[216:217], off
	v_lshl_add_u64 v[216:217], s[16:17], 0, v[194:195]
	s_add_i32 m0, s15, 0x2000
	s_nop 0
	global_load_lds_dwordx4 v[216:217], off
	v_lshl_add_u64 v[216:217], s[10:11], 0, v[188:189]
	s_mov_b32 m0, s63
	s_nop 0
	global_load_lds_dwordx4 v[216:217], off
	s_mov_b32 m0, s68
	s_nop 0
	global_load_lds_dwordx4 v[220:221], off
	s_waitcnt vmcnt(8)
	s_waitcnt lgkmcnt(0)
	s_barrier
	s_cmp_lg_u32 s98, 0
	s_cbranch_scc1 .Lsk_co_2
	s_waitcnt lgkmcnt(0)
	v_mfma_f32_16x16x32_bf16 v[92:95], v[124:127], v[160:163], v[92:95]
	v_mfma_f32_16x16x32_bf16 v[88:91], v[136:139], v[160:163], v[88:91]
	v_mfma_f32_16x16x32_bf16 v[84:87], v[124:127], v[168:171], v[84:87]
	v_mfma_f32_16x16x32_bf16 v[80:83], v[136:139], v[168:171], v[80:83]
	v_mfma_f32_16x16x32_bf16 v[76:79], v[124:127], v[176:179], v[76:79]
	v_mfma_f32_16x16x32_bf16 v[72:75], v[136:139], v[176:179], v[72:75]
	v_mfma_f32_16x16x32_bf16 v[64:67], v[124:127], v[184:187], v[64:67]
	v_mfma_f32_16x16x32_bf16 v[56:59], v[136:139], v[184:187], v[56:59]
	v_mfma_f32_16x16x32_bf16 v[92:95], v[132:135], v[164:167], v[92:95]
	v_mfma_f32_16x16x32_bf16 v[88:91], v[140:143], v[164:167], v[88:91]
	v_mfma_f32_16x16x32_bf16 v[84:87], v[132:135], v[172:175], v[84:87]
	v_mfma_f32_16x16x32_bf16 v[80:83], v[140:143], v[172:175], v[80:83]
	v_mfma_f32_16x16x32_bf16 v[76:79], v[132:135], v[180:183], v[76:79]
	v_mfma_f32_16x16x32_bf16 v[72:75], v[140:143], v[180:183], v[72:75]
	v_mfma_f32_16x16x32_bf16 v[64:67], v[132:135], v[210:213], v[64:67]
	v_mfma_f32_16x16x32_bf16 v[56:59], v[140:143], v[210:213], v[56:59]
	v_mfma_f32_16x16x32_bf16 v[28:31], v[144:147], v[160:163], v[28:31]
	v_mfma_f32_16x16x32_bf16 v[24:27], v[152:155], v[160:163], v[24:27]
	v_mfma_f32_16x16x32_bf16 v[20:23], v[144:147], v[168:171], v[20:23]
	v_mfma_f32_16x16x32_bf16 v[16:19], v[152:155], v[168:171], v[16:19]
	v_mfma_f32_16x16x32_bf16 v[12:15], v[144:147], v[176:179], v[12:15]
	v_mfma_f32_16x16x32_bf16 v[8:11], v[152:155], v[176:179], v[8:11]
	v_mfma_f32_16x16x32_bf16 v[4:7], v[144:147], v[184:187], v[4:7]
	v_mfma_f32_16x16x32_bf16 v[0:3], v[152:155], v[184:187], v[0:3]
	v_mfma_f32_16x16x32_bf16 v[28:31], v[148:151], v[164:167], v[28:31]
	v_mfma_f32_16x16x32_bf16 v[24:27], v[156:159], v[164:167], v[24:27]
	v_mfma_f32_16x16x32_bf16 v[20:23], v[148:151], v[172:175], v[20:23]
	v_mfma_f32_16x16x32_bf16 v[16:19], v[156:159], v[172:175], v[16:19]
	v_mfma_f32_16x16x32_bf16 v[12:15], v[148:151], v[180:183], v[12:15]
	v_mfma_f32_16x16x32_bf16 v[8:11], v[156:159], v[180:183], v[8:11]
	v_mfma_f32_16x16x32_bf16 v[4:7], v[148:151], v[210:213], v[4:7]
	v_mfma_f32_16x16x32_bf16 v[0:3], v[156:159], v[210:213], v[0:3]
.Lsk_co_2:
	s_barrier
	s_add_i32 s15, 0, 0x18000
	s_add_i32 s16, 0, 0x1c000
	v_add_u32_e32 v140, s15, v214
	v_add_u32_e32 v156, s16, v214
	s_cmp_lg_u32 s99, 0
	s_cbranch_scc1 .Lskr_co_4
	ds_read_b128 v[124:127], v140
	ds_read_b128 v[132:135], v140 offset:1024
	ds_read_b128 v[136:139], v140 offset:2048
	ds_read_b128 v[140:143], v140 offset:3072
	ds_read_b128 v[144:147], v156
	ds_read_b128 v[148:151], v156 offset:1024
	ds_read_b128 v[152:155], v156 offset:2048
	ds_read_b128 v[156:159], v156 offset:3072

; #define PG8_STAGE(bufoff, gbase, voff) do { _Pragma("unroll") for (int _i = 0; _i < 2; ++_i) \
;         __builtin_amdgcn_global_load_lds((const unsigned*)((const char*)(gbase) + (voff)[_i]), (LAS unsigned*)(lds + (bufoff) + ldsw + _i * 8192), 16, 0, 0); } while (0)
; #define PG8_LDA(dst, b, h) do { _Pragma("unroll") for (int m = 0; m < 4; ++m) _Pragma("unroll") for (int k = 0; k < 2; ++k) dst[m][k] = *(const LAS bf16x8*)(lds + PG8_SA(b, h) + aoff + m * 2048 + k * 1024); } while (0)
; #define PG8_LDB(dst, b, h) do { _Pragma("unroll") for (int n = 0; n < 2; ++n) _Pragma("unroll") for (int k = 0; k < 2; ++k) dst[n][k] = *(const LAS bf16x8*)(lds + PG8_SB(b, h) + boff + n * 2048 + k * 1024); } while (0)
; #define PG8_MMA(ai, bj, At, Bt) do { __builtin_amdgcn_s_setprio(1); _Pragma("unroll") for (int m = 0; m < 4; ++m) _Pragma("unroll") for (int n = 0; n < 2; ++n) _Pragma("unroll") for (int k = 0; k < 2; ++k) \
;         acc[ai][bj][m][n] = __builtin_amdgcn_mfma_f32_16x16x32_bf16(Bt[n][k], At[m][k], acc[ai][bj][m][n], 0, 0, 0); __builtin_amdgcn_s_setprio(0); } while (0)
; #define PG8_WAIT_V(n) asm volatile("s_waitcnt vmcnt(" #n ")" ::: "memory")
; #define PG8_WAIT_L(n) asm volatile("s_waitcnt lgkmcnt(" #n ")" ::: "memory")
; #define PG8_BAR __builtin_amdgcn_s_barrier()
; #define PG8_SCHED __builtin_amdgcn_sched_barrier(0)
; template <class Epi, class Sched>
; __device__ __forceinline__ void gemm_phase(LAS unsigned char* lds, const GemmP g, const Sched& S, const Epi& E, int tid) {
;     ...
;             PG8_LDB(B0, 1, 0); PG8_LDB(B1, 1, 1); PG8_SCHED; PG8_LDA(At, 1, 0); PG8_STAGE(PG8_SA(0, 1), a2 + hstepA, voffA);
;             PG8_WAIT_V(8); PG8_WAIT_L(0); PG8_BAR; PG8_MMA(0, 0, At, B0); PG8_MMA(0, 1, At, B1); PG8_BAR; PG8_SCHED;
;             PG8_LDA(At, 1, 1); PG8_STAGE(PG8_SB(1, 0), b3, voffB); PG8_STAGE(PG8_SB(1, 1), b3 + hstepB, voffB); PG8_STAGE(PG8_SA(1, 0), a3, voffA);
;             PG8_WAIT_V(8); PG8_WAIT_L(0); PG8_BAR; PG8_MMA(1, 0, At, B0); PG8_MMA(1, 1, At, B1); PG8_BAR; PG8_SCHED;
;         }
;         if (wr == 0) PG8_BAR;
.Lskr_co_5:
	global_load_lds_dwordx4 v[222:223], off
	v_lshl_add_u64 v[222:223], s[10:11], 0, v[192:193]
	s_mov_b32 m0, s88
	s_nop 0
	global_load_lds_dwordx4 v[222:223], off
	s_waitcnt vmcnt(8)
	s_waitcnt lgkmcnt(0)
	s_barrier
	s_cmp_lg_u32 s32, 0
	s_cbranch_scc1 .Lsk_co_3
	s_waitcnt lgkmcnt(0)
	v_mfma_f32_16x16x32_bf16 v[120:123], v[124:127], v[160:163], v[120:123]
	v_mfma_f32_16x16x32_bf16 v[128:131], v[136:139], v[160:163], v[128:131]
	v_mfma_f32_16x16x32_bf16 v[116:119], v[124:127], v[168:171], v[116:119]
	v_mfma_f32_16x16x32_bf16 v[112:115], v[136:139], v[168:171], v[112:115]
	v_mfma_f32_16x16x32_bf16 v[108:111], v[124:127], v[176:179], v[108:111]
	v_mfma_f32_16x16x32_bf16 v[104:107], v[136:139], v[176:179], v[104:107]
	v_mfma_f32_16x16x32_bf16 v[100:103], v[124:127], v[184:187], v[100:103]
	v_mfma_f32_16x16x32_bf16 v[96:99], v[136:139], v[184:187], v[96:99]
	v_mfma_f32_16x16x32_bf16 v[120:123], v[132:135], v[164:167], v[120:123]
	v_mfma_f32_16x16x32_bf16 v[128:131], v[140:143], v[164:167], v[128:131]
	v_mfma_f32_16x16x32_bf16 v[116:119], v[132:135], v[172:175], v[116:119]
	v_mfma_f32_16x16x32_bf16 v[112:115], v[140:143], v[172:175], v[112:115]
	v_mfma_f32_16x16x32_bf16 v[108:111], v[132:135], v[180:183], v[108:111]
	v_mfma_f32_16x16x32_bf16 v[104:107], v[140:143], v[180:183], v[104:107]
	v_mfma_f32_16x16x32_bf16 v[100:103], v[132:135], v[210:213], v[100:103]
	v_mfma_f32_16x16x32_bf16 v[96:99], v[140:143], v[210:213], v[96:99]
	v_mfma_f32_16x16x32_bf16 v[68:71], v[144:147], v[160:163], v[68:71]
	v_mfma_f32_16x16x32_bf16 v[60:63], v[152:155], v[160:163], v[60:63]
	v_mfma_f32_16x16x32_bf16 v[52:55], v[144:147], v[168:171], v[52:55]
	v_mfma_f32_16x16x32_bf16 v[48:51], v[152:155], v[168:171], v[48:51]
	v_mfma_f32_16x16x32_bf16 v[44:47], v[144:147], v[176:179], v[44:47]
	v_mfma_f32_16x16x32_bf16 v[40:43], v[152:155], v[176:179], v[40:43]
	v_mfma_f32_16x16x32_bf16 v[36:39], v[144:147], v[184:187], v[36:39]
	v_mfma_f32_16x16x32_bf16 v[32:35], v[152:155], v[184:187], v[32:35]
	v_mfma_f32_16x16x32_bf16 v[68:71], v[148:151], v[164:167], v[68:71]
	v_mfma_f32_16x16x32_bf16 v[60:63], v[156:159], v[164:167], v[60:63]
	v_mfma_f32_16x16x32_bf16 v[52:55], v[148:151], v[172:175], v[52:55]
	v_mfma_f32_16x16x32_bf16 v[48:51], v[156:159], v[172:175], v[48:51]
	v_mfma_f32_16x16x32_bf16 v[44:47], v[148:151], v[180:183], v[44:47]
	v_mfma_f32_16x16x32_bf16 v[40:43], v[156:159], v[180:183], v[40:43]
	v_mfma_f32_16x16x32_bf16 v[36:39], v[148:151], v[210:213], v[36:39]
	v_mfma_f32_16x16x32_bf16 v[32:35], v[156:159], v[210:213], v[32:35]
.Lsk_co_3:
	s_barrier
	s_add_i32 s10, s15, s62
	v_lshl_add_u64 v[198:199], v[198:199], 0, s[80:81]
	s_mov_b32 m0, s10
	s_cmp_lg_u32 s98, 0
	s_cbranch_scc1 .Lskr_co_6
	ds_read_b128 v[160:163], v215 offset:49152
	ds_read_b128 v[164:167], v215 offset:50176
	ds_read_b128 v[168:171], v215 offset:51200
	ds_read_b128 v[172:175], v215 offset:52224
	ds_read_b128 v[176:179], v215 offset:53248
	ds_read_b128 v[180:183], v215 offset:54272
	ds_read_b128 v[184:187], v215 offset:55296
	ds_read_b128 v[210:213], v215 offset:56320
.Lskr_co_6:
	global_load_lds_dwordx4 v[198:199], off
	s_add_i32 m0, s10, 0x2000
	s_add_u32 s8, s8, 0x40080
	v_lshl_add_u64 v[198:199], v[200:201], 0, s[80:81]
	s_addc_u32 s9, s9, 0
	s_add_i32 s10, s16, s62
	global_load_lds_dwordx4 v[198:199], off
	v_lshl_add_u64 v[198:199], s[8:9], 0, v[190:191]
	s_mov_b32 m0, s10
	s_nop 0
	global_load_lds_dwordx4 v[198:199], off
	v_lshl_add_u64 v[198:199], s[8:9], 0, v[194:195]
	s_add_i32 m0, s10, 0x2000
	s_nop 0
	global_load_lds_dwordx4 v[198:199], off
	v_lshl_add_u64 v[198:199], v[216:217], 0, s[80:81]
	s_mov_b32 m0, s82
	s_nop 0
	global_load_lds_dwordx4 v[198:199], off
	v_lshl_add_u64 v[198:199], v[220:221], 0, s[80:81]
	s_mov_b32 m0, s0
	s_nop 0
	global_load_lds_dwordx4 v[198:199], off
	s_waitcnt vmcnt(8)
	s_waitcnt lgkmcnt(0)
	s_barrier
	s_cmp_lg_u32 s98, 0
	s_cbranch_scc1 .Lsk_co_4
	s_waitcnt lgkmcnt(0)
	v_mfma_f32_16x16x32_bf16 v[92:95], v[124:127], v[160:163], v[92:95]
	v_mfma_f32_16x16x32_bf16 v[88:91], v[136:139], v[160:163], v[88:91]
	v_mfma_f32_16x16x32_bf16 v[84:87], v[124:127], v[168:171], v[84:87]
	v_mfma_f32_16x16x32_bf16 v[80:83], v[136:139], v[168:171], v[80:83]
	v_mfma_f32_16x16x32_bf16 v[76:79], v[124:127], v[176:179], v[76:79]
	v_mfma_f32_16x16x32_bf16 v[72:75], v[136:139], v[176:179], v[72:75]
	v_mfma_f32_16x16x32_bf16 v[64:67], v[124:127], v[184:187], v[64:67]
	v_mfma_f32_16x16x32_bf16 v[56:59], v[136:139], v[184:187], v[56:59]
	v_mfma_f32_16x16x32_bf16 v[92:95], v[132:135], v[164:167], v[92:95]
	v_mfma_f32_16x16x32_bf16 v[88:91], v[140:143], v[164:167], v[88:91]
	v_mfma_f32_16x16x32_bf16 v[84:87], v[132:135], v[172:175], v[84:87]
	v_mfma_f32_16x16x32_bf16 v[80:83], v[140:143], v[172:175], v[80:83]
	v_mfma_f32_16x16x32_bf16 v[76:79], v[132:135], v[180:183], v[76:79]
	v_mfma_f32_16x16x32_bf16 v[72:75], v[140:143], v[180:183], v[72:75]
	v_mfma_f32_16x16x32_bf16 v[64:67], v[132:135], v[210:213], v[64:67]
	v_mfma_f32_16x16x32_bf16 v[56:59], v[140:143], v[210:213], v[56:59]
	v_mfma_f32_16x16x32_bf16 v[28:31], v[144:147], v[160:163], v[28:31]
	v_mfma_f32_16x16x32_bf16 v[24:27], v[152:155], v[160:163], v[24:27]
	v_mfma_f32_16x16x32_bf16 v[20:23], v[144:147], v[168:171], v[20:23]
	v_mfma_f32_16x16x32_bf16 v[16:19], v[152:155], v[168:171], v[16:19]
	v_mfma_f32_16x16x32_bf16 v[12:15], v[144:147], v[176:179], v[12:15]
	v_mfma_f32_16x16x32_bf16 v[8:11], v[152:155], v[176:179], v[8:11]
	v_mfma_f32_16x16x32_bf16 v[4:7], v[144:147], v[184:187], v[4:7]
	v_mfma_f32_16x16x32_bf16 v[0:3], v[152:155], v[184:187], v[0:3]
	v_mfma_f32_16x16x32_bf16 v[28:31], v[148:151], v[164:167], v[28:31]
	v_mfma_f32_16x16x32_bf16 v[24:27], v[156:159], v[164:167], v[24:27]
	v_mfma_f32_16x16x32_bf16 v[20:23], v[148:151], v[172:175], v[20:23]
	v_mfma_f32_16x16x32_bf16 v[16:19], v[156:159], v[172:175], v[16:19]
	v_mfma_f32_16x16x32_bf16 v[12:15], v[148:151], v[180:183], v[12:15]
	v_mfma_f32_16x16x32_bf16 v[8:11], v[156:159], v[180:183], v[8:11]
	v_mfma_f32_16x16x32_bf16 v[4:7], v[148:151], v[210:213], v[4:7]
	v_mfma_f32_16x16x32_bf16 v[0:3], v[156:159], v[210:213], v[0:3]
.Lsk_co_4:
	s_barrier
	s_add_i32 s14, s14, 2
	s_add_u32 s12, s12, 0x100
	s_addc_u32 s13, s13, 0
	s_add_u32 s6, s6, 0x100
	s_addc_u32 s7, s7, 0
	s_cmp_gt_u32 s14, 13
	s_cbranch_scc0 .LBB0_1163
	s_setprio 0
	s_and_b64 vcc, exec, s[78:79]
	s_cbranch_vccz .LBB0_1166
	s_barrier

; #define PG8_STAGE(bufoff, gbase, voff) do { _Pragma("unroll") for (int _i = 0; _i < 2; ++_i) \
;         __builtin_amdgcn_global_load_lds((const unsigned*)((const char*)(gbase) + (voff)[_i]), (LAS unsigned*)(lds + (bufoff) + ldsw + _i * 8192), 16, 0, 0); } while (0)
; #define PG8_LDA(dst, b, h) do { _Pragma("unroll") for (int m = 0; m < 4; ++m) _Pragma("unroll") for (int k = 0; k < 2; ++k) dst[m][k] = *(const LAS bf16x8*)(lds + PG8_SA(b, h) + aoff + m * 2048 + k * 1024); } while (0)
; #define PG8_LDB(dst, b, h) do { _Pragma("unroll") for (int n = 0; n < 2; ++n) _Pragma("unroll") for (int k = 0; k < 2; ++k) dst[n][k] = *(const LAS bf16x8*)(lds + PG8_SB(b, h) + boff + n * 2048 + k * 1024); } while (0)
; #define PG8_SCHED __builtin_amdgcn_sched_barrier(0)
; template <class Epi, class Sched>
; __device__ __forceinline__ void gemm_phase(LAS unsigned char* lds, const GemmP g, const Sched& S, const Epi& E, int tid) {
;     ...
;         for (int t = 0; t < nt; t += 2) {
;             const bool last = (t == nt - 2);
;             const char* a1 = cA + (size_t)(t + 1) * kstep;
;             const char* a2 = last ? nA : cA + (size_t)(t + 2) * kstep; const char* b2 = last ? nB : cB + (size_t)(t + 2) * kstep;
;             const char* a3 = a2 + kstep; const char* b3 = b2 + kstep;
;             PG8_LDB(B0, 0, 0); PG8_LDB(B1, 0, 1); PG8_SCHED; PG8_LDA(At, 0, 0); PG8_STAGE(PG8_SA(1, 1), a1 + hstepA, voffA);
;     ...
; #pragma unroll
;         for (int a = 0; a < 2; ++a)
; #pragma unroll
;             for (int b = 0; b < 2; ++b)
; #pragma unroll
;                 for (int m = 0; m < 4; ++m)
; #pragma unroll
;                     for (int n = 0; n < 2; ++n) acc[a][b][m][n] = (f32x4){0.f, 0.f, 0.f, 0.f};
;         cur = nxt; cA = nA; cB = nB; ++ui;
.LBB0_1389:
	s_add_u32 s14, s12, 0x100
	s_addc_u32 s15, s13, 0
	s_add_u32 s6, s10, 0x40080
	v_mov_b32_e32 v96, 0
	s_addc_u32 s7, s11, 0
	s_mov_b32 s38, -2
	v_mov_b32_e32 v97, v96
	v_mov_b32_e32 v98, v96
	v_mov_b32_e32 v99, v96
	v_mov_b32_e32 v100, v96
	v_mov_b32_e32 v101, v96
	v_mov_b32_e32 v102, v96
	v_mov_b32_e32 v103, v96
	v_mov_b32_e32 v0, v96
	v_mov_b32_e32 v1, v96
	v_mov_b32_e32 v2, v96
	v_mov_b32_e32 v3, v96
	v_mov_b32_e32 v4, v96
	v_mov_b32_e32 v5, v96
	v_mov_b32_e32 v6, v96
	v_mov_b32_e32 v7, v96
	v_mov_b32_e32 v16, v96
	v_mov_b32_e32 v17, v96
	v_mov_b32_e32 v18, v96
	v_mov_b32_e32 v19, v96
	v_mov_b32_e32 v20, v96
	v_mov_b32_e32 v21, v96
	v_mov_b32_e32 v22, v96
	v_mov_b32_e32 v23, v96
	v_mov_b32_e32 v32, v96
	v_mov_b32_e32 v33, v96
	v_mov_b32_e32 v34, v96
	v_mov_b32_e32 v35, v96
	v_mov_b32_e32 v36, v96
	v_mov_b32_e32 v37, v96
	v_mov_b32_e32 v38, v96
	v_mov_b32_e32 v39, v96
	v_mov_b32_e32 v104, v96
	v_mov_b32_e32 v105, v96
	v_mov_b32_e32 v106, v96
	v_mov_b32_e32 v107, v96
	v_mov_b32_e32 v108, v96
	v_mov_b32_e32 v109, v96
	v_mov_b32_e32 v110, v96
	v_mov_b32_e32 v111, v96
	v_mov_b32_e32 v8, v96
	v_mov_b32_e32 v9, v96
	v_mov_b32_e32 v10, v96
	v_mov_b32_e32 v11, v96
	v_mov_b32_e32 v12, v96
	v_mov_b32_e32 v13, v96
	v_mov_b32_e32 v14, v96
	v_mov_b32_e32 v15, v96
	v_mov_b32_e32 v24, v96
	v_mov_b32_e32 v25, v96
	v_mov_b32_e32 v26, v96
	v_mov_b32_e32 v27, v96
	v_mov_b32_e32 v28, v96
	v_mov_b32_e32 v29, v96
	v_mov_b32_e32 v30, v96
	v_mov_b32_e32 v31, v96
	v_mov_b32_e32 v40, v96
	v_mov_b32_e32 v41, v96
	v_mov_b32_e32 v42, v96
	v_mov_b32_e32 v43, v96
	v_mov_b32_e32 v44, v96
	v_mov_b32_e32 v45, v96
	v_mov_b32_e32 v46, v96
	v_mov_b32_e32 v47, v96
	v_mov_b32_e32 v112, v96
	v_mov_b32_e32 v113, v96
	v_mov_b32_e32 v114, v96
	v_mov_b32_e32 v115, v96
	v_mov_b32_e32 v116, v96
	v_mov_b32_e32 v117, v96
	v_mov_b32_e32 v118, v96
	v_mov_b32_e32 v119, v96
	v_mov_b32_e32 v48, v96
	v_mov_b32_e32 v49, v96
	v_mov_b32_e32 v50, v96
	v_mov_b32_e32 v51, v96
	v_mov_b32_e32 v52, v96
	v_mov_b32_e32 v53, v96
	v_mov_b32_e32 v54, v96
	v_mov_b32_e32 v55, v96
	v_mov_b32_e32 v64, v96
	v_mov_b32_e32 v65, v96
	v_mov_b32_e32 v66, v96
	v_mov_b32_e32 v67, v96
	v_mov_b32_e32 v68, v96
	v_mov_b32_e32 v69, v96
	v_mov_b32_e32 v70, v96
	v_mov_b32_e32 v71, v96
	v_mov_b32_e32 v80, v96
	v_mov_b32_e32 v81, v96
	v_mov_b32_e32 v82, v96
	v_mov_b32_e32 v83, v96
	v_mov_b32_e32 v84, v96
	v_mov_b32_e32 v85, v96
	v_mov_b32_e32 v86, v96
	v_mov_b32_e32 v87, v96
	v_mov_b32_e32 v120, v96
	v_mov_b32_e32 v121, v96
	v_mov_b32_e32 v122, v96
	v_mov_b32_e32 v123, v96
	v_mov_b32_e32 v124, v96
	v_mov_b32_e32 v125, v96
	v_mov_b32_e32 v126, v96
	v_mov_b32_e32 v127, v96
	v_mov_b32_e32 v56, v96
	v_mov_b32_e32 v57, v96
	v_mov_b32_e32 v58, v96
	v_mov_b32_e32 v59, v96
	v_mov_b32_e32 v60, v96
	v_mov_b32_e32 v61, v96
	v_mov_b32_e32 v62, v96
	v_mov_b32_e32 v63, v96
	v_mov_b32_e32 v72, v96
	v_mov_b32_e32 v73, v96
	v_mov_b32_e32 v74, v96
	v_mov_b32_e32 v75, v96
	v_mov_b32_e32 v76, v96
	v_mov_b32_e32 v77, v96
	v_mov_b32_e32 v78, v96
	v_mov_b32_e32 v79, v96
	v_mov_b32_e32 v88, v96
	v_mov_b32_e32 v89, v96
	v_mov_b32_e32 v90, v96
	v_mov_b32_e32 v91, v96
	v_mov_b32_e32 v92, v96
	v_mov_b32_e32 v93, v96
	v_mov_b32_e32 v94, v96
	v_mov_b32_e32 v95, v96
	s_cmp_lg_u64 s[2:3], 0
	s_cbranch_scc1 .Lsp_1390
	s_setprio 1
.Lsp_1390:
.LBB0_1390:
	s_add_u32 s10, s6, 0xfffc0080
	s_addc_u32 s11, s7, -1
	s_add_i32 s39, 0, 0x10000
	s_cmp_eq_u32 s38, 12
	s_cselect_b32 s13, s95, s11
	s_cselect_b32 s12, s94, s10
	v_add_u32_e32 v144, s39, v146
	v_add_u32_e32 v232, s39, v231
	s_cselect_b32 s11, s97, s15
	s_cselect_b32 s10, s96, s14
	s_add_i32 s56, 0, 0x14000
	ds_read_b128 v[140:143], v144
	ds_read_b128 v[148:151], v232
	ds_read_b128 v[152:155], v144 offset:2048
	ds_read_b128 v[156:159], v232 offset:2048
	v_add_u32_e32 v144, s56, v146
	v_add_u32_e32 v233, s56, v231
	ds_read_b128 v[160:163], v144
	ds_read_b128 v[164:167], v233
	ds_read_b128 v[168:171], v144 offset:2048
	ds_read_b128 v[172:175], v233 offset:2048
	v_lshl_add_u64 v[144:145], s[6:7], 0, v[138:139]
	s_add_i32 m0, s53, 0xc000
	ds_read_b128 v[176:179], v147
	ds_read_b128 v[180:183], v230
	ds_read_b128 v[184:187], v147 offset:2048
	ds_read_b128 v[188:191], v230 offset:2048
	ds_read_b128 v[192:195], v147 offset:4096
	ds_read_b128 v[206:209], v230 offset:4096
	ds_read_b128 v[210:213], v147 offset:6144
	ds_read_b128 v[214:217], v230 offset:6144
	global_load_lds_dwordx4 v[144:145], off
	v_lshl_add_u64 v[144:145], s[6:7], 0, v[136:137]
	s_add_i32 m0, s53, 0xe000
	s_nop 0
	global_load_lds_dwordx4 v[144:145], off
	s_cmp_eq_u32 s38, -2
	s_cbranch_scc1 .Lfirstit_5
	s_waitcnt vmcnt(8)
; #define PG8_STAGE(bufoff, gbase, voff) do { _Pragma("unroll") for (int _i = 0; _i < 2; ++_i) \
;         __builtin_amdgcn_global_load_lds((const unsigned*)((const char*)(gbase) + (voff)[_i]), (LAS unsigned*)(lds + (bufoff) + ldsw + _i * 8192), 16, 0, 0); } while (0)
; #define PG8_LDA(dst, b, h) do { _Pragma("unroll") for (int m = 0; m < 4; ++m) _Pragma("unroll") for (int k = 0; k < 2; ++k) dst[m][k] = *(const LAS bf16x8*)(lds + PG8_SA(b, h) + aoff + m * 2048 + k * 1024); } while (0)
; #define PG8_MMA(ai, bj, At, Bt) do { __builtin_amdgcn_s_setprio(1); _Pragma("unroll") for (int m = 0; m < 4; ++m) _Pragma("unroll") for (int n = 0; n < 2; ++n) _Pragma("unroll") for (int k = 0; k < 2; ++k) \
;         acc[ai][bj][m][n] = __builtin_amdgcn_mfma_f32_16x16x32_bf16(Bt[n][k], At[m][k], acc[ai][bj][m][n], 0, 0, 0); __builtin_amdgcn_s_setprio(0); } while (0)
; #define PG8_WAIT_V(n) asm volatile("s_waitcnt vmcnt(" #n ")" ::: "memory")
; #define PG8_WAIT_L(n) asm volatile("s_waitcnt lgkmcnt(" #n ")" ::: "memory")
; #define PG8_BAR __builtin_amdgcn_s_barrier()
; #define PG8_SCHED __builtin_amdgcn_sched_barrier(0)
; template <class Epi, class Sched>
; __device__ __forceinline__ void gemm_phase(LAS unsigned char* lds, const GemmP g, const Sched& S, const Epi& E, int tid) {
;     ...
;             PG8_WAIT_V(8); PG8_WAIT_L(0); PG8_BAR; PG8_MMA(0, 0, At, B0); PG8_MMA(0, 1, At, B1); PG8_BAR; PG8_SCHED;
;             PG8_LDA(At, 0, 1); PG8_STAGE(PG8_SB(0, 0), b2, voffB); PG8_STAGE(PG8_SB(0, 1), b2 + hstepB, voffB); PG8_STAGE(PG8_SA(0, 0), a2, voffA);
;             PG8_WAIT_V(8); PG8_WAIT_L(0); PG8_BAR; PG8_MMA(1, 0, At, B0); PG8_MMA(1, 1, At, B1); PG8_BAR; PG8_SCHED;
.Lfirstit_5:
	s_waitcnt lgkmcnt(0)
	s_barrier
	s_waitcnt lgkmcnt(0)
	v_mfma_f32_16x16x32_bf16 v[92:95], v[140:143], v[176:179], v[92:95]
	v_mfma_f32_16x16x32_bf16 v[88:91], v[152:155], v[176:179], v[88:91]
	v_mfma_f32_16x16x32_bf16 v[76:79], v[140:143], v[184:187], v[76:79]
	v_mfma_f32_16x16x32_bf16 v[72:75], v[152:155], v[184:187], v[72:75]
	v_mfma_f32_16x16x32_bf16 v[60:63], v[140:143], v[192:195], v[60:63]
	v_mfma_f32_16x16x32_bf16 v[56:59], v[152:155], v[192:195], v[56:59]
	v_mfma_f32_16x16x32_bf16 v[124:127], v[140:143], v[210:213], v[124:127]
	v_mfma_f32_16x16x32_bf16 v[120:123], v[152:155], v[210:213], v[120:123]
	v_mfma_f32_16x16x32_bf16 v[92:95], v[148:151], v[180:183], v[92:95]
	v_mfma_f32_16x16x32_bf16 v[88:91], v[156:159], v[180:183], v[88:91]
	v_mfma_f32_16x16x32_bf16 v[76:79], v[148:151], v[188:191], v[76:79]
	v_mfma_f32_16x16x32_bf16 v[72:75], v[156:159], v[188:191], v[72:75]
	v_mfma_f32_16x16x32_bf16 v[60:63], v[148:151], v[206:209], v[60:63]
	v_mfma_f32_16x16x32_bf16 v[56:59], v[156:159], v[206:209], v[56:59]
	v_mfma_f32_16x16x32_bf16 v[124:127], v[148:151], v[214:217], v[124:127]
	v_mfma_f32_16x16x32_bf16 v[120:123], v[156:159], v[214:217], v[120:123]
	v_mfma_f32_16x16x32_bf16 v[84:87], v[160:163], v[176:179], v[84:87]
	v_mfma_f32_16x16x32_bf16 v[80:83], v[168:171], v[176:179], v[80:83]
	v_mfma_f32_16x16x32_bf16 v[68:71], v[160:163], v[184:187], v[68:71]
	v_mfma_f32_16x16x32_bf16 v[64:67], v[168:171], v[184:187], v[64:67]
	v_mfma_f32_16x16x32_bf16 v[52:55], v[160:163], v[192:195], v[52:55]
	v_mfma_f32_16x16x32_bf16 v[48:51], v[168:171], v[192:195], v[48:51]
	v_mfma_f32_16x16x32_bf16 v[116:119], v[160:163], v[210:213], v[116:119]
	v_mfma_f32_16x16x32_bf16 v[112:115], v[168:171], v[210:213], v[112:115]
	v_mfma_f32_16x16x32_bf16 v[84:87], v[164:167], v[180:183], v[84:87]
	v_mfma_f32_16x16x32_bf16 v[80:83], v[172:175], v[180:183], v[80:83]
	v_mfma_f32_16x16x32_bf16 v[68:71], v[164:167], v[188:191], v[68:71]
	v_mfma_f32_16x16x32_bf16 v[64:67], v[172:175], v[188:191], v[64:67]
	v_mfma_f32_16x16x32_bf16 v[52:55], v[164:167], v[206:209], v[52:55]
	v_mfma_f32_16x16x32_bf16 v[48:51], v[172:175], v[206:209], v[48:51]
	v_mfma_f32_16x16x32_bf16 v[116:119], v[164:167], v[214:217], v[116:119]
	v_mfma_f32_16x16x32_bf16 v[112:115], v[172:175], v[214:217], v[112:115]
	s_barrier
	s_add_i32 s39, s39, s52
	v_lshl_add_u64 v[144:145], s[10:11], 0, v[130:131]
	s_mov_b32 m0, s39
	ds_read_b128 v[176:179], v147 offset:16384
	ds_read_b128 v[180:183], v230 offset:16384
	ds_read_b128 v[184:187], v147 offset:18432
	ds_read_b128 v[188:191], v230 offset:18432
	ds_read_b128 v[192:195], v147 offset:20480
	ds_read_b128 v[206:209], v230 offset:20480
	ds_read_b128 v[210:213], v147 offset:22528
	ds_read_b128 v[214:217], v230 offset:22528
	global_load_lds_dwordx4 v[144:145], off
	s_add_i32 m0, s39, 0x2000
	s_add_u32 s48, s10, 0x40000
	v_lshl_add_u64 v[198:199], s[10:11], 0, v[134:135]
	s_addc_u32 s49, s11, 0
	s_add_i32 s39, s56, s52
	global_load_lds_dwordx4 v[198:199], off
	v_lshl_add_u64 v[200:201], s[48:49], 0, v[130:131]
	s_mov_b32 m0, s39
	v_lshl_add_u64 v[220:221], s[12:13], 0, v[132:133]
	global_load_lds_dwordx4 v[200:201], off
	v_lshl_add_u64 v[200:201], s[48:49], 0, v[134:135]
	s_add_i32 m0, s39, 0x2000
	s_nop 0
	global_load_lds_dwordx4 v[200:201], off
	v_lshl_add_u64 v[200:201], s[12:13], 0, v[128:129]
	s_mov_b32 m0, s53
	s_nop 0
	global_load_lds_dwordx4 v[200:201], off
	s_mov_b32 m0, s54
	s_nop 0
	global_load_lds_dwordx4 v[220:221], off
	s_waitcnt vmcnt(8)
	s_waitcnt lgkmcnt(0)
	s_barrier
	s_waitcnt lgkmcnt(0)
	v_mfma_f32_16x16x32_bf16 v[44:47], v[140:143], v[176:179], v[44:47]
	v_mfma_f32_16x16x32_bf16 v[40:43], v[152:155], v[176:179], v[40:43]
	v_mfma_f32_16x16x32_bf16 v[28:31], v[140:143], v[184:187], v[28:31]
	v_mfma_f32_16x16x32_bf16 v[24:27], v[152:155], v[184:187], v[24:27]
	v_mfma_f32_16x16x32_bf16 v[12:15], v[140:143], v[192:195], v[12:15]
	v_mfma_f32_16x16x32_bf16 v[8:11], v[152:155], v[192:195], v[8:11]
	v_mfma_f32_16x16x32_bf16 v[108:111], v[140:143], v[210:213], v[108:111]
	v_mfma_f32_16x16x32_bf16 v[104:107], v[152:155], v[210:213], v[104:107]
	v_mfma_f32_16x16x32_bf16 v[44:47], v[148:151], v[180:183], v[44:47]
	v_mfma_f32_16x16x32_bf16 v[40:43], v[156:159], v[180:183], v[40:43]
	v_mfma_f32_16x16x32_bf16 v[28:31], v[148:151], v[188:191], v[28:31]
	v_mfma_f32_16x16x32_bf16 v[24:27], v[156:159], v[188:191], v[24:27]
	v_mfma_f32_16x16x32_bf16 v[12:15], v[148:151], v[206:209], v[12:15]
	v_mfma_f32_16x16x32_bf16 v[8:11], v[156:159], v[206:209], v[8:11]
	v_mfma_f32_16x16x32_bf16 v[108:111], v[148:151], v[214:217], v[108:111]
	v_mfma_f32_16x16x32_bf16 v[104:107], v[156:159], v[214:217], v[104:107]
	v_mfma_f32_16x16x32_bf16 v[36:39], v[160:163], v[176:179], v[36:39]
	v_mfma_f32_16x16x32_bf16 v[32:35], v[168:171], v[176:179], v[32:35]
	v_mfma_f32_16x16x32_bf16 v[20:23], v[160:163], v[184:187], v[20:23]
	v_mfma_f32_16x16x32_bf16 v[16:19], v[168:171], v[184:187], v[16:19]
	v_mfma_f32_16x16x32_bf16 v[4:7], v[160:163], v[192:195], v[4:7]
	v_mfma_f32_16x16x32_bf16 v[0:3], v[168:171], v[192:195], v[0:3]
	v_mfma_f32_16x16x32_bf16 v[100:103], v[160:163], v[210:213], v[100:103]
	v_mfma_f32_16x16x32_bf16 v[96:99], v[168:171], v[210:213], v[96:99]
	v_mfma_f32_16x16x32_bf16 v[36:39], v[164:167], v[180:183], v[36:39]
	v_mfma_f32_16x16x32_bf16 v[32:35], v[172:175], v[180:183], v[32:35]
	v_mfma_f32_16x16x32_bf16 v[20:23], v[164:167], v[188:191], v[20:23]
	v_mfma_f32_16x16x32_bf16 v[16:19], v[172:175], v[188:191], v[16:19]
	v_mfma_f32_16x16x32_bf16 v[4:7], v[164:167], v[206:209], v[4:7]
	v_mfma_f32_16x16x32_bf16 v[0:3], v[172:175], v[206:209], v[0:3]
	v_mfma_f32_16x16x32_bf16 v[100:103], v[164:167], v[214:217], v[100:103]
	v_mfma_f32_16x16x32_bf16 v[96:99], v[172:175], v[214:217], v[96:99]
	s_barrier
; #define PG8_STAGE(bufoff, gbase, voff) do { _Pragma("unroll") for (int _i = 0; _i < 2; ++_i) \
;         __builtin_amdgcn_global_load_lds((const unsigned*)((const char*)(gbase) + (voff)[_i]), (LAS unsigned*)(lds + (bufoff) + ldsw + _i * 8192), 16, 0, 0); } while (0)
; #define PG8_LDA(dst, b, h) do { _Pragma("unroll") for (int m = 0; m < 4; ++m) _Pragma("unroll") for (int k = 0; k < 2; ++k) dst[m][k] = *(const LAS bf16x8*)(lds + PG8_SA(b, h) + aoff + m * 2048 + k * 1024); } while (0)
; #define PG8_LDB(dst, b, h) do { _Pragma("unroll") for (int n = 0; n < 2; ++n) _Pragma("unroll") for (int k = 0; k < 2; ++k) dst[n][k] = *(const LAS bf16x8*)(lds + PG8_SB(b, h) + boff + n * 2048 + k * 1024); } while (0)
; #define PG8_MMA(ai, bj, At, Bt) do { __builtin_amdgcn_s_setprio(1); _Pragma("unroll") for (int m = 0; m < 4; ++m) _Pragma("unroll") for (int n = 0; n < 2; ++n) _Pragma("unroll") for (int k = 0; k < 2; ++k) \
;         acc[ai][bj][m][n] = __builtin_amdgcn_mfma_f32_16x16x32_bf16(Bt[n][k], At[m][k], acc[ai][bj][m][n], 0, 0, 0); __builtin_amdgcn_s_setprio(0); } while (0)
; #define PG8_WAIT_V(n) asm volatile("s_waitcnt vmcnt(" #n ")" ::: "memory")
; #define PG8_WAIT_L(n) asm volatile("s_waitcnt lgkmcnt(" #n ")" ::: "memory")
; #define PG8_BAR __builtin_amdgcn_s_barrier()
; #define PG8_SCHED __builtin_amdgcn_sched_barrier(0)
; template <class Epi, class Sched>
; __device__ __forceinline__ void gemm_phase(LAS unsigned char* lds, const GemmP g, const Sched& S, const Epi& E, int tid) {
;     ...
;             PG8_LDB(B0, 1, 0); PG8_LDB(B1, 1, 1); PG8_SCHED; PG8_LDA(At, 1, 0); PG8_STAGE(PG8_SA(0, 1), a2 + hstepA, voffA);
;             PG8_WAIT_V(8); PG8_WAIT_L(0); PG8_BAR; PG8_MMA(0, 0, At, B0); PG8_MMA(0, 1, At, B1); PG8_BAR; PG8_SCHED;
	s_add_i32 s39, 0, 0x18000
	s_add_i32 s48, 0, 0x1c000
	v_add_u32_e32 v156, s39, v146
	v_add_u32_e32 v232, s39, v231
	v_add_u32_e32 v172, s48, v146
	v_add_u32_e32 v233, s48, v231
	ds_read_b128 v[140:143], v156
	ds_read_b128 v[148:151], v232
	ds_read_b128 v[152:155], v156 offset:2048
	ds_read_b128 v[156:159], v232 offset:2048
	ds_read_b128 v[160:163], v172
	ds_read_b128 v[164:167], v233
	ds_read_b128 v[168:171], v172 offset:2048
	ds_read_b128 v[172:175], v233 offset:2048
	s_add_u32 s12, s12, 0x40000
	s_addc_u32 s13, s13, 0
	s_mov_b32 m0, s58
	v_lshl_add_u64 v[222:223], s[12:13], 0, v[128:129]
	ds_read_b128 v[176:179], v147 offset:32768
	ds_read_b128 v[180:183], v230 offset:32768
	ds_read_b128 v[184:187], v147 offset:34816
	ds_read_b128 v[188:191], v230 offset:34816
	ds_read_b128 v[192:195], v147 offset:36864
	ds_read_b128 v[206:209], v230 offset:36864
	ds_read_b128 v[210:213], v147 offset:38912
	ds_read_b128 v[214:217], v230 offset:38912
	global_load_lds_dwordx4 v[222:223], off
	v_lshl_add_u64 v[222:223], s[12:13], 0, v[132:133]
	s_mov_b32 m0, s59
	s_nop 0
	global_load_lds_dwordx4 v[222:223], off
	s_waitcnt vmcnt(8)
	s_waitcnt lgkmcnt(0)
	s_barrier
	s_waitcnt lgkmcnt(0)
	v_mfma_f32_16x16x32_bf16 v[92:95], v[140:143], v[176:179], v[92:95]
	v_mfma_f32_16x16x32_bf16 v[88:91], v[152:155], v[176:179], v[88:91]
	v_mfma_f32_16x16x32_bf16 v[76:79], v[140:143], v[184:187], v[76:79]
	v_mfma_f32_16x16x32_bf16 v[72:75], v[152:155], v[184:187], v[72:75]
	v_mfma_f32_16x16x32_bf16 v[60:63], v[140:143], v[192:195], v[60:63]
	v_mfma_f32_16x16x32_bf16 v[56:59], v[152:155], v[192:195], v[56:59]
	v_mfma_f32_16x16x32_bf16 v[124:127], v[140:143], v[210:213], v[124:127]
	v_mfma_f32_16x16x32_bf16 v[120:123], v[152:155], v[210:213], v[120:123]
	v_mfma_f32_16x16x32_bf16 v[92:95], v[148:151], v[180:183], v[92:95]
	v_mfma_f32_16x16x32_bf16 v[88:91], v[156:159], v[180:183], v[88:91]
	v_mfma_f32_16x16x32_bf16 v[76:79], v[148:151], v[188:191], v[76:79]
	v_mfma_f32_16x16x32_bf16 v[72:75], v[156:159], v[188:191], v[72:75]
	v_mfma_f32_16x16x32_bf16 v[60:63], v[148:151], v[206:209], v[60:63]
	v_mfma_f32_16x16x32_bf16 v[56:59], v[156:159], v[206:209], v[56:59]
	v_mfma_f32_16x16x32_bf16 v[124:127], v[148:151], v[214:217], v[124:127]
	v_mfma_f32_16x16x32_bf16 v[120:123], v[156:159], v[214:217], v[120:123]
	v_mfma_f32_16x16x32_bf16 v[84:87], v[160:163], v[176:179], v[84:87]
	v_mfma_f32_16x16x32_bf16 v[80:83], v[168:171], v[176:179], v[80:83]
	v_mfma_f32_16x16x32_bf16 v[68:71], v[160:163], v[184:187], v[68:71]
	v_mfma_f32_16x16x32_bf16 v[64:67], v[168:171], v[184:187], v[64:67]
	v_mfma_f32_16x16x32_bf16 v[52:55], v[160:163], v[192:195], v[52:55]
	v_mfma_f32_16x16x32_bf16 v[48:51], v[168:171], v[192:195], v[48:51]
	v_mfma_f32_16x16x32_bf16 v[116:119], v[160:163], v[210:213], v[116:119]
	v_mfma_f32_16x16x32_bf16 v[112:115], v[168:171], v[210:213], v[112:115]
	v_mfma_f32_16x16x32_bf16 v[84:87], v[164:167], v[180:183], v[84:87]
	v_mfma_f32_16x16x32_bf16 v[80:83], v[172:175], v[180:183], v[80:83]
	v_mfma_f32_16x16x32_bf16 v[68:71], v[164:167], v[188:191], v[68:71]
	v_mfma_f32_16x16x32_bf16 v[64:67], v[172:175], v[188:191], v[64:67]
	v_mfma_f32_16x16x32_bf16 v[52:55], v[164:167], v[206:209], v[52:55]
	v_mfma_f32_16x16x32_bf16 v[48:51], v[172:175], v[206:209], v[48:51]
	v_mfma_f32_16x16x32_bf16 v[116:119], v[164:167], v[214:217], v[116:119]
	v_mfma_f32_16x16x32_bf16 v[112:115], v[172:175], v[214:217], v[112:115]
	s_barrier
; #define PG8_STAGE(bufoff, gbase, voff) do { _Pragma("unroll") for (int _i = 0; _i < 2; ++_i) \
;         __builtin_amdgcn_global_load_lds((const unsigned*)((const char*)(gbase) + (voff)[_i]), (LAS unsigned*)(lds + (bufoff) + ldsw + _i * 8192), 16, 0, 0); } while (0)
; #define PG8_LDA(dst, b, h) do { _Pragma("unroll") for (int m = 0; m < 4; ++m) _Pragma("unroll") for (int k = 0; k < 2; ++k) dst[m][k] = *(const LAS bf16x8*)(lds + PG8_SA(b, h) + aoff + m * 2048 + k * 1024); } while (0)
; #define PG8_MMA(ai, bj, At, Bt) do { __builtin_amdgcn_s_setprio(1); _Pragma("unroll") for (int m = 0; m < 4; ++m) _Pragma("unroll") for (int n = 0; n < 2; ++n) _Pragma("unroll") for (int k = 0; k < 2; ++k) \
;         acc[ai][bj][m][n] = __builtin_amdgcn_mfma_f32_16x16x32_bf16(Bt[n][k], At[m][k], acc[ai][bj][m][n], 0, 0, 0); __builtin_amdgcn_s_setprio(0); } while (0)
; #define PG8_WAIT_V(n) asm volatile("s_waitcnt vmcnt(" #n ")" ::: "memory")
; #define PG8_WAIT_L(n) asm volatile("s_waitcnt lgkmcnt(" #n ")" ::: "memory")
; #define PG8_BAR __builtin_amdgcn_s_barrier()
; #define PG8_SCHED __builtin_amdgcn_sched_barrier(0)
; template <class Epi, class Sched>
; __device__ __forceinline__ void gemm_phase(LAS unsigned char* lds, const GemmP g, const Sched& S, const Epi& E, int tid) {
;     ...
;             PG8_LDA(At, 1, 1); PG8_STAGE(PG8_SB(1, 0), b3, voffB); PG8_STAGE(PG8_SB(1, 1), b3 + hstepB, voffB); PG8_STAGE(PG8_SA(1, 0), a3, voffA);
;             PG8_WAIT_V(8); PG8_WAIT_L(0); PG8_BAR; PG8_MMA(1, 0, At, B0); PG8_MMA(1, 1, At, B1); PG8_BAR; PG8_SCHED;
;         }
;         if (wr == 0) PG8_BAR;
	s_add_i32 s12, s39, s52
	v_lshl_add_u64 v[144:145], v[144:145], 0, s[80:81]
	s_mov_b32 m0, s12
	ds_read_b128 v[176:179], v147 offset:49152
	ds_read_b128 v[180:183], v230 offset:49152
	ds_read_b128 v[184:187], v147 offset:51200
	ds_read_b128 v[188:191], v230 offset:51200
	ds_read_b128 v[192:195], v147 offset:53248
	ds_read_b128 v[206:209], v230 offset:53248
	ds_read_b128 v[210:213], v147 offset:55296
	ds_read_b128 v[214:217], v230 offset:55296
	global_load_lds_dwordx4 v[144:145], off
	s_add_i32 m0, s12, 0x2000
	s_add_u32 s10, s10, 0x40080
	v_lshl_add_u64 v[144:145], v[198:199], 0, s[80:81]
	s_addc_u32 s11, s11, 0
	s_add_i32 s12, s48, s52
	global_load_lds_dwordx4 v[144:145], off
	v_lshl_add_u64 v[144:145], s[10:11], 0, v[130:131]
	s_mov_b32 m0, s12
	s_nop 0
	global_load_lds_dwordx4 v[144:145], off
	v_lshl_add_u64 v[144:145], s[10:11], 0, v[134:135]
	s_add_i32 m0, s12, 0x2000
	s_nop 0
	global_load_lds_dwordx4 v[144:145], off
	v_lshl_add_u64 v[144:145], v[200:201], 0, s[80:81]
	s_mov_b32 m0, s89
	s_nop 0
	global_load_lds_dwordx4 v[144:145], off
	v_lshl_add_u64 v[144:145], v[220:221], 0, s[80:81]
	s_mov_b32 m0, s64
	s_nop 0
	global_load_lds_dwordx4 v[144:145], off
	s_waitcnt vmcnt(8)
	s_waitcnt lgkmcnt(0)
	s_barrier
	s_waitcnt lgkmcnt(0)
	v_mfma_f32_16x16x32_bf16 v[44:47], v[140:143], v[176:179], v[44:47]
	v_mfma_f32_16x16x32_bf16 v[40:43], v[152:155], v[176:179], v[40:43]
	v_mfma_f32_16x16x32_bf16 v[28:31], v[140:143], v[184:187], v[28:31]
	v_mfma_f32_16x16x32_bf16 v[24:27], v[152:155], v[184:187], v[24:27]
	v_mfma_f32_16x16x32_bf16 v[12:15], v[140:143], v[192:195], v[12:15]
	v_mfma_f32_16x16x32_bf16 v[8:11], v[152:155], v[192:195], v[8:11]
	v_mfma_f32_16x16x32_bf16 v[108:111], v[140:143], v[210:213], v[108:111]
	v_mfma_f32_16x16x32_bf16 v[104:107], v[152:155], v[210:213], v[104:107]
	v_mfma_f32_16x16x32_bf16 v[44:47], v[148:151], v[180:183], v[44:47]
	v_mfma_f32_16x16x32_bf16 v[40:43], v[156:159], v[180:183], v[40:43]
	v_mfma_f32_16x16x32_bf16 v[28:31], v[148:151], v[188:191], v[28:31]
	v_mfma_f32_16x16x32_bf16 v[24:27], v[156:159], v[188:191], v[24:27]
	v_mfma_f32_16x16x32_bf16 v[12:15], v[148:151], v[206:209], v[12:15]
	v_mfma_f32_16x16x32_bf16 v[8:11], v[156:159], v[206:209], v[8:11]
	v_mfma_f32_16x16x32_bf16 v[108:111], v[148:151], v[214:217], v[108:111]
	v_mfma_f32_16x16x32_bf16 v[104:107], v[156:159], v[214:217], v[104:107]
	v_mfma_f32_16x16x32_bf16 v[36:39], v[160:163], v[176:179], v[36:39]
	v_mfma_f32_16x16x32_bf16 v[32:35], v[168:171], v[176:179], v[32:35]
	v_mfma_f32_16x16x32_bf16 v[20:23], v[160:163], v[184:187], v[20:23]
	v_mfma_f32_16x16x32_bf16 v[16:19], v[168:171], v[184:187], v[16:19]
	v_mfma_f32_16x16x32_bf16 v[4:7], v[160:163], v[192:195], v[4:7]
	v_mfma_f32_16x16x32_bf16 v[0:3], v[168:171], v[192:195], v[0:3]
	v_mfma_f32_16x16x32_bf16 v[100:103], v[160:163], v[210:213], v[100:103]
	v_mfma_f32_16x16x32_bf16 v[96:99], v[168:171], v[210:213], v[96:99]
	v_mfma_f32_16x16x32_bf16 v[36:39], v[164:167], v[180:183], v[36:39]
	v_mfma_f32_16x16x32_bf16 v[32:35], v[172:175], v[180:183], v[32:35]
	v_mfma_f32_16x16x32_bf16 v[20:23], v[164:167], v[188:191], v[20:23]
	v_mfma_f32_16x16x32_bf16 v[16:19], v[172:175], v[188:191], v[16:19]
	v_mfma_f32_16x16x32_bf16 v[4:7], v[164:167], v[206:209], v[4:7]
	v_mfma_f32_16x16x32_bf16 v[0:3], v[172:175], v[206:209], v[0:3]
	v_mfma_f32_16x16x32_bf16 v[100:103], v[164:167], v[214:217], v[100:103]
	v_mfma_f32_16x16x32_bf16 v[96:99], v[172:175], v[214:217], v[96:99]
	s_barrier
	s_add_i32 s38, s38, 2
	s_add_u32 s14, s14, 0x100
	s_addc_u32 s15, s15, 0
	s_add_u32 s6, s6, 0x100
	s_addc_u32 s7, s7, 0
	s_cmp_gt_u32 s38, 13
	s_cbranch_scc0 .LBB0_1390
	s_setprio 0
	s_and_b64 vcc, exec, s[2:3]
	s_cbranch_vccz .LBB0_1393
	s_barrier

; #define PG8_STAGE(bufoff, gbase, voff) do { _Pragma("unroll") for (int _i = 0; _i < 2; ++_i) \
;         __builtin_amdgcn_global_load_lds((const unsigned*)((const char*)(gbase) + (voff)[_i]), (LAS unsigned*)(lds + (bufoff) + ldsw + _i * 8192), 16, 0, 0); } while (0)
; #define PG8_LDA(dst, b, h) do { _Pragma("unroll") for (int m = 0; m < 4; ++m) _Pragma("unroll") for (int k = 0; k < 2; ++k) dst[m][k] = *(const LAS bf16x8*)(lds + PG8_SA(b, h) + aoff + m * 2048 + k * 1024); } while (0)
; #define PG8_LDB(dst, b, h) do { _Pragma("unroll") for (int n = 0; n < 2; ++n) _Pragma("unroll") for (int k = 0; k < 2; ++k) dst[n][k] = *(const LAS bf16x8*)(lds + PG8_SB(b, h) + boff + n * 2048 + k * 1024); } while (0)
; #define PG8_SCHED __builtin_amdgcn_sched_barrier(0)
; template <class Epi, class Sched>
; __device__ __forceinline__ void gemm_phase(LAS unsigned char* lds, const GemmP g, const Sched& S, const Epi& E, int tid) {
;     ...
;         for (int t = 0; t < nt; t += 2) {
;             const bool last = (t == nt - 2);
;             const char* a1 = cA + (size_t)(t + 1) * kstep;
;             const char* a2 = last ? nA : cA + (size_t)(t + 2) * kstep; const char* b2 = last ? nB : cB + (size_t)(t + 2) * kstep;
;             const char* a3 = a2 + kstep; const char* b3 = b2 + kstep;
;             PG8_LDB(B0, 0, 0); PG8_LDB(B1, 0, 1); PG8_SCHED; PG8_LDA(At, 0, 0); PG8_STAGE(PG8_SA(1, 1), a1 + hstepA, voffA);
;     ...
; #pragma unroll
;         for (int a = 0; a < 2; ++a)
; #pragma unroll
;             for (int b = 0; b < 2; ++b)
; #pragma unroll
;                 for (int m = 0; m < 4; ++m)
; #pragma unroll
;                     for (int n = 0; n < 2; ++n) acc[a][b][m][n] = (f32x4){0.f, 0.f, 0.f, 0.f};
;         cur = nxt; cA = nA; cB = nB; ++ui;
.LBB0_1533:
	s_add_u32 s16, s8, 0x100
	v_mov_b32_e32 v0, 0
	s_addc_u32 s17, s9, 0
	s_mov_b32 s18, -2
	v_mov_b32_e32 v1, v0
	v_mov_b32_e32 v2, v0
	s_waitcnt lgkmcnt(0)
	v_mov_b32_e32 v3, v0
	v_mov_b32_e32 v4, v0
	v_mov_b32_e32 v5, v0
	v_mov_b32_e32 v6, v0
	v_mov_b32_e32 v7, v0
	v_mov_b32_e32 v8, v0
	v_mov_b32_e32 v9, v0
	v_mov_b32_e32 v10, v0
	v_mov_b32_e32 v11, v0
	v_mov_b32_e32 v12, v0
	v_mov_b32_e32 v13, v0
	v_mov_b32_e32 v14, v0
	v_mov_b32_e32 v15, v0
	v_mov_b32_e32 v16, v0
	v_mov_b32_e32 v17, v0
	v_mov_b32_e32 v18, v0
	v_mov_b32_e32 v19, v0
	v_mov_b32_e32 v20, v0
	v_mov_b32_e32 v21, v0
	v_mov_b32_e32 v22, v0
	v_mov_b32_e32 v23, v0
	v_mov_b32_e32 v24, v0
	v_mov_b32_e32 v25, v0
	v_mov_b32_e32 v26, v0
	v_mov_b32_e32 v27, v0
	v_mov_b32_e32 v28, v0
	v_mov_b32_e32 v29, v0
	v_mov_b32_e32 v30, v0
	v_mov_b32_e32 v31, v0
	v_mov_b32_e32 v56, v0
	v_mov_b32_e32 v57, v0
	v_mov_b32_e32 v58, v0
	v_mov_b32_e32 v59, v0
	v_mov_b32_e32 v64, v0
	v_mov_b32_e32 v65, v0
	v_mov_b32_e32 v66, v0
	v_mov_b32_e32 v67, v0
	v_mov_b32_e32 v72, v0
	v_mov_b32_e32 v73, v0
	v_mov_b32_e32 v74, v0
	v_mov_b32_e32 v75, v0
	v_mov_b32_e32 v76, v0
	v_mov_b32_e32 v77, v0
	v_mov_b32_e32 v78, v0
	v_mov_b32_e32 v79, v0
	v_mov_b32_e32 v80, v0
	v_mov_b32_e32 v81, v0
	v_mov_b32_e32 v82, v0
	v_mov_b32_e32 v83, v0
	v_mov_b32_e32 v84, v0
	v_mov_b32_e32 v85, v0
	v_mov_b32_e32 v86, v0
	v_mov_b32_e32 v87, v0
	v_mov_b32_e32 v88, v0
	v_mov_b32_e32 v89, v0
	v_mov_b32_e32 v90, v0
	v_mov_b32_e32 v91, v0
	v_mov_b32_e32 v92, v0
	v_mov_b32_e32 v93, v0
	v_mov_b32_e32 v94, v0
	v_mov_b32_e32 v95, v0
	v_mov_b32_e32 v32, v0
	v_mov_b32_e32 v33, v0
	v_mov_b32_e32 v34, v0
	v_mov_b32_e32 v35, v0
	v_mov_b32_e32 v36, v0
	v_mov_b32_e32 v37, v0
	v_mov_b32_e32 v38, v0
	v_mov_b32_e32 v39, v0
	v_mov_b32_e32 v40, v0
	v_mov_b32_e32 v41, v0
	v_mov_b32_e32 v42, v0
	v_mov_b32_e32 v43, v0
	v_mov_b32_e32 v44, v0
	v_mov_b32_e32 v45, v0
	v_mov_b32_e32 v46, v0
	v_mov_b32_e32 v47, v0
	v_mov_b32_e32 v48, v0
	v_mov_b32_e32 v49, v0
	v_mov_b32_e32 v50, v0
	v_mov_b32_e32 v51, v0
	v_mov_b32_e32 v52, v0
	v_mov_b32_e32 v53, v0
	v_mov_b32_e32 v54, v0
	v_mov_b32_e32 v55, v0
	v_mov_b32_e32 v60, v0
	v_mov_b32_e32 v61, v0
	v_mov_b32_e32 v62, v0
	v_mov_b32_e32 v63, v0
	v_mov_b32_e32 v68, v0
	v_mov_b32_e32 v69, v0
	v_mov_b32_e32 v70, v0
	v_mov_b32_e32 v71, v0
	v_mov_b32_e32 v96, v0
	v_mov_b32_e32 v97, v0
	v_mov_b32_e32 v98, v0
	v_mov_b32_e32 v99, v0
	v_mov_b32_e32 v100, v0
	v_mov_b32_e32 v101, v0
	v_mov_b32_e32 v102, v0
	v_mov_b32_e32 v103, v0
	v_mov_b32_e32 v104, v0
	v_mov_b32_e32 v105, v0
	v_mov_b32_e32 v106, v0
	v_mov_b32_e32 v107, v0
	v_mov_b32_e32 v108, v0
	v_mov_b32_e32 v109, v0
	v_mov_b32_e32 v110, v0
	v_mov_b32_e32 v111, v0
	v_mov_b32_e32 v112, v0
	v_mov_b32_e32 v113, v0
	v_mov_b32_e32 v114, v0
	v_mov_b32_e32 v115, v0
	v_mov_b32_e32 v116, v0
	v_mov_b32_e32 v117, v0
	v_mov_b32_e32 v118, v0
	v_mov_b32_e32 v119, v0
	v_mov_b32_e32 v120, v0
	v_mov_b32_e32 v121, v0
	v_mov_b32_e32 v122, v0
	v_mov_b32_e32 v123, v0
	v_mov_b32_e32 v124, v0
	v_mov_b32_e32 v125, v0
	v_mov_b32_e32 v126, v0
	v_mov_b32_e32 v127, v0
	s_cmp_lg_u64 s[86:87], 0
	s_cbranch_scc1 .Lsp_1534
	s_setprio 1
.Lsp_1534:
.LBB0_1534:
	s_add_u32 s8, s6, 0x100
	s_addc_u32 s9, s7, 0
	s_add_i32 s19, 0, 0x10000
	s_cmp_eq_u32 s18, 40
	s_cselect_b32 s13, s93, s9
	s_cselect_b32 s12, s92, s8
	s_cselect_b32 s11, s95, s17
	s_cselect_b32 s10, s94, s16
	s_add_i32 s20, 0, 0x14000
	v_add_u32_e32 v140, s19, v212
	v_add_u32_e32 v156, s20, v212
	ds_read_b128 v[128:131], v140
	ds_read_b128 v[132:135], v140 offset:1024
	ds_read_b128 v[136:139], v140 offset:2048
	ds_read_b128 v[140:143], v140 offset:3072
	ds_read_b128 v[144:147], v156
	ds_read_b128 v[148:151], v156 offset:1024
	ds_read_b128 v[152:155], v156 offset:2048
	ds_read_b128 v[156:159], v156 offset:3072
	v_lshl_add_u64 v[198:199], s[6:7], 0, v[206:207]
	s_add_i32 m0, s63, 0xc000
	ds_read_b128 v[160:163], v213
	ds_read_b128 v[164:167], v213 offset:1024
	ds_read_b128 v[168:171], v213 offset:2048
	ds_read_b128 v[172:175], v213 offset:3072
	ds_read_b128 v[176:179], v213 offset:4096
	ds_read_b128 v[180:183], v213 offset:5120
	ds_read_b128 v[184:187], v213 offset:6144
	ds_read_b128 v[208:211], v213 offset:7168
	global_load_lds_dwordx4 v[198:199], off
	v_lshl_add_u64 v[198:199], s[6:7], 0, v[194:195]
	s_add_i32 m0, s63, 0xe000
	s_nop 0
	global_load_lds_dwordx4 v[198:199], off
	s_cmp_eq_u32 s18, -2
	s_cbranch_scc1 .Lfirstit_6
	s_waitcnt vmcnt(8)
; #define PG8_STAGE(bufoff, gbase, voff) do { _Pragma("unroll") for (int _i = 0; _i < 2; ++_i) \
;         __builtin_amdgcn_global_load_lds((const unsigned*)((const char*)(gbase) + (voff)[_i]), (LAS unsigned*)(lds + (bufoff) + ldsw + _i * 8192), 16, 0, 0); } while (0)
; #define PG8_LDA(dst, b, h) do { _Pragma("unroll") for (int m = 0; m < 4; ++m) _Pragma("unroll") for (int k = 0; k < 2; ++k) dst[m][k] = *(const LAS bf16x8*)(lds + PG8_SA(b, h) + aoff + m * 2048 + k * 1024); } while (0)
; #define PG8_MMA(ai, bj, At, Bt) do { __builtin_amdgcn_s_setprio(1); _Pragma("unroll") for (int m = 0; m < 4; ++m) _Pragma("unroll") for (int n = 0; n < 2; ++n) _Pragma("unroll") for (int k = 0; k < 2; ++k) \
;         acc[ai][bj][m][n] = __builtin_amdgcn_mfma_f32_16x16x32_bf16(Bt[n][k], At[m][k], acc[ai][bj][m][n], 0, 0, 0); __builtin_amdgcn_s_setprio(0); } while (0)
; #define PG8_WAIT_V(n) asm volatile("s_waitcnt vmcnt(" #n ")" ::: "memory")
; #define PG8_WAIT_L(n) asm volatile("s_waitcnt lgkmcnt(" #n ")" ::: "memory")
; #define PG8_BAR __builtin_amdgcn_s_barrier()
; #define PG8_SCHED __builtin_amdgcn_sched_barrier(0)
; template <class Epi, class Sched>
; __device__ __forceinline__ void gemm_phase(LAS unsigned char* lds, const GemmP g, const Sched& S, const Epi& E, int tid) {
;     ...
;             PG8_WAIT_V(8); PG8_WAIT_L(0); PG8_BAR; PG8_MMA(0, 0, At, B0); PG8_MMA(0, 1, At, B1); PG8_BAR; PG8_SCHED;
;             PG8_LDA(At, 0, 1); PG8_STAGE(PG8_SB(0, 0), b2, voffB); PG8_STAGE(PG8_SB(0, 1), b2 + hstepB, voffB); PG8_STAGE(PG8_SA(0, 0), a2, voffA);
;             PG8_WAIT_V(8); PG8_WAIT_L(0); PG8_BAR; PG8_MMA(1, 0, At, B0); PG8_MMA(1, 1, At, B1); PG8_BAR; PG8_SCHED;
.Lfirstit_6:
	s_waitcnt lgkmcnt(0)
	s_barrier
	s_waitcnt lgkmcnt(0)
	v_mfma_f32_16x16x32_bf16 v[124:127], v[128:131], v[160:163], v[124:127]
	v_mfma_f32_16x16x32_bf16 v[120:123], v[136:139], v[160:163], v[120:123]
	v_mfma_f32_16x16x32_bf16 v[116:119], v[128:131], v[168:171], v[116:119]
	v_mfma_f32_16x16x32_bf16 v[112:115], v[136:139], v[168:171], v[112:115]
	v_mfma_f32_16x16x32_bf16 v[108:111], v[128:131], v[176:179], v[108:111]
	v_mfma_f32_16x16x32_bf16 v[104:107], v[136:139], v[176:179], v[104:107]
	v_mfma_f32_16x16x32_bf16 v[100:103], v[128:131], v[184:187], v[100:103]
	v_mfma_f32_16x16x32_bf16 v[96:99], v[136:139], v[184:187], v[96:99]
	v_mfma_f32_16x16x32_bf16 v[124:127], v[132:135], v[164:167], v[124:127]
	v_mfma_f32_16x16x32_bf16 v[120:123], v[140:143], v[164:167], v[120:123]
	v_mfma_f32_16x16x32_bf16 v[116:119], v[132:135], v[172:175], v[116:119]
	v_mfma_f32_16x16x32_bf16 v[112:115], v[140:143], v[172:175], v[112:115]
	v_mfma_f32_16x16x32_bf16 v[108:111], v[132:135], v[180:183], v[108:111]
	v_mfma_f32_16x16x32_bf16 v[104:107], v[140:143], v[180:183], v[104:107]
	v_mfma_f32_16x16x32_bf16 v[100:103], v[132:135], v[208:211], v[100:103]
	v_mfma_f32_16x16x32_bf16 v[96:99], v[140:143], v[208:211], v[96:99]
	v_mfma_f32_16x16x32_bf16 v[68:71], v[144:147], v[160:163], v[68:71]
	v_mfma_f32_16x16x32_bf16 v[60:63], v[152:155], v[160:163], v[60:63]
	v_mfma_f32_16x16x32_bf16 v[52:55], v[144:147], v[168:171], v[52:55]
	v_mfma_f32_16x16x32_bf16 v[48:51], v[152:155], v[168:171], v[48:51]
	v_mfma_f32_16x16x32_bf16 v[44:47], v[144:147], v[176:179], v[44:47]
	v_mfma_f32_16x16x32_bf16 v[40:43], v[152:155], v[176:179], v[40:43]
	v_mfma_f32_16x16x32_bf16 v[36:39], v[144:147], v[184:187], v[36:39]
	v_mfma_f32_16x16x32_bf16 v[32:35], v[152:155], v[184:187], v[32:35]
	v_mfma_f32_16x16x32_bf16 v[68:71], v[148:151], v[164:167], v[68:71]
	v_mfma_f32_16x16x32_bf16 v[60:63], v[156:159], v[164:167], v[60:63]
	v_mfma_f32_16x16x32_bf16 v[52:55], v[148:151], v[172:175], v[52:55]
	v_mfma_f32_16x16x32_bf16 v[48:51], v[156:159], v[172:175], v[48:51]
	v_mfma_f32_16x16x32_bf16 v[44:47], v[148:151], v[180:183], v[44:47]
	v_mfma_f32_16x16x32_bf16 v[40:43], v[156:159], v[180:183], v[40:43]
	v_mfma_f32_16x16x32_bf16 v[36:39], v[148:151], v[208:211], v[36:39]
	v_mfma_f32_16x16x32_bf16 v[32:35], v[156:159], v[208:211], v[32:35]
	s_barrier
	s_add_i32 s6, s19, s62
	v_lshl_add_u64 v[198:199], s[10:11], 0, v[196:197]
	s_mov_b32 m0, s6
	ds_read_b128 v[160:163], v213 offset:16384
	ds_read_b128 v[164:167], v213 offset:17408
	ds_read_b128 v[168:171], v213 offset:18432
	ds_read_b128 v[172:175], v213 offset:19456
	ds_read_b128 v[176:179], v213 offset:20480
	ds_read_b128 v[180:183], v213 offset:21504
	ds_read_b128 v[184:187], v213 offset:22528
	ds_read_b128 v[208:211], v213 offset:23552
	global_load_lds_dwordx4 v[198:199], off
	s_add_i32 m0, s6, 0x2000
	s_add_u32 s6, s10, 0xb0000
	v_lshl_add_u64 v[200:201], s[10:11], 0, v[192:193]
	s_addc_u32 s7, s11, 0
	s_add_i32 s19, s20, s62
	global_load_lds_dwordx4 v[200:201], off
	v_lshl_add_u64 v[214:215], s[6:7], 0, v[196:197]
	s_mov_b32 m0, s19
	v_lshl_add_u64 v[216:217], s[12:13], 0, v[190:191]
	global_load_lds_dwordx4 v[214:215], off
	v_lshl_add_u64 v[214:215], s[6:7], 0, v[192:193]
	s_add_i32 m0, s19, 0x2000
	s_nop 0
	global_load_lds_dwordx4 v[214:215], off
	v_lshl_add_u64 v[214:215], s[12:13], 0, v[188:189]
	s_mov_b32 m0, s63
	s_nop 0
	global_load_lds_dwordx4 v[214:215], off
	s_mov_b32 m0, s82
	s_nop 0
	global_load_lds_dwordx4 v[216:217], off
	s_waitcnt vmcnt(8)
	s_waitcnt lgkmcnt(0)
	s_barrier
	s_waitcnt lgkmcnt(0)
	v_mfma_f32_16x16x32_bf16 v[92:95], v[128:131], v[160:163], v[92:95]
	v_mfma_f32_16x16x32_bf16 v[88:91], v[136:139], v[160:163], v[88:91]
	v_mfma_f32_16x16x32_bf16 v[84:87], v[128:131], v[168:171], v[84:87]
	v_mfma_f32_16x16x32_bf16 v[80:83], v[136:139], v[168:171], v[80:83]
	v_mfma_f32_16x16x32_bf16 v[76:79], v[128:131], v[176:179], v[76:79]
	v_mfma_f32_16x16x32_bf16 v[72:75], v[136:139], v[176:179], v[72:75]
	v_mfma_f32_16x16x32_bf16 v[64:67], v[128:131], v[184:187], v[64:67]
	v_mfma_f32_16x16x32_bf16 v[56:59], v[136:139], v[184:187], v[56:59]
	v_mfma_f32_16x16x32_bf16 v[92:95], v[132:135], v[164:167], v[92:95]
	v_mfma_f32_16x16x32_bf16 v[88:91], v[140:143], v[164:167], v[88:91]
	v_mfma_f32_16x16x32_bf16 v[84:87], v[132:135], v[172:175], v[84:87]
	v_mfma_f32_16x16x32_bf16 v[80:83], v[140:143], v[172:175], v[80:83]
	v_mfma_f32_16x16x32_bf16 v[76:79], v[132:135], v[180:183], v[76:79]
	v_mfma_f32_16x16x32_bf16 v[72:75], v[140:143], v[180:183], v[72:75]
	v_mfma_f32_16x16x32_bf16 v[64:67], v[132:135], v[208:211], v[64:67]
	v_mfma_f32_16x16x32_bf16 v[56:59], v[140:143], v[208:211], v[56:59]
	v_mfma_f32_16x16x32_bf16 v[28:31], v[144:147], v[160:163], v[28:31]
	v_mfma_f32_16x16x32_bf16 v[24:27], v[152:155], v[160:163], v[24:27]
	v_mfma_f32_16x16x32_bf16 v[20:23], v[144:147], v[168:171], v[20:23]
	v_mfma_f32_16x16x32_bf16 v[16:19], v[152:155], v[168:171], v[16:19]
	v_mfma_f32_16x16x32_bf16 v[12:15], v[144:147], v[176:179], v[12:15]
	v_mfma_f32_16x16x32_bf16 v[8:11], v[152:155], v[176:179], v[8:11]
	v_mfma_f32_16x16x32_bf16 v[4:7], v[144:147], v[184:187], v[4:7]
	v_mfma_f32_16x16x32_bf16 v[0:3], v[152:155], v[184:187], v[0:3]
	v_mfma_f32_16x16x32_bf16 v[28:31], v[148:151], v[164:167], v[28:31]
	v_mfma_f32_16x16x32_bf16 v[24:27], v[156:159], v[164:167], v[24:27]
	v_mfma_f32_16x16x32_bf16 v[20:23], v[148:151], v[172:175], v[20:23]
	v_mfma_f32_16x16x32_bf16 v[16:19], v[156:159], v[172:175], v[16:19]
	v_mfma_f32_16x16x32_bf16 v[12:15], v[148:151], v[180:183], v[12:15]
	v_mfma_f32_16x16x32_bf16 v[8:11], v[156:159], v[180:183], v[8:11]
	v_mfma_f32_16x16x32_bf16 v[4:7], v[148:151], v[208:211], v[4:7]
	v_mfma_f32_16x16x32_bf16 v[0:3], v[156:159], v[208:211], v[0:3]
	s_barrier
; #define PG8_STAGE(bufoff, gbase, voff) do { _Pragma("unroll") for (int _i = 0; _i < 2; ++_i) \
;         __builtin_amdgcn_global_load_lds((const unsigned*)((const char*)(gbase) + (voff)[_i]), (LAS unsigned*)(lds + (bufoff) + ldsw + _i * 8192), 16, 0, 0); } while (0)
; #define PG8_LDA(dst, b, h) do { _Pragma("unroll") for (int m = 0; m < 4; ++m) _Pragma("unroll") for (int k = 0; k < 2; ++k) dst[m][k] = *(const LAS bf16x8*)(lds + PG8_SA(b, h) + aoff + m * 2048 + k * 1024); } while (0)
; #define PG8_LDB(dst, b, h) do { _Pragma("unroll") for (int n = 0; n < 2; ++n) _Pragma("unroll") for (int k = 0; k < 2; ++k) dst[n][k] = *(const LAS bf16x8*)(lds + PG8_SB(b, h) + boff + n * 2048 + k * 1024); } while (0)
; #define PG8_MMA(ai, bj, At, Bt) do { __builtin_amdgcn_s_setprio(1); _Pragma("unroll") for (int m = 0; m < 4; ++m) _Pragma("unroll") for (int n = 0; n < 2; ++n) _Pragma("unroll") for (int k = 0; k < 2; ++k) \
;         acc[ai][bj][m][n] = __builtin_amdgcn_mfma_f32_16x16x32_bf16(Bt[n][k], At[m][k], acc[ai][bj][m][n], 0, 0, 0); __builtin_amdgcn_s_setprio(0); } while (0)
; #define PG8_WAIT_V(n) asm volatile("s_waitcnt vmcnt(" #n ")" ::: "memory")
; #define PG8_WAIT_L(n) asm volatile("s_waitcnt lgkmcnt(" #n ")" ::: "memory")
; #define PG8_BAR __builtin_amdgcn_s_barrier()
; #define PG8_SCHED __builtin_amdgcn_sched_barrier(0)
; template <class Epi, class Sched>
; __device__ __forceinline__ void gemm_phase(LAS unsigned char* lds, const GemmP g, const Sched& S, const Epi& E, int tid) {
;     ...
;             PG8_LDB(B0, 1, 0); PG8_LDB(B1, 1, 1); PG8_SCHED; PG8_LDA(At, 1, 0); PG8_STAGE(PG8_SA(0, 1), a2 + hstepA, voffA);
;             PG8_WAIT_V(8); PG8_WAIT_L(0); PG8_BAR; PG8_MMA(0, 0, At, B0); PG8_MMA(0, 1, At, B1); PG8_BAR; PG8_SCHED;
	s_add_i32 s19, 0, 0x18000
	s_add_i32 s20, 0, 0x1c000
	v_add_u32_e32 v140, s19, v212
	v_add_u32_e32 v156, s20, v212
	ds_read_b128 v[128:131], v140
	ds_read_b128 v[132:135], v140 offset:1024
	ds_read_b128 v[136:139], v140 offset:2048
	ds_read_b128 v[140:143], v140 offset:3072
	ds_read_b128 v[144:147], v156
	ds_read_b128 v[148:151], v156 offset:1024
	ds_read_b128 v[152:155], v156 offset:2048
	ds_read_b128 v[156:159], v156 offset:3072
	s_add_u32 s6, s12, 0xb0000
	s_addc_u32 s7, s13, 0
	s_mov_b32 m0, s56
	v_lshl_add_u64 v[220:221], s[6:7], 0, v[188:189]
	ds_read_b128 v[160:163], v213 offset:32768
	ds_read_b128 v[164:167], v213 offset:33792
	ds_read_b128 v[168:171], v213 offset:34816
	ds_read_b128 v[172:175], v213 offset:35840
	ds_read_b128 v[176:179], v213 offset:36864
	ds_read_b128 v[180:183], v213 offset:37888
	ds_read_b128 v[184:187], v213 offset:38912
	ds_read_b128 v[208:211], v213 offset:39936
	global_load_lds_dwordx4 v[220:221], off
	v_lshl_add_u64 v[220:221], s[6:7], 0, v[190:191]
	s_mov_b32 m0, s57
	s_nop 0
	global_load_lds_dwordx4 v[220:221], off
	s_waitcnt vmcnt(8)
	s_waitcnt lgkmcnt(0)
	s_barrier
	s_waitcnt lgkmcnt(0)
	v_mfma_f32_16x16x32_bf16 v[124:127], v[128:131], v[160:163], v[124:127]
	v_mfma_f32_16x16x32_bf16 v[120:123], v[136:139], v[160:163], v[120:123]
	v_mfma_f32_16x16x32_bf16 v[116:119], v[128:131], v[168:171], v[116:119]
	v_mfma_f32_16x16x32_bf16 v[112:115], v[136:139], v[168:171], v[112:115]
	v_mfma_f32_16x16x32_bf16 v[108:111], v[128:131], v[176:179], v[108:111]
	v_mfma_f32_16x16x32_bf16 v[104:107], v[136:139], v[176:179], v[104:107]
	v_mfma_f32_16x16x32_bf16 v[100:103], v[128:131], v[184:187], v[100:103]
	v_mfma_f32_16x16x32_bf16 v[96:99], v[136:139], v[184:187], v[96:99]
	v_mfma_f32_16x16x32_bf16 v[124:127], v[132:135], v[164:167], v[124:127]
	v_mfma_f32_16x16x32_bf16 v[120:123], v[140:143], v[164:167], v[120:123]
	v_mfma_f32_16x16x32_bf16 v[116:119], v[132:135], v[172:175], v[116:119]
	v_mfma_f32_16x16x32_bf16 v[112:115], v[140:143], v[172:175], v[112:115]
	v_mfma_f32_16x16x32_bf16 v[108:111], v[132:135], v[180:183], v[108:111]
	v_mfma_f32_16x16x32_bf16 v[104:107], v[140:143], v[180:183], v[104:107]
	v_mfma_f32_16x16x32_bf16 v[100:103], v[132:135], v[208:211], v[100:103]
	v_mfma_f32_16x16x32_bf16 v[96:99], v[140:143], v[208:211], v[96:99]
	v_mfma_f32_16x16x32_bf16 v[68:71], v[144:147], v[160:163], v[68:71]
	v_mfma_f32_16x16x32_bf16 v[60:63], v[152:155], v[160:163], v[60:63]
	v_mfma_f32_16x16x32_bf16 v[52:55], v[144:147], v[168:171], v[52:55]
	v_mfma_f32_16x16x32_bf16 v[48:51], v[152:155], v[168:171], v[48:51]
	v_mfma_f32_16x16x32_bf16 v[44:47], v[144:147], v[176:179], v[44:47]
	v_mfma_f32_16x16x32_bf16 v[40:43], v[152:155], v[176:179], v[40:43]
	v_mfma_f32_16x16x32_bf16 v[36:39], v[144:147], v[184:187], v[36:39]
	v_mfma_f32_16x16x32_bf16 v[32:35], v[152:155], v[184:187], v[32:35]
	v_mfma_f32_16x16x32_bf16 v[68:71], v[148:151], v[164:167], v[68:71]
	v_mfma_f32_16x16x32_bf16 v[60:63], v[156:159], v[164:167], v[60:63]
	v_mfma_f32_16x16x32_bf16 v[52:55], v[148:151], v[172:175], v[52:55]
	v_mfma_f32_16x16x32_bf16 v[48:51], v[156:159], v[172:175], v[48:51]
	v_mfma_f32_16x16x32_bf16 v[44:47], v[148:151], v[180:183], v[44:47]
	v_mfma_f32_16x16x32_bf16 v[40:43], v[156:159], v[180:183], v[40:43]
	v_mfma_f32_16x16x32_bf16 v[36:39], v[148:151], v[208:211], v[36:39]
	v_mfma_f32_16x16x32_bf16 v[32:35], v[156:159], v[208:211], v[32:35]
	s_barrier
; #define PG8_STAGE(bufoff, gbase, voff) do { _Pragma("unroll") for (int _i = 0; _i < 2; ++_i) \
;         __builtin_amdgcn_global_load_lds((const unsigned*)((const char*)(gbase) + (voff)[_i]), (LAS unsigned*)(lds + (bufoff) + ldsw + _i * 8192), 16, 0, 0); } while (0)
; #define PG8_LDA(dst, b, h) do { _Pragma("unroll") for (int m = 0; m < 4; ++m) _Pragma("unroll") for (int k = 0; k < 2; ++k) dst[m][k] = *(const LAS bf16x8*)(lds + PG8_SA(b, h) + aoff + m * 2048 + k * 1024); } while (0)
; #define PG8_MMA(ai, bj, At, Bt) do { __builtin_amdgcn_s_setprio(1); _Pragma("unroll") for (int m = 0; m < 4; ++m) _Pragma("unroll") for (int n = 0; n < 2; ++n) _Pragma("unroll") for (int k = 0; k < 2; ++k) \
;         acc[ai][bj][m][n] = __builtin_amdgcn_mfma_f32_16x16x32_bf16(Bt[n][k], At[m][k], acc[ai][bj][m][n], 0, 0, 0); __builtin_amdgcn_s_setprio(0); } while (0)
; #define PG8_WAIT_V(n) asm volatile("s_waitcnt vmcnt(" #n ")" ::: "memory")
; #define PG8_WAIT_L(n) asm volatile("s_waitcnt lgkmcnt(" #n ")" ::: "memory")
; #define PG8_BAR __builtin_amdgcn_s_barrier()
; #define PG8_SCHED __builtin_amdgcn_sched_barrier(0)
; template <class Epi, class Sched>
; __device__ __forceinline__ void gemm_phase(LAS unsigned char* lds, const GemmP g, const Sched& S, const Epi& E, int tid) {
;     ...
;             PG8_LDA(At, 1, 1); PG8_STAGE(PG8_SB(1, 0), b3, voffB); PG8_STAGE(PG8_SB(1, 1), b3 + hstepB, voffB); PG8_STAGE(PG8_SA(1, 0), a3, voffA);
;             PG8_WAIT_V(8); PG8_WAIT_L(0); PG8_BAR; PG8_MMA(1, 0, At, B0); PG8_MMA(1, 1, At, B1); PG8_BAR; PG8_SCHED;
;         }
;         if (wr == 0) PG8_BAR;
	s_add_i32 s6, s19, s62
	v_lshl_add_u64 v[198:199], v[198:199], 0, s[80:81]
	s_mov_b32 m0, s6
	ds_read_b128 v[160:163], v213 offset:49152
	ds_read_b128 v[164:167], v213 offset:50176
	ds_read_b128 v[168:171], v213 offset:51200
	ds_read_b128 v[172:175], v213 offset:52224
	ds_read_b128 v[176:179], v213 offset:53248
	ds_read_b128 v[180:183], v213 offset:54272
	ds_read_b128 v[184:187], v213 offset:55296
	ds_read_b128 v[208:211], v213 offset:56320
	global_load_lds_dwordx4 v[198:199], off
	s_add_i32 m0, s6, 0x2000
	s_add_u32 s6, s10, 0xb0080
	v_lshl_add_u64 v[198:199], v[200:201], 0, s[80:81]
	s_addc_u32 s7, s11, 0
	s_add_i32 s10, s20, s62
	global_load_lds_dwordx4 v[198:199], off
	v_lshl_add_u64 v[198:199], s[6:7], 0, v[196:197]
	s_mov_b32 m0, s10
	s_nop 0
	global_load_lds_dwordx4 v[198:199], off
	v_lshl_add_u64 v[198:199], s[6:7], 0, v[192:193]
	s_add_i32 m0, s10, 0x2000
	s_nop 0
	global_load_lds_dwordx4 v[198:199], off
	v_lshl_add_u64 v[198:199], v[214:215], 0, s[80:81]
	s_mov_b32 m0, s3
	s_nop 0
	global_load_lds_dwordx4 v[198:199], off
	v_lshl_add_u64 v[198:199], v[216:217], 0, s[80:81]
	s_mov_b32 m0, s44
	s_nop 0
	global_load_lds_dwordx4 v[198:199], off
	s_waitcnt vmcnt(8)
	s_waitcnt lgkmcnt(0)
	s_barrier
	s_waitcnt lgkmcnt(0)
	v_mfma_f32_16x16x32_bf16 v[92:95], v[128:131], v[160:163], v[92:95]
	v_mfma_f32_16x16x32_bf16 v[88:91], v[136:139], v[160:163], v[88:91]
	v_mfma_f32_16x16x32_bf16 v[84:87], v[128:131], v[168:171], v[84:87]
	v_mfma_f32_16x16x32_bf16 v[80:83], v[136:139], v[168:171], v[80:83]
	v_mfma_f32_16x16x32_bf16 v[76:79], v[128:131], v[176:179], v[76:79]
	v_mfma_f32_16x16x32_bf16 v[72:75], v[136:139], v[176:179], v[72:75]
	v_mfma_f32_16x16x32_bf16 v[64:67], v[128:131], v[184:187], v[64:67]
	v_mfma_f32_16x16x32_bf16 v[56:59], v[136:139], v[184:187], v[56:59]
	v_mfma_f32_16x16x32_bf16 v[92:95], v[132:135], v[164:167], v[92:95]
	v_mfma_f32_16x16x32_bf16 v[88:91], v[140:143], v[164:167], v[88:91]
	v_mfma_f32_16x16x32_bf16 v[84:87], v[132:135], v[172:175], v[84:87]
	v_mfma_f32_16x16x32_bf16 v[80:83], v[140:143], v[172:175], v[80:83]
	v_mfma_f32_16x16x32_bf16 v[76:79], v[132:135], v[180:183], v[76:79]
	v_mfma_f32_16x16x32_bf16 v[72:75], v[140:143], v[180:183], v[72:75]
	v_mfma_f32_16x16x32_bf16 v[64:67], v[132:135], v[208:211], v[64:67]
	v_mfma_f32_16x16x32_bf16 v[56:59], v[140:143], v[208:211], v[56:59]
	v_mfma_f32_16x16x32_bf16 v[28:31], v[144:147], v[160:163], v[28:31]
	v_mfma_f32_16x16x32_bf16 v[24:27], v[152:155], v[160:163], v[24:27]
	v_mfma_f32_16x16x32_bf16 v[20:23], v[144:147], v[168:171], v[20:23]
	v_mfma_f32_16x16x32_bf16 v[16:19], v[152:155], v[168:171], v[16:19]
	v_mfma_f32_16x16x32_bf16 v[12:15], v[144:147], v[176:179], v[12:15]
	v_mfma_f32_16x16x32_bf16 v[8:11], v[152:155], v[176:179], v[8:11]
	v_mfma_f32_16x16x32_bf16 v[4:7], v[144:147], v[184:187], v[4:7]
	v_mfma_f32_16x16x32_bf16 v[0:3], v[152:155], v[184:187], v[0:3]
	v_mfma_f32_16x16x32_bf16 v[28:31], v[148:151], v[164:167], v[28:31]
	v_mfma_f32_16x16x32_bf16 v[24:27], v[156:159], v[164:167], v[24:27]
	v_mfma_f32_16x16x32_bf16 v[20:23], v[148:151], v[172:175], v[20:23]
	v_mfma_f32_16x16x32_bf16 v[16:19], v[156:159], v[172:175], v[16:19]
	v_mfma_f32_16x16x32_bf16 v[12:15], v[148:151], v[180:183], v[12:15]
	v_mfma_f32_16x16x32_bf16 v[8:11], v[156:159], v[180:183], v[8:11]
	v_mfma_f32_16x16x32_bf16 v[4:7], v[148:151], v[208:211], v[4:7]
	v_mfma_f32_16x16x32_bf16 v[0:3], v[156:159], v[208:211], v[0:3]
	s_barrier
	s_add_i32 s18, s18, 2
	s_add_u32 s16, s16, 0x100
	s_addc_u32 s17, s17, 0
	s_cmp_gt_u32 s18, 41
	s_mov_b64 s[6:7], s[8:9]
	s_cbranch_scc0 .LBB0_1534
	s_setprio 0
	s_and_b64 vcc, exec, s[86:87]
	s_cbranch_vccz .LBB0_1537
	s_barrier
